# rwkv_combine: staging loop made straight-line with all 64 loads in flight; epilogue's 64 per-token u loads hoisted (was ~120 serialized round trips per item); plus LRU weight prefetch
# speedup vs baseline: 1.0733x; 1.0525x over previous
.LBB0_521:
	s_xor_b64 s[8:9], s[0:1], -1
	v_lshl_add_u32 v87, s10, 7, v17
	s_mov_b64 s[0:1], 0
	v_mov_b32_e32 v28, v85
	v_mov_b32_e32 v29, v85
	v_mov_b32_e32 v32, v85
	v_mov_b32_e32 v33, v85
	v_mov_b32_e32 v36, v85
	v_mov_b32_e32 v37, v85
	v_mov_b32_e32 v40, v85
	v_mov_b32_e32 v41, v85
	v_mov_b32_e32 v44, v85
	v_mov_b32_e32 v45, v85
	v_mov_b32_e32 v48, v85
	v_mov_b32_e32 v49, v85
	v_mov_b32_e32 v52, v85
	v_mov_b32_e32 v53, v85
	v_mov_b32_e32 v56, v85
	v_mov_b32_e32 v57, v85
	v_mov_b32_e32 v60, v85
	v_mov_b32_e32 v61, v85
	v_mov_b32_e32 v64, v85
	v_mov_b32_e32 v65, v85
	v_mov_b32_e32 v68, v85
	v_mov_b32_e32 v69, v85
	v_mov_b32_e32 v10, v85
	v_mov_b32_e32 v11, v85
	v_mov_b32_e32 v14, v85
	v_mov_b32_e32 v15, v85
	v_mov_b32_e32 v74, v85
	v_mov_b32_e32 v75, v85
	v_mov_b32_e32 v80, v85
	v_mov_b32_e32 v81, v85
	v_mov_b32_e32 v0, v85
	v_mov_b32_e32 v1, v85
	s_waitcnt vmcnt(0)
	v_mov_b32_e32 v82, v84
	v_mov_b32_e32 v83, v84
	v_mov_b32_e32 v78, v84
	v_mov_b32_e32 v79, v84
	v_mov_b32_e32 v76, v84
	v_mov_b32_e32 v77, v84
	v_mov_b32_e32 v72, v84
	v_mov_b32_e32 v73, v84
	v_mov_b32_e32 v12, v84
	v_mov_b32_e32 v13, v84
	v_mov_b32_e32 v70, v84
	v_mov_b32_e32 v71, v84
	v_mov_b32_e32 v66, v84
	v_mov_b32_e32 v67, v84
	v_mov_b32_e32 v62, v84
	v_mov_b32_e32 v63, v84
	v_mov_b32_e32 v58, v84
	v_mov_b32_e32 v59, v84
	v_mov_b32_e32 v54, v84
	v_mov_b32_e32 v55, v84
	v_mov_b32_e32 v50, v84
	v_mov_b32_e32 v51, v84
	v_mov_b32_e32 v46, v84
	v_mov_b32_e32 v47, v84
	v_mov_b32_e32 v42, v84
	v_mov_b32_e32 v43, v84
	v_mov_b32_e32 v38, v84
	v_mov_b32_e32 v39, v84
	v_mov_b32_e32 v34, v84
	v_mov_b32_e32 v35, v84
	v_mov_b32_e32 v30, v84
	v_mov_b32_e32 v31, v84
	global_load_dword v106, v[22:23], off
	global_load_dword v102, v[20:21], off
	global_load_dword v116, v[22:23], off offset:256
	global_load_dword v114, v[20:21], off offset:256
.LBB0_522:
	v_lshl_add_u64 v[104:105], v[22:23], 0, s[0:1]
	v_lshl_add_u64 v[100:101], v[20:21], 0, s[0:1]
	s_cmpk_eq_i32 s0, 0x3e00
	s_cbranch_scc1 .Llru_nopf
	global_load_dword v110, v[104:105], off offset:512
	global_load_dword v111, v[100:101], off offset:512
	global_load_dword v112, v[104:105], off offset:768
	global_load_dword v113, v[100:101], off offset:768
.Llru_nopf:
	ds_read_b128 v[6:9], v87
	ds_read_b128 v[88:91], v87 offset:16
	ds_read_b128 v[92:95], v87 offset:32
	ds_read_b128 v[96:99], v87 offset:48
	s_add_u32 s0, s0, 0x200
	s_addc_u32 s1, s1, 0
	s_cmpk_eq_i32 s0, 0x4000
	s_waitcnt vmcnt(4) lgkmcnt(3)
	v_pk_fma_f32 v[108:109], v[106:107], v[6:7], v[0:1] op_sel_hi:[0,1,1]
	ds_read_b128 v[0:3], v87 offset:64
	v_pk_fma_f32 v[78:79], v[102:103], v[8:9], v[78:79] op_sel_hi:[0,1,1]
	v_pk_fma_f32 v[80:81], v[106:107], v[8:9], v[80:81] op_sel_hi:[0,1,1]
	s_waitcnt lgkmcnt(3)
	v_pk_fma_f32 v[72:73], v[102:103], v[90:91], v[72:73] op_sel_hi:[0,1,1]
	v_pk_fma_f32 v[14:15], v[106:107], v[90:91], v[14:15] op_sel_hi:[0,1,1]
	s_waitcnt lgkmcnt(2)
	v_pk_fma_f32 v[90:91], v[106:107], v[92:93], v[10:11] op_sel_hi:[0,1,1]
	ds_read_b128 v[8:11], v87 offset:112
	s_waitcnt lgkmcnt(1)
	v_pk_fma_f32 v[58:59], v[102:103], v[0:1], v[58:59] op_sel_hi:[0,1,1]
	v_pk_fma_f32 v[54:55], v[102:103], v[2:3], v[54:55] op_sel_hi:[0,1,1]
	v_pk_fma_f32 v[56:57], v[106:107], v[0:1], v[56:57] op_sel_hi:[0,1,1]
	v_pk_fma_f32 v[52:53], v[106:107], v[2:3], v[52:53] op_sel_hi:[0,1,1]
	ds_read_b128 v[0:3], v87 offset:80
	v_pk_fma_f32 v[76:77], v[102:103], v[88:89], v[76:77] op_sel_hi:[0,1,1]
	v_pk_fma_f32 v[74:75], v[106:107], v[88:89], v[74:75] op_sel_hi:[0,1,1]
	v_pk_fma_f32 v[88:89], v[102:103], v[92:93], v[12:13] op_sel_hi:[0,1,1]
	v_pk_fma_f32 v[70:71], v[102:103], v[94:95], v[70:71] op_sel_hi:[0,1,1]
	v_pk_fma_f32 v[68:69], v[106:107], v[94:95], v[68:69] op_sel_hi:[0,1,1]
	s_waitcnt lgkmcnt(0)
	v_pk_fma_f32 v[50:51], v[102:103], v[0:1], v[50:51] op_sel_hi:[0,1,1]
	v_pk_fma_f32 v[46:47], v[102:103], v[2:3], v[46:47] op_sel_hi:[0,1,1]
	v_pk_fma_f32 v[48:49], v[106:107], v[0:1], v[48:49] op_sel_hi:[0,1,1]
	v_pk_fma_f32 v[44:45], v[106:107], v[2:3], v[44:45] op_sel_hi:[0,1,1]
	ds_read_b128 v[0:3], v87 offset:96
	v_pk_fma_f32 v[82:83], v[102:103], v[6:7], v[82:83] op_sel_hi:[0,1,1]
	v_pk_fma_f32 v[6:7], v[102:103], v[10:11], v[30:31] op_sel_hi:[0,1,1]
	v_pk_fma_f32 v[28:29], v[106:107], v[10:11], v[28:29] op_sel_hi:[0,1,1]
	ds_read_b128 v[10:13], v87 offset:272
	s_waitcnt lgkmcnt(1)
	v_pk_fma_f32 v[42:43], v[102:103], v[0:1], v[42:43] op_sel_hi:[0,1,1]
	v_pk_fma_f32 v[38:39], v[102:103], v[2:3], v[38:39] op_sel_hi:[0,1,1]
	v_pk_fma_f32 v[40:41], v[106:107], v[0:1], v[40:41] op_sel_hi:[0,1,1]
	v_pk_fma_f32 v[36:37], v[106:107], v[2:3], v[36:37] op_sel_hi:[0,1,1]
	v_pk_fma_f32 v[2:3], v[102:103], v[8:9], v[34:35] op_sel_hi:[0,1,1]
	v_pk_fma_f32 v[8:9], v[106:107], v[8:9], v[32:33] op_sel_hi:[0,1,1]
	ds_read_b128 v[30:33], v87 offset:304
	v_pk_fma_f32 v[66:67], v[102:103], v[96:97], v[66:67] op_sel_hi:[0,1,1]
	v_pk_fma_f32 v[62:63], v[102:103], v[98:99], v[62:63] op_sel_hi:[0,1,1]
	v_pk_fma_f32 v[64:65], v[106:107], v[96:97], v[64:65] op_sel_hi:[0,1,1]
	v_pk_fma_f32 v[60:61], v[106:107], v[98:99], v[60:61] op_sel_hi:[0,1,1]
	s_waitcnt lgkmcnt(1)
	v_pk_fma_f32 v[82:83], v[114:115], v[10:11], v[82:83] op_sel_hi:[0,1,1]
	v_pk_fma_f32 v[78:79], v[114:115], v[12:13], v[78:79] op_sel_hi:[0,1,1]
	v_pk_fma_f32 v[0:1], v[116:117], v[10:11], v[108:109] op_sel_hi:[0,1,1]
	v_pk_fma_f32 v[80:81], v[116:117], v[12:13], v[80:81] op_sel_hi:[0,1,1]
	ds_read_b128 v[10:13], v87 offset:288
	s_waitcnt lgkmcnt(1)
	v_pk_fma_f32 v[70:71], v[114:115], v[32:33], v[70:71] op_sel_hi:[0,1,1]
	v_pk_fma_f32 v[68:69], v[116:117], v[32:33], v[68:69] op_sel_hi:[0,1,1]
	s_waitcnt lgkmcnt(0)
	v_pk_fma_f32 v[76:77], v[114:115], v[10:11], v[76:77] op_sel_hi:[0,1,1]
	v_pk_fma_f32 v[72:73], v[114:115], v[12:13], v[72:73] op_sel_hi:[0,1,1]
	v_pk_fma_f32 v[74:75], v[116:117], v[10:11], v[74:75] op_sel_hi:[0,1,1]
	v_pk_fma_f32 v[14:15], v[116:117], v[12:13], v[14:15] op_sel_hi:[0,1,1]
	v_pk_fma_f32 v[12:13], v[114:115], v[30:31], v[88:89] op_sel_hi:[0,1,1]
	v_pk_fma_f32 v[10:11], v[116:117], v[30:31], v[90:91] op_sel_hi:[0,1,1]
	ds_read_b128 v[30:33], v87 offset:320
	ds_read_b128 v[88:91], v87 offset:384
	s_waitcnt lgkmcnt(1)
	v_pk_fma_f32 v[66:67], v[114:115], v[30:31], v[66:67] op_sel_hi:[0,1,1]
	v_pk_fma_f32 v[62:63], v[114:115], v[32:33], v[62:63] op_sel_hi:[0,1,1]
	v_pk_fma_f32 v[64:65], v[116:117], v[30:31], v[64:65] op_sel_hi:[0,1,1]
	v_pk_fma_f32 v[60:61], v[116:117], v[32:33], v[60:61] op_sel_hi:[0,1,1]
	ds_read_b128 v[30:33], v87 offset:336
	s_waitcnt lgkmcnt(1)
	v_pk_fma_f32 v[34:35], v[114:115], v[88:89], v[2:3] op_sel_hi:[0,1,1]
	v_pk_fma_f32 v[28:29], v[116:117], v[90:91], v[28:29] op_sel_hi:[0,1,1]
	s_waitcnt lgkmcnt(0)
	v_pk_fma_f32 v[58:59], v[114:115], v[30:31], v[58:59] op_sel_hi:[0,1,1]
	v_pk_fma_f32 v[54:55], v[114:115], v[32:33], v[54:55] op_sel_hi:[0,1,1]
	v_pk_fma_f32 v[56:57], v[116:117], v[30:31], v[56:57] op_sel_hi:[0,1,1]
	v_pk_fma_f32 v[52:53], v[116:117], v[32:33], v[52:53] op_sel_hi:[0,1,1]
	ds_read_b128 v[30:33], v87 offset:352
	s_waitcnt lgkmcnt(0)
	v_pk_fma_f32 v[50:51], v[114:115], v[30:31], v[50:51] op_sel_hi:[0,1,1]
	v_pk_fma_f32 v[46:47], v[114:115], v[32:33], v[46:47] op_sel_hi:[0,1,1]
	v_pk_fma_f32 v[48:49], v[116:117], v[30:31], v[48:49] op_sel_hi:[0,1,1]
	v_pk_fma_f32 v[44:45], v[116:117], v[32:33], v[44:45] op_sel_hi:[0,1,1]
	ds_read_b128 v[30:33], v87 offset:368
	v_add_u32_e32 v87, 0x220, v87
	s_waitcnt lgkmcnt(0)
	v_pk_fma_f32 v[42:43], v[114:115], v[30:31], v[42:43] op_sel_hi:[0,1,1]
	v_pk_fma_f32 v[38:39], v[114:115], v[32:33], v[38:39] op_sel_hi:[0,1,1]
	v_pk_fma_f32 v[40:41], v[116:117], v[30:31], v[40:41] op_sel_hi:[0,1,1]
	v_pk_fma_f32 v[36:37], v[116:117], v[32:33], v[36:37] op_sel_hi:[0,1,1]
	v_pk_fma_f32 v[30:31], v[114:115], v[90:91], v[6:7] op_sel_hi:[0,1,1]
	v_pk_fma_f32 v[32:33], v[116:117], v[88:89], v[8:9] op_sel_hi:[0,1,1]
	s_waitcnt vmcnt(0)
	v_mov_b32_e32 v106, v110
	v_mov_b32_e32 v102, v111
	v_mov_b32_e32 v116, v112
	v_mov_b32_e32 v114, v113
	s_cbranch_scc0 .LBB0_522
	v_mul_f32_e32 v0, 0xbfb8aa3b, v0
	v_exp_f32_e32 v0, v0
	v_mul_f32_e32 v2, 0xbfb8aa3b, v82
	v_exp_f32_e32 v89, v2
	s_mov_b32 s18, 0xf800000
	v_add_f32_e32 v0, 1.0, v0
	v_div_scale_f32 v3, s[0:1], v0, v0, 1.0
	v_rcp_f32_e32 v6, v3
	v_div_scale_f32 v2, vcc, 1.0, v0, 1.0
	s_lshl_b32 s10, s10, 7
	v_fma_f32 v7, -v3, v6, 1.0
	v_fmac_f32_e32 v6, v7, v6
	v_mul_f32_e32 v7, v2, v6
	v_fma_f32 v8, -v3, v7, v2
	v_fmac_f32_e32 v7, v8, v6
	v_fma_f32 v2, -v3, v7, v2
	v_div_fmas_f32 v2, v2, v6, v7
	v_div_fixup_f32 v90, v2, v0, 1.0
	v_mul_f32_e32 v0, 0xbfb8aa3b, v1
	v_exp_f32_e32 v82, v0
	v_add_u32_e32 v87, s10, v86
	ds_read_b128 v[6:9], v87
	ds_read_b128 v[0:3], v87 offset:16
	s_mov_b32 s19, 0xc1880000
	v_add_f32_e32 v91, 1.0, v82
	v_div_scale_f32 v92, s[0:1], v91, v91, 1.0
	v_rcp_f32_e32 v93, v92
	v_mul_f32_e32 v82, 0xbfb8aa3b, v83
	v_exp_f32_e32 v88, v82
	v_div_scale_f32 v94, vcc, 1.0, v91, 1.0
	v_fma_f32 v82, -v92, v93, 1.0
	v_fmac_f32_e32 v93, v82, v93
	v_mul_f32_e32 v95, v94, v93
	v_fma_f32 v82, -v92, v95, v94
	v_fmac_f32_e32 v95, v82, v93
	v_pk_add_f32 v[82:83], v[88:89], 1.0 op_sel_hi:[1,0]
	v_fma_f32 v92, -v92, v95, v94
	v_div_scale_f32 v88, s[0:1], v83, v83, 1.0
	v_rcp_f32_e32 v89, v88
	v_div_fmas_f32 v92, v92, v93, v95
	v_div_fixup_f32 v91, v92, v91, 1.0
	s_add_i32 s11, s10, 0x11000
	v_fma_f32 v93, -v88, v89, 1.0
	v_fmac_f32_e32 v89, v93, v89
	v_div_scale_f32 v93, vcc, 1.0, v83, 1.0
	v_mul_f32_e32 v94, v93, v89
	v_fma_f32 v95, -v88, v94, v93
	v_fmac_f32_e32 v94, v95, v89
	v_fma_f32 v88, -v88, v94, v93
	v_div_scale_f32 v93, s[0:1], v82, v82, 1.0
	v_rcp_f32_e32 v95, v93
	v_div_fmas_f32 v88, v88, v89, v94
	v_div_fixup_f32 v83, v88, v83, 1.0
	v_mul_f32_e32 v80, 0xbfb8aa3b, v80
	v_fma_f32 v88, -v93, v95, 1.0
	v_fmac_f32_e32 v95, v88, v95
	v_div_scale_f32 v88, vcc, 1.0, v82, 1.0
	v_mul_f32_e32 v89, v88, v95
	v_fma_f32 v94, -v93, v89, v88
	v_fmac_f32_e32 v89, v94, v95
	v_fma_f32 v88, -v93, v89, v88
	v_div_fmas_f32 v88, v88, v95, v89
	v_div_fixup_f32 v82, v88, v82, 1.0
	v_pk_mul_f32 v[82:83], v[82:83], s[44:45] op_sel_hi:[1,0]
	v_exp_f32_e32 v80, v80
	v_pk_mul_f32 v[82:83], v[18:19], v[82:83]
	v_readlane_b32 s14, v247, 4
	v_pk_add_f32 v[88:89], v[82:83], v[82:83]
	v_mul_f32_e32 v83, 0x3fb8aa3b, v83
	v_mul_f32_e32 v93, 0x3fb8aa3b, v89
	v_rndne_f32_e32 v93, v93
	v_fmamk_f32 v94, v93, 0xbf317218, v89
	v_fmac_f32_e32 v94, 0x3102e308, v93
	v_fmamk_f32 v95, v94, 0x395133b1, v180
	v_fmaak_f32 v95, v94, v95, 0x3c0887f9
	v_fmaak_f32 v95, v94, v95, 0x3d2aaa81
	v_cvt_i32_f32_e32 v96, v93
	v_fmaak_f32 v95, v94, v95, 0x3e2aaaab
	v_fma_f32 v95, v94, v95, 0.5
	v_mul_f32_e32 v95, v94, v95
	v_fmac_f32_e32 v94, v94, v95
	v_ldexp_f32 v95, 1.0, v96
	v_cmp_eq_f32_e32 vcc, s34, v93
	v_exp_f32_e32 v83, v83
	v_readlane_b32 s16, v247, 6
	v_cndmask_b32_e32 v93, v95, v197, vcc
	v_add_f32_e32 v95, -1.0, v93
	v_fmac_f32_e32 v95, v93, v94
	v_add_f32_e32 v93, v95, v95
	v_cndmask_b32_e32 v93, v95, v93, vcc
	v_cmp_nlt_f32_e32 vcc, s35, v89
	v_readlane_b32 s15, v247, 5
	v_readlane_b32 s17, v247, 7
	v_cndmask_b32_e64 v93, v190, -v93, vcc
	v_mul_f32_e32 v94, 0x4f800000, v93
	v_cmp_gt_f32_e32 vcc, s18, v93
	v_add_f32_e32 v80, 1.0, v80
	v_mul_f32_e32 v78, 0xbfb8aa3b, v78
	v_cndmask_b32_e32 v93, v93, v94, vcc
	v_sqrt_f32_e32 v94, v93
	v_mul_f32_e32 v81, 0xbfb8aa3b, v81
	v_exp_f32_e32 v81, v81
	v_mul_f32_e32 v74, 0xbfb8aa3b, v74
	v_add_u32_e32 v92, -1, v94
	v_fma_f32 v95, -v92, v94, v93
	v_cmp_ge_f32_e64 s[0:1], 0, v95
	v_add_u32_e32 v95, 1, v94
	v_exp_f32_e32 v74, v74
	v_cndmask_b32_e64 v92, v94, v92, s[0:1]
	v_fma_f32 v94, -v95, v94, v93
	v_cmp_lt_f32_e64 s[0:1], 0, v94
	v_add_f32_e32 v74, 1.0, v74
	v_mul_f32_e32 v75, 0xbfb8aa3b, v75
	v_cndmask_b32_e64 v92, v92, v95, s[0:1]
	v_mul_f32_e32 v94, 0x37800000, v92
	v_cndmask_b32_e32 v92, v92, v94, vcc
	v_cmp_class_f32_e32 vcc, v93, v181
	v_exp_f32_e32 v75, v75
	v_mul_f32_e32 v69, 0xbfb8aa3b, v69
	v_cndmask_b32_e32 v92, v92, v93, vcc
	v_cmp_ngt_f32_e32 vcc, s19, v89
	v_exp_f32_e32 v69, v69
	v_mul_f32_e32 v53, 0xbfb8aa3b, v53
	v_cndmask_b32_e32 v89, 1.0, v92, vcc
	v_mul_f32_e32 v89, v90, v89
	s_waitcnt lgkmcnt(1)
	v_mul_f32_e32 v96, v89, v6
	v_fmac_f32_e32 v96, v4, v83
	v_mul_f32_e32 v4, 0x3fb8aa3b, v88
	v_rndne_f32_e32 v4, v4
	v_fmamk_f32 v6, v4, 0xbf317218, v88
	v_fmac_f32_e32 v6, 0x3102e308, v4
	v_fmamk_f32 v89, v6, 0x395133b1, v180
	v_fmaak_f32 v89, v6, v89, 0x3c0887f9
	v_fmaak_f32 v89, v6, v89, 0x3d2aaa81
	v_cvt_i32_f32_e32 v90, v4
	v_fmaak_f32 v89, v6, v89, 0x3e2aaaab
	v_fma_f32 v89, v6, v89, 0.5
	v_mul_f32_e32 v89, v6, v89
	v_fmac_f32_e32 v6, v6, v89
	v_ldexp_f32 v89, 1.0, v90
	v_cmp_eq_f32_e32 vcc, s34, v4
	v_mul_f32_e32 v83, v5, v83
	v_mul_f32_e32 v5, 0x3fb8aa3b, v82
	v_cndmask_b32_e32 v4, v89, v197, vcc
	v_add_f32_e32 v89, -1.0, v4
	v_fmac_f32_e32 v89, v4, v6
	v_add_f32_e32 v4, v89, v89
	v_cndmask_b32_e32 v4, v89, v4, vcc
	v_cmp_nlt_f32_e32 vcc, s35, v88
	v_exp_f32_e32 v5, v5
	v_exp_f32_e32 v53, v53
	v_cndmask_b32_e64 v4, v190, -v4, vcc
	v_mul_f32_e32 v6, 0x4f800000, v4
	v_cmp_gt_f32_e32 vcc, s18, v4
	v_mul_f32_e32 v98, v5, v83
	v_mul_f32_e32 v37, 0xbfb8aa3b, v37
	v_cndmask_b32_e32 v4, v4, v6, vcc
	v_sqrt_f32_e32 v6, v4
	v_exp_f32_e32 v37, v37
	s_mov_b32 s10, 1
	v_add_u32_e32 v82, -1, v6
	v_fma_f32 v89, -v82, v6, v4
	v_cmp_ge_f32_e64 s[0:1], 0, v89
	v_add_u32_e32 v89, 1, v6
	s_nop 0
	v_cndmask_b32_e64 v82, v6, v82, s[0:1]
	v_fma_f32 v6, -v89, v6, v4
	v_cmp_lt_f32_e64 s[0:1], 0, v6
	s_nop 1
	v_cndmask_b32_e64 v6, v82, v89, s[0:1]
	v_mul_f32_e32 v82, 0x37800000, v6
	v_cndmask_b32_e32 v6, v6, v82, vcc
	v_cmp_class_f32_e32 vcc, v4, v181
	v_mov_b32_e32 v82, s11
	s_nop 0
	v_cndmask_b32_e32 v4, v6, v4, vcc
	v_cmp_ngt_f32_e32 vcc, s19, v88
	s_nop 1
	v_cndmask_b32_e32 v4, 1.0, v4, vcc
	v_mul_f32_e32 v4, v91, v4
	ds_read_b128 v[88:91], v82
	v_mul_f32_e32 v97, v4, v7
	v_fmac_f32_e32 v97, v5, v96
	ds_read_b128 v[4:7], v82 offset:16
	s_waitcnt lgkmcnt(1)
	v_ashrrev_i32_e32 v93, 31, v89
	v_mov_b32_e32 v92, v89
	v_ashrrev_i32_e32 v89, 31, v88
	v_lshlrev_b64 v[88:89], 9, v[88:89]
	v_lshl_add_u64 v[88:89], v[88:89], 0, v[24:25]
	v_lshlrev_b64 v[92:93], 9, v[92:93]
	v_lshlrev_b64 v[88:89], 2, v[88:89]
	v_lshl_add_u64 v[92:93], v[92:93], 0, v[26:27]
	v_lshl_add_u64 v[94:95], s[14:15], 0, v[88:89]
	v_lshl_add_u64 v[88:89], s[16:17], 0, v[88:89]
	global_store_dword v[94:95], v83, off
	global_store_dword v[88:89], v96, off
	v_lshlrev_b64 v[88:89], 2, v[92:93]
	v_lshl_add_u64 v[92:93], s[14:15], 0, v[88:89]
	v_div_scale_f32 v83, s[0:1], v80, v80, 1.0
	global_store_dword v[92:93], v98, off
	v_rcp_f32_e32 v92, v83
	v_lshl_add_u64 v[88:89], s[16:17], 0, v[88:89]
	global_store_dword v[88:89], v97, off
	v_exp_f32_e32 v89, v78
	v_fma_f32 v78, -v83, v92, 1.0
	v_fmac_f32_e32 v92, v78, v92
	v_div_scale_f32 v78, vcc, 1.0, v80, 1.0
	v_mul_f32_e32 v88, v78, v92
	v_fma_f32 v93, -v83, v88, v78
	v_fmac_f32_e32 v88, v93, v92
	v_fma_f32 v78, -v83, v88, v78
	v_add_f32_e32 v83, 1.0, v81
	v_div_scale_f32 v81, s[0:1], v83, v83, 1.0
	v_div_fmas_f32 v78, v78, v92, v88
	v_rcp_f32_e32 v92, v81
	v_div_fixup_f32 v93, v78, v80, 1.0
	v_mul_f32_e32 v78, 0xbfb8aa3b, v79
	v_exp_f32_e32 v88, v78
	v_fma_f32 v78, -v81, v92, 1.0
	v_fmac_f32_e32 v92, v78, v92
	v_div_scale_f32 v80, vcc, 1.0, v83, 1.0
	v_mul_f32_e32 v94, v80, v92
	v_fma_f32 v78, -v81, v94, v80
	v_fmac_f32_e32 v94, v78, v92
	v_pk_add_f32 v[78:79], v[88:89], 1.0 op_sel_hi:[1,0]
	v_fma_f32 v80, -v81, v94, v80
	v_div_scale_f32 v88, s[0:1], v79, v79, 1.0
	v_rcp_f32_e32 v89, v88
	v_div_fmas_f32 v92, v80, v92, v94
	v_div_fixup_f32 v83, v92, v83, 1.0
	v_fma_f32 v80, -v88, v89, 1.0
	v_fmac_f32_e32 v89, v80, v89
	v_div_scale_f32 v80, vcc, 1.0, v79, 1.0
	v_mul_f32_e32 v81, v80, v89
	v_fma_f32 v94, -v88, v81, v80
	v_fmac_f32_e32 v81, v94, v89
	v_fma_f32 v80, -v88, v81, v80
	v_div_scale_f32 v88, s[0:1], v78, v78, 1.0
	v_rcp_f32_e32 v94, v88
	v_div_fmas_f32 v80, v80, v89, v81
	v_div_fixup_f32 v79, v80, v79, 1.0
	v_fma_f32 v80, -v88, v94, 1.0
	v_fmac_f32_e32 v94, v80, v94
	v_div_scale_f32 v80, vcc, 1.0, v78, 1.0
	v_mul_f32_e32 v81, v80, v94
	v_fma_f32 v89, -v88, v81, v80
	v_fmac_f32_e32 v81, v89, v94
	v_fma_f32 v80, -v88, v81, v80
	v_div_fmas_f32 v80, v80, v94, v81
	v_div_fixup_f32 v78, v80, v78, 1.0
	v_pk_mul_f32 v[78:79], v[78:79], s[44:45] op_sel_hi:[1,0]
	s_nop 0
	v_pk_mul_f32 v[78:79], v[18:19], v[78:79]
	s_nop 0
	v_pk_add_f32 v[80:81], v[78:79], v[78:79]
	v_mul_f32_e32 v79, 0x3fb8aa3b, v79
	v_mul_f32_e32 v88, 0x3fb8aa3b, v81
	v_rndne_f32_e32 v88, v88
	v_fmamk_f32 v89, v88, 0xbf317218, v81
	v_fmac_f32_e32 v89, 0x3102e308, v88
	v_fmamk_f32 v94, v89, 0x395133b1, v180
	v_fmaak_f32 v94, v89, v94, 0x3c0887f9
	v_fmaak_f32 v94, v89, v94, 0x3d2aaa81
	v_cvt_i32_f32_e32 v95, v88
	v_fmaak_f32 v94, v89, v94, 0x3e2aaaab
	v_fma_f32 v94, v89, v94, 0.5
	v_mul_f32_e32 v94, v89, v94
	v_fmac_f32_e32 v89, v89, v94
	v_ldexp_f32 v94, 1.0, v95
	v_cmp_eq_f32_e32 vcc, s34, v88
	v_exp_f32_e32 v79, v79
	v_mul_f32_e32 v78, 0x3fb8aa3b, v78
	v_cndmask_b32_e32 v88, v94, v197, vcc
	v_add_f32_e32 v94, -1.0, v88
	v_fmac_f32_e32 v94, v88, v89
	v_add_f32_e32 v88, v94, v94
	v_cndmask_b32_e32 v88, v94, v88, vcc
	v_cmp_nlt_f32_e32 vcc, s35, v81
	v_exp_f32_e32 v78, v78
	s_nop 0
	v_cndmask_b32_e64 v88, v190, -v88, vcc
	v_mul_f32_e32 v89, 0x4f800000, v88
	v_cmp_gt_f32_e32 vcc, s18, v88
	s_nop 1
	v_cndmask_b32_e32 v88, v88, v89, vcc
	v_sqrt_f32_e32 v89, v88
	s_nop 0
	v_add_u32_e32 v92, -1, v89
	v_fma_f32 v94, -v92, v89, v88
	v_cmp_ge_f32_e64 s[0:1], 0, v94
	v_add_u32_e32 v94, 1, v89
	s_nop 0
	v_cndmask_b32_e64 v92, v89, v92, s[0:1]
	v_fma_f32 v89, -v94, v89, v88
	v_cmp_lt_f32_e64 s[0:1], 0, v89
	s_nop 1
	v_cndmask_b32_e64 v89, v92, v94, s[0:1]
	v_mul_f32_e32 v92, 0x37800000, v89
	v_cndmask_b32_e32 v89, v89, v92, vcc
	v_cmp_class_f32_e32 vcc, v88, v181
	s_nop 1
	v_cndmask_b32_e32 v88, v89, v88, vcc
	v_cmp_ngt_f32_e32 vcc, s19, v81
	s_nop 1
	v_cndmask_b32_e32 v81, 1.0, v88, vcc
	v_mul_f32_e32 v81, v93, v81
	v_mul_f32_e32 v88, v81, v8
	v_mul_f32_e32 v8, 0x3fb8aa3b, v80
	v_rndne_f32_e32 v8, v8
	v_fmamk_f32 v81, v8, 0xbf317218, v80
	v_fmac_f32_e32 v81, 0x3102e308, v8
	v_fmamk_f32 v89, v81, 0x395133b1, v180
	v_fmaak_f32 v89, v81, v89, 0x3c0887f9
	v_fmaak_f32 v89, v81, v89, 0x3d2aaa81
	v_cvt_i32_f32_e32 v92, v8
	v_fmaak_f32 v89, v81, v89, 0x3e2aaaab
	v_fma_f32 v89, v81, v89, 0.5
	v_mul_f32_e32 v89, v81, v89
	v_fmac_f32_e32 v81, v81, v89
	v_ldexp_f32 v89, 1.0, v92
	v_cmp_eq_f32_e32 vcc, s34, v8
	v_fmac_f32_e32 v88, v79, v97
	s_nop 0
	v_cndmask_b32_e32 v8, v89, v197, vcc
	v_add_f32_e32 v89, -1.0, v8
	v_fmac_f32_e32 v89, v8, v81
	v_add_f32_e32 v8, v89, v89
	v_cndmask_b32_e32 v8, v89, v8, vcc
	v_cmp_nlt_f32_e32 vcc, s35, v80
	v_mul_f32_e32 v89, v79, v98
	s_nop 0
	v_cndmask_b32_e64 v8, v190, -v8, vcc
	v_mul_f32_e32 v81, 0x4f800000, v8
	v_cmp_gt_f32_e32 vcc, s18, v8
	s_nop 1
	v_cndmask_b32_e32 v8, v8, v81, vcc
	v_sqrt_f32_e32 v81, v8
	s_nop 0
	v_add_u32_e32 v79, -1, v81
	v_fma_f32 v92, -v79, v81, v8
	v_cmp_ge_f32_e64 s[0:1], 0, v92
	v_add_u32_e32 v92, 1, v81
	s_nop 0
	v_cndmask_b32_e64 v79, v81, v79, s[0:1]
	v_fma_f32 v81, -v92, v81, v8
	v_cmp_lt_f32_e64 s[0:1], 0, v81
	s_nop 1
	v_cndmask_b32_e64 v79, v79, v92, s[0:1]
	v_mul_f32_e32 v81, 0x37800000, v79
	v_cndmask_b32_e32 v79, v79, v81, vcc
	v_cmp_class_f32_e32 vcc, v8, v181
	v_mul_f32_e32 v92, v78, v89
	s_nop 0
	v_cndmask_b32_e32 v8, v79, v8, vcc
	v_cmp_ngt_f32_e32 vcc, s19, v80
	s_nop 1
	v_cndmask_b32_e32 v8, 1.0, v8, vcc
	v_mul_f32_e32 v8, v83, v8
	v_mul_f32_e32 v83, v8, v9
	v_ashrrev_i32_e32 v9, 31, v91
	v_mov_b32_e32 v8, v91
	v_ashrrev_i32_e32 v91, 31, v90
	v_fmac_f32_e32 v83, v78, v88
	v_lshlrev_b64 v[78:79], 9, v[90:91]
	v_lshlrev_b64 v[8:9], 9, v[8:9]
	v_lshl_add_u64 v[78:79], v[78:79], 0, v[24:25]
	v_lshl_add_u64 v[8:9], v[8:9], 0, v[26:27]
	v_lshlrev_b64 v[78:79], 2, v[78:79]
	v_lshl_add_u64 v[80:81], s[14:15], 0, v[78:79]
	v_lshl_add_u64 v[78:79], s[16:17], 0, v[78:79]
	v_lshlrev_b64 v[8:9], 2, v[8:9]
	global_store_dword v[80:81], v89, off
	global_store_dword v[78:79], v88, off
	v_lshl_add_u64 v[78:79], s[14:15], 0, v[8:9]
	global_store_dword v[78:79], v92, off
	v_div_scale_f32 v78, s[0:1], v74, v74, 1.0
	v_rcp_f32_e32 v79, v78
	v_lshl_add_u64 v[8:9], s[16:17], 0, v[8:9]
	global_store_dword v[8:9], v83, off
	v_mul_f32_e32 v8, 0xbfb8aa3b, v76
	v_exp_f32_e32 v9, v8
	v_fma_f32 v8, -v78, v79, 1.0
	v_fmac_f32_e32 v79, v8, v79
	v_div_scale_f32 v8, vcc, 1.0, v74, 1.0
	v_mul_f32_e32 v76, v8, v79
	v_fma_f32 v80, -v78, v76, v8
	v_fmac_f32_e32 v76, v80, v79
	v_fma_f32 v8, -v78, v76, v8
	v_div_fmas_f32 v8, v8, v79, v76
	v_add_f32_e32 v76, 1.0, v75
	v_div_scale_f32 v75, s[0:1], v76, v76, 1.0
	v_rcp_f32_e32 v78, v75
	v_div_fixup_f32 v79, v8, v74, 1.0
	v_mul_f32_e32 v8, 0xbfb8aa3b, v77
	v_exp_f32_e32 v8, v8
	v_fma_f32 v74, -v75, v78, 1.0
	v_fmac_f32_e32 v78, v74, v78
	v_div_scale_f32 v74, vcc, 1.0, v76, 1.0
	v_mul_f32_e32 v77, v74, v78
	v_fma_f32 v80, -v75, v77, v74
	v_pk_add_f32 v[8:9], v[8:9], 1.0 op_sel_hi:[1,0]
	v_fmac_f32_e32 v77, v80, v78
	v_div_scale_f32 v80, s[0:1], v9, v9, 1.0
	v_rcp_f32_e32 v81, v80
	v_fma_f32 v74, -v75, v77, v74
	v_div_fmas_f32 v77, v74, v78, v77
	v_div_fixup_f32 v76, v77, v76, 1.0
	v_fma_f32 v74, -v80, v81, 1.0
	v_fmac_f32_e32 v81, v74, v81
	v_div_scale_f32 v74, vcc, 1.0, v9, 1.0
	v_mul_f32_e32 v75, v74, v81
	v_fma_f32 v78, -v80, v75, v74
	v_fmac_f32_e32 v75, v78, v81
	v_div_scale_f32 v78, s[0:1], v8, v8, 1.0
	v_fma_f32 v74, -v80, v75, v74
	v_rcp_f32_e32 v80, v78
	v_div_fmas_f32 v74, v74, v81, v75
	v_div_fixup_f32 v9, v74, v9, 1.0
	v_fma_f32 v74, -v78, v80, 1.0
	v_fmac_f32_e32 v80, v74, v80
	v_div_scale_f32 v74, vcc, 1.0, v8, 1.0
	v_mul_f32_e32 v75, v74, v80
	v_fma_f32 v81, -v78, v75, v74
	v_fmac_f32_e32 v75, v81, v80
	v_fma_f32 v74, -v78, v75, v74
	v_div_fmas_f32 v74, v74, v80, v75
	v_div_fixup_f32 v8, v74, v8, 1.0
	v_pk_mul_f32 v[8:9], v[8:9], s[44:45] op_sel_hi:[1,0]
	s_nop 0
	v_pk_mul_f32 v[8:9], v[18:19], v[8:9]
	s_nop 0
	v_pk_add_f32 v[74:75], v[8:9], v[8:9]
	v_mul_f32_e32 v9, 0x3fb8aa3b, v9
	v_mul_f32_e32 v78, 0x3fb8aa3b, v75
	v_rndne_f32_e32 v78, v78
	v_fmamk_f32 v80, v78, 0xbf317218, v75
	v_fmac_f32_e32 v80, 0x3102e308, v78
	v_fmamk_f32 v81, v80, 0x395133b1, v180
	v_fmaak_f32 v81, v80, v81, 0x3c0887f9
	v_fmaak_f32 v81, v80, v81, 0x3d2aaa81
	v_cvt_i32_f32_e32 v88, v78
	v_fmaak_f32 v81, v80, v81, 0x3e2aaaab
	v_fma_f32 v81, v80, v81, 0.5
	v_mul_f32_e32 v81, v80, v81
	v_fmac_f32_e32 v80, v80, v81
	v_ldexp_f32 v81, 1.0, v88
	v_cmp_eq_f32_e32 vcc, s34, v78
	v_exp_f32_e32 v9, v9
	v_mul_f32_e32 v8, 0x3fb8aa3b, v8
	v_cndmask_b32_e32 v78, v81, v197, vcc
	v_add_f32_e32 v81, -1.0, v78
	v_fmac_f32_e32 v81, v78, v80
	v_add_f32_e32 v78, v81, v81
	v_cndmask_b32_e32 v78, v81, v78, vcc
	v_cmp_nlt_f32_e32 vcc, s35, v75
	v_exp_f32_e32 v8, v8
	s_nop 0
	v_cndmask_b32_e64 v78, v190, -v78, vcc
	v_mul_f32_e32 v80, 0x4f800000, v78
	v_cmp_gt_f32_e32 vcc, s18, v78
	s_nop 1
	v_cndmask_b32_e32 v78, v78, v80, vcc
	v_sqrt_f32_e32 v80, v78
	s_nop 0
	v_add_u32_e32 v77, -1, v80
	v_fma_f32 v81, -v77, v80, v78
	v_cmp_ge_f32_e64 s[0:1], 0, v81
	v_add_u32_e32 v81, 1, v80
	s_nop 0
	v_cndmask_b32_e64 v77, v80, v77, s[0:1]
	v_fma_f32 v80, -v81, v80, v78
	v_cmp_lt_f32_e64 s[0:1], 0, v80
	s_nop 1
	v_cndmask_b32_e64 v77, v77, v81, s[0:1]
	v_mul_f32_e32 v80, 0x37800000, v77
	v_cndmask_b32_e32 v77, v77, v80, vcc
	v_cmp_class_f32_e32 vcc, v78, v181
	s_nop 1
	v_cndmask_b32_e32 v77, v77, v78, vcc
	v_cmp_ngt_f32_e32 vcc, s19, v75
	s_nop 1
	v_cndmask_b32_e32 v75, 1.0, v77, vcc
	v_mul_f32_e32 v75, v79, v75
	v_mul_f32_e32 v75, v75, v0
	v_mul_f32_e32 v0, 0x3fb8aa3b, v74
	v_rndne_f32_e32 v0, v0
	v_fmamk_f32 v77, v0, 0xbf317218, v74
	v_fmac_f32_e32 v77, 0x3102e308, v0
	v_fmamk_f32 v78, v77, 0x395133b1, v180
	v_fmaak_f32 v78, v77, v78, 0x3c0887f9
	v_fmaak_f32 v78, v77, v78, 0x3d2aaa81
	v_cvt_i32_f32_e32 v79, v0
	v_fmaak_f32 v78, v77, v78, 0x3e2aaaab
	v_fma_f32 v78, v77, v78, 0.5
	v_mul_f32_e32 v78, v77, v78
	v_fmac_f32_e32 v77, v77, v78
	v_ldexp_f32 v78, 1.0, v79
	v_cmp_eq_f32_e32 vcc, s34, v0
	v_fmac_f32_e32 v75, v9, v83
	s_nop 0
	v_cndmask_b32_e32 v0, v78, v197, vcc
	v_add_f32_e32 v78, -1.0, v0
	v_fmac_f32_e32 v78, v0, v77
	v_add_f32_e32 v0, v78, v78
	v_cndmask_b32_e32 v0, v78, v0, vcc
	v_cmp_nlt_f32_e32 vcc, s35, v74
	v_mul_f32_e32 v78, v9, v92
	s_nop 0
	v_cndmask_b32_e64 v0, v190, -v0, vcc
	v_mul_f32_e32 v77, 0x4f800000, v0
	v_cmp_gt_f32_e32 vcc, s18, v0
	s_nop 1
	v_cndmask_b32_e32 v0, v0, v77, vcc
	v_sqrt_f32_e32 v77, v0
	s_nop 0
	v_add_u32_e32 v9, -1, v77
	v_fma_f32 v79, -v9, v77, v0
	v_cmp_ge_f32_e64 s[0:1], 0, v79
	v_add_u32_e32 v79, 1, v77
	s_nop 0
	v_cndmask_b32_e64 v9, v77, v9, s[0:1]
	v_fma_f32 v77, -v79, v77, v0
	v_cmp_lt_f32_e64 s[0:1], 0, v77
	s_nop 1
	v_cndmask_b32_e64 v9, v9, v79, s[0:1]
	v_mul_f32_e32 v77, 0x37800000, v9
	v_cndmask_b32_e32 v9, v9, v77, vcc
	v_cmp_class_f32_e32 vcc, v0, v181
	s_nop 1
	v_cndmask_b32_e32 v0, v9, v0, vcc
	v_cmp_ngt_f32_e32 vcc, s19, v74
	s_nop 1
	v_cndmask_b32_e32 v0, 1.0, v0, vcc
	v_mul_f32_e32 v0, v76, v0
	v_mul_f32_e32 v74, v0, v1
	s_waitcnt lgkmcnt(0)
	v_ashrrev_i32_e32 v1, 31, v5
	v_mov_b32_e32 v0, v5
	v_ashrrev_i32_e32 v5, 31, v4
	v_lshlrev_b64 v[4:5], 9, v[4:5]
	v_lshl_add_u64 v[4:5], v[4:5], 0, v[24:25]
	v_lshlrev_b64 v[4:5], 2, v[4:5]
	v_fmac_f32_e32 v74, v8, v75
	v_mul_f32_e32 v76, v8, v78
	v_lshl_add_u64 v[8:9], s[14:15], 0, v[4:5]
	v_lshl_add_u64 v[4:5], s[16:17], 0, v[4:5]
	global_store_dword v[8:9], v78, off
	global_store_dword v[4:5], v75, off
	v_mul_f32_e32 v4, 0xbfb8aa3b, v14
	v_lshlrev_b64 v[0:1], 9, v[0:1]
	v_exp_f32_e32 v8, v4
	v_lshl_add_u64 v[0:1], v[0:1], 0, v[26:27]
	v_lshlrev_b64 v[0:1], 2, v[0:1]
	v_lshl_add_u64 v[4:5], s[14:15], 0, v[0:1]
	global_store_dword v[4:5], v76, off
	v_add_f32_e32 v4, 1.0, v8
	v_div_scale_f32 v5, s[0:1], v4, v4, 1.0
	v_rcp_f32_e32 v8, v5
	v_lshl_add_u64 v[0:1], s[16:17], 0, v[0:1]
	global_store_dword v[0:1], v74, off
	v_mul_f32_e32 v0, 0xbfb8aa3b, v72
	v_exp_f32_e32 v1, v0
	v_fma_f32 v0, -v5, v8, 1.0
	v_fmac_f32_e32 v8, v0, v8
	v_div_scale_f32 v0, vcc, 1.0, v4, 1.0
	v_mul_f32_e32 v9, v0, v8
	v_fma_f32 v14, -v5, v9, v0
	v_fmac_f32_e32 v9, v14, v8
	v_mul_f32_e32 v14, 0xbfb8aa3b, v15
	v_exp_f32_e32 v14, v14
	v_fma_f32 v0, -v5, v9, v0
	v_div_fmas_f32 v0, v0, v8, v9
	v_add_f32_e32 v8, 1.0, v14
	v_div_scale_f32 v5, s[0:1], v8, v8, 1.0
	v_rcp_f32_e32 v9, v5
	v_div_fixup_f32 v14, v0, v4, 1.0
	v_mul_f32_e32 v0, 0xbfb8aa3b, v73
	v_exp_f32_e32 v0, v0
	v_fma_f32 v4, -v5, v9, 1.0
	v_fmac_f32_e32 v9, v4, v9
	v_div_scale_f32 v4, vcc, 1.0, v8, 1.0
	v_mul_f32_e32 v15, v4, v9
	v_fma_f32 v72, -v5, v15, v4
	v_pk_add_f32 v[0:1], v[0:1], 1.0 op_sel_hi:[1,0]
	v_fmac_f32_e32 v15, v72, v9
	v_div_scale_f32 v72, s[0:1], v1, v1, 1.0
	v_rcp_f32_e32 v73, v72
	v_fma_f32 v4, -v5, v15, v4
	v_div_fmas_f32 v9, v4, v9, v15
	v_div_fixup_f32 v8, v9, v8, 1.0
	v_fma_f32 v4, -v72, v73, 1.0
	v_fmac_f32_e32 v73, v4, v73
	v_div_scale_f32 v4, vcc, 1.0, v1, 1.0
	v_mul_f32_e32 v5, v4, v73
	v_fma_f32 v15, -v72, v5, v4
	v_fmac_f32_e32 v5, v15, v73
	v_div_scale_f32 v15, s[0:1], v0, v0, 1.0
	v_fma_f32 v4, -v72, v5, v4
	v_rcp_f32_e32 v72, v15
	v_div_fmas_f32 v4, v4, v73, v5
	v_div_fixup_f32 v1, v4, v1, 1.0
	v_fma_f32 v4, -v15, v72, 1.0
	v_fmac_f32_e32 v72, v4, v72
	v_div_scale_f32 v4, vcc, 1.0, v0, 1.0
	v_mul_f32_e32 v5, v4, v72
	v_fma_f32 v73, -v15, v5, v4
	v_fmac_f32_e32 v5, v73, v72
	v_fma_f32 v4, -v15, v5, v4
	v_div_fmas_f32 v4, v4, v72, v5
	v_div_fixup_f32 v0, v4, v0, 1.0
	v_pk_mul_f32 v[0:1], v[0:1], s[44:45] op_sel_hi:[1,0]
	s_nop 0
	v_pk_mul_f32 v[0:1], v[18:19], v[0:1]
	s_nop 0
	v_pk_add_f32 v[4:5], v[0:1], v[0:1]
	v_mul_f32_e32 v1, 0x3fb8aa3b, v1
	v_mul_f32_e32 v15, 0x3fb8aa3b, v5
	v_rndne_f32_e32 v15, v15
	v_fmamk_f32 v72, v15, 0xbf317218, v5
	v_fmac_f32_e32 v72, 0x3102e308, v15
	v_fmamk_f32 v73, v72, 0x395133b1, v180
	v_fmaak_f32 v73, v72, v73, 0x3c0887f9
	v_fmaak_f32 v73, v72, v73, 0x3d2aaa81
	v_cvt_i32_f32_e32 v75, v15
	v_fmaak_f32 v73, v72, v73, 0x3e2aaaab
	v_fma_f32 v73, v72, v73, 0.5
	v_mul_f32_e32 v73, v72, v73
	v_fmac_f32_e32 v72, v72, v73
	v_ldexp_f32 v73, 1.0, v75
	v_cmp_eq_f32_e32 vcc, s34, v15
	v_exp_f32_e32 v1, v1
	v_mul_f32_e32 v0, 0x3fb8aa3b, v0
	v_cndmask_b32_e32 v15, v73, v197, vcc
	v_add_f32_e32 v73, -1.0, v15
	v_fmac_f32_e32 v73, v15, v72
	v_add_f32_e32 v15, v73, v73
	v_cndmask_b32_e32 v15, v73, v15, vcc
	v_cmp_nlt_f32_e32 vcc, s35, v5
	v_exp_f32_e32 v0, v0
	s_nop 0
	v_cndmask_b32_e64 v15, v190, -v15, vcc
	v_mul_f32_e32 v72, 0x4f800000, v15
	v_cmp_gt_f32_e32 vcc, s18, v15
	s_nop 1
	v_cndmask_b32_e32 v15, v15, v72, vcc
	v_sqrt_f32_e32 v72, v15
	s_nop 0
	v_add_u32_e32 v9, -1, v72
	v_fma_f32 v73, -v9, v72, v15
	v_cmp_ge_f32_e64 s[0:1], 0, v73
	v_add_u32_e32 v73, 1, v72
	s_nop 0
	v_cndmask_b32_e64 v9, v72, v9, s[0:1]
	v_fma_f32 v72, -v73, v72, v15
	v_cmp_lt_f32_e64 s[0:1], 0, v72
	s_nop 1
	v_cndmask_b32_e64 v9, v9, v73, s[0:1]
	v_mul_f32_e32 v72, 0x37800000, v9
	v_cndmask_b32_e32 v9, v9, v72, vcc
	v_cmp_class_f32_e32 vcc, v15, v181
	s_nop 1
	v_cndmask_b32_e32 v9, v9, v15, vcc
	v_cmp_ngt_f32_e32 vcc, s19, v5
	s_nop 1
	v_cndmask_b32_e32 v5, 1.0, v9, vcc
	v_mul_f32_e32 v5, v14, v5
	v_mul_f32_e32 v9, v5, v2
	v_mul_f32_e32 v2, 0x3fb8aa3b, v4
	v_rndne_f32_e32 v2, v2
	v_fmamk_f32 v5, v2, 0xbf317218, v4
	v_fmac_f32_e32 v5, 0x3102e308, v2
	v_fmamk_f32 v14, v5, 0x395133b1, v180
	v_fmaak_f32 v14, v5, v14, 0x3c0887f9
	v_fmaak_f32 v14, v5, v14, 0x3d2aaa81
	v_cvt_i32_f32_e32 v15, v2
	v_fmaak_f32 v14, v5, v14, 0x3e2aaaab
	v_fma_f32 v14, v5, v14, 0.5
	v_mul_f32_e32 v14, v5, v14
	v_fmac_f32_e32 v5, v5, v14
	v_ldexp_f32 v14, 1.0, v15
	v_cmp_eq_f32_e32 vcc, s34, v2
	v_fmac_f32_e32 v9, v1, v74
	s_nop 0
	v_cndmask_b32_e32 v2, v14, v197, vcc
	v_add_f32_e32 v14, -1.0, v2
	v_fmac_f32_e32 v14, v2, v5
	v_add_f32_e32 v2, v14, v14
	v_cndmask_b32_e32 v2, v14, v2, vcc
	v_cmp_nlt_f32_e32 vcc, s35, v4
	v_mul_f32_e32 v14, v1, v76
	v_mul_f32_e32 v72, v0, v14
	v_cndmask_b32_e64 v2, v190, -v2, vcc
	v_mul_f32_e32 v5, 0x4f800000, v2
	v_cmp_gt_f32_e32 vcc, s18, v2
	s_nop 1
	v_cndmask_b32_e32 v2, v2, v5, vcc
	v_sqrt_f32_e32 v5, v2
	s_nop 0
	v_add_u32_e32 v1, -1, v5
	v_fma_f32 v15, -v1, v5, v2
	v_cmp_ge_f32_e64 s[0:1], 0, v15
	v_add_u32_e32 v15, 1, v5
	s_nop 0
	v_cndmask_b32_e64 v1, v5, v1, s[0:1]
	v_fma_f32 v5, -v15, v5, v2
	v_cmp_lt_f32_e64 s[0:1], 0, v5
	s_nop 1
	v_cndmask_b32_e64 v1, v1, v15, s[0:1]
	v_mul_f32_e32 v5, 0x37800000, v1
	v_cndmask_b32_e32 v1, v1, v5, vcc
	v_cmp_class_f32_e32 vcc, v2, v181
	s_nop 1
	v_cndmask_b32_e32 v1, v1, v2, vcc
	v_cmp_ngt_f32_e32 vcc, s19, v4
	s_nop 1
	v_cndmask_b32_e32 v1, 1.0, v1, vcc
	v_mul_f32_e32 v1, v8, v1
	v_mul_f32_e32 v15, v1, v3
	v_fmac_f32_e32 v15, v0, v9
	v_ashrrev_i32_e32 v1, 31, v7
	v_mov_b32_e32 v0, v7
	v_ashrrev_i32_e32 v7, 31, v6
	v_lshlrev_b64 v[2:3], 9, v[6:7]
	v_lshl_add_u64 v[2:3], v[2:3], 0, v[24:25]
	v_lshlrev_b64 v[2:3], 2, v[2:3]
	v_lshl_add_u64 v[4:5], s[14:15], 0, v[2:3]
	v_lshl_add_u64 v[2:3], s[16:17], 0, v[2:3]
	global_store_dword v[4:5], v14, off
	global_store_dword v[2:3], v9, off
	v_mul_f32_e32 v2, 0xbfb8aa3b, v10
	v_lshlrev_b64 v[0:1], 9, v[0:1]
	v_exp_f32_e32 v4, v2
	v_lshl_add_u64 v[0:1], v[0:1], 0, v[26:27]
	v_lshlrev_b64 v[0:1], 2, v[0:1]
	v_lshl_add_u64 v[2:3], s[14:15], 0, v[0:1]
	global_store_dword v[2:3], v72, off
	v_add_f32_e32 v2, 1.0, v4
	v_div_scale_f32 v3, s[0:1], v2, v2, 1.0
	v_rcp_f32_e32 v4, v3
	v_lshl_add_u64 v[0:1], s[16:17], 0, v[0:1]
	global_store_dword v[0:1], v15, off
	v_mul_f32_e32 v0, 0xbfb8aa3b, v12
	v_exp_f32_e32 v5, v0
	v_fma_f32 v0, -v3, v4, 1.0
	v_fmac_f32_e32 v4, v0, v4
	v_div_scale_f32 v0, vcc, 1.0, v2, 1.0
	v_mul_f32_e32 v1, v0, v4
	v_fma_f32 v6, -v3, v1, v0
	v_fmac_f32_e32 v1, v6, v4
	v_fma_f32 v0, -v3, v1, v0
	v_mul_f32_e32 v3, 0xbfb8aa3b, v11
	v_exp_f32_e32 v3, v3
	v_div_fmas_f32 v0, v0, v4, v1
	v_mul_f32_e32 v4, 0xbfb8aa3b, v13
	v_exp_f32_e32 v4, v4
	v_add_f32_e32 v7, 1.0, v3
	v_div_scale_f32 v8, s[0:1], v7, v7, 1.0
	v_rcp_f32_e32 v9, v8
	v_pk_add_f32 v[4:5], v[4:5], 1.0 op_sel_hi:[1,0]
	v_div_fixup_f32 v6, v0, v2, 1.0
	ds_read_b128 v[0:3], v87 offset:32
	v_fma_f32 v10, -v8, v9, 1.0
	v_fmac_f32_e32 v9, v10, v9
	v_div_scale_f32 v10, vcc, 1.0, v7, 1.0
	v_mul_f32_e32 v11, v10, v9
	v_fma_f32 v12, -v8, v11, v10
	v_fmac_f32_e32 v11, v12, v9
	v_div_scale_f32 v12, s[0:1], v5, v5, 1.0
	v_rcp_f32_e32 v13, v12
	v_fma_f32 v8, -v8, v11, v10
	v_div_fmas_f32 v14, v8, v9, v11
	v_fma_f32 v8, -v12, v13, 1.0
	v_fmac_f32_e32 v13, v8, v13
	v_div_scale_f32 v8, vcc, 1.0, v5, 1.0
	v_mul_f32_e32 v9, v8, v13
	v_fma_f32 v10, -v12, v9, v8
	v_fmac_f32_e32 v9, v10, v13
	v_div_scale_f32 v10, s[0:1], v4, v4, 1.0
	v_rcp_f32_e32 v11, v10
	v_fma_f32 v8, -v12, v9, v8
	v_div_fmas_f32 v8, v8, v13, v9
	v_div_fixup_f32 v5, v8, v5, 1.0
	v_fma_f32 v8, -v10, v11, 1.0
	v_fmac_f32_e32 v11, v8, v11
	v_div_scale_f32 v8, vcc, 1.0, v4, 1.0
	v_mul_f32_e32 v9, v8, v11
	v_fma_f32 v12, -v10, v9, v8
	v_fmac_f32_e32 v9, v12, v11
	v_fma_f32 v8, -v10, v9, v8
	v_div_fmas_f32 v8, v8, v11, v9
	v_div_fixup_f32 v4, v8, v4, 1.0
	v_pk_mul_f32 v[4:5], v[4:5], s[44:45] op_sel_hi:[1,0]
	s_nop 0
	v_pk_mul_f32 v[10:11], v[18:19], v[4:5]
	s_nop 0
	v_pk_add_f32 v[8:9], v[10:11], v[10:11]
	v_mul_f32_e32 v10, 0x3fb8aa3b, v10
	v_mul_f32_e32 v4, 0x3fb8aa3b, v9
	v_rndne_f32_e32 v4, v4
	v_fmamk_f32 v5, v4, 0xbf317218, v9
	v_fmac_f32_e32 v5, 0x3102e308, v4
	v_fmamk_f32 v12, v5, 0x395133b1, v180
	v_fmaak_f32 v12, v5, v12, 0x3c0887f9
	v_fmaak_f32 v12, v5, v12, 0x3d2aaa81
	v_cvt_i32_f32_e32 v13, v4
	v_fmaak_f32 v12, v5, v12, 0x3e2aaaab
	v_fma_f32 v12, v5, v12, 0.5
	v_mul_f32_e32 v12, v5, v12
	v_fmac_f32_e32 v5, v5, v12
	v_ldexp_f32 v12, 1.0, v13
	v_cmp_eq_f32_e32 vcc, s34, v4
	v_exp_f32_e32 v10, v10
	s_nop 0
	v_cndmask_b32_e32 v4, v12, v197, vcc
	v_add_f32_e32 v12, -1.0, v4
	v_fmac_f32_e32 v12, v4, v5
	v_add_f32_e32 v4, v12, v12
	v_cndmask_b32_e32 v4, v12, v4, vcc
	v_cmp_nlt_f32_e32 vcc, s35, v9
	v_div_fixup_f32 v12, v14, v7, 1.0
	v_mul_f32_e32 v7, 0x3fb8aa3b, v11
	v_cndmask_b32_e64 v4, v190, -v4, vcc
	v_mul_f32_e32 v5, 0x4f800000, v4
	v_cmp_gt_f32_e32 vcc, s18, v4
	v_exp_f32_e32 v11, v7
	s_nop 0
	v_cndmask_b32_e32 v4, v4, v5, vcc
	v_sqrt_f32_e32 v5, v4
	v_mul_f32_e32 v75, v11, v72
	v_mul_f32_e32 v77, v10, v75
	v_add_u32_e32 v7, -1, v5
	v_fma_f32 v13, -v7, v5, v4
	v_cmp_ge_f32_e64 s[0:1], 0, v13
	v_add_u32_e32 v13, 1, v5
	s_nop 0
	v_cndmask_b32_e64 v7, v5, v7, s[0:1]
	v_fma_f32 v5, -v13, v5, v4
	v_cmp_lt_f32_e64 s[0:1], 0, v5
	s_nop 1
	v_cndmask_b32_e64 v5, v7, v13, s[0:1]
	v_mul_f32_e32 v7, 0x37800000, v5
	v_cndmask_b32_e32 v5, v5, v7, vcc
	v_cmp_class_f32_e32 vcc, v4, v181
	s_nop 1
	v_cndmask_b32_e32 v4, v5, v4, vcc
	v_cmp_ngt_f32_e32 vcc, s19, v9
	s_nop 1
	v_cndmask_b32_e32 v4, 1.0, v4, vcc
	v_mul_f32_e32 v9, v6, v4
	ds_read_b128 v[4:7], v87 offset:48
	s_waitcnt lgkmcnt(1)
	v_mul_f32_e32 v74, v9, v0
	v_mul_f32_e32 v0, 0x3fb8aa3b, v8
	v_rndne_f32_e32 v0, v0
	v_fmamk_f32 v9, v0, 0xbf317218, v8
	v_fmac_f32_e32 v9, 0x3102e308, v0
	v_fmamk_f32 v13, v9, 0x395133b1, v180
	v_fmaak_f32 v13, v9, v13, 0x3c0887f9
	v_fmaak_f32 v13, v9, v13, 0x3d2aaa81
	v_cvt_i32_f32_e32 v14, v0
	v_fmaak_f32 v13, v9, v13, 0x3e2aaaab
	v_fma_f32 v13, v9, v13, 0.5
	v_mul_f32_e32 v13, v9, v13
	v_fmac_f32_e32 v9, v9, v13
	v_ldexp_f32 v13, 1.0, v14
	v_cmp_eq_f32_e32 vcc, s34, v0
	v_fmac_f32_e32 v74, v11, v15
	s_nop 0
	v_cndmask_b32_e32 v0, v13, v197, vcc
	v_add_f32_e32 v13, -1.0, v0
	v_fmac_f32_e32 v13, v0, v9
	v_add_f32_e32 v0, v13, v13
	v_cndmask_b32_e32 v0, v13, v0, vcc
	v_cmp_nlt_f32_e32 vcc, s35, v8
	s_nop 1
	v_cndmask_b32_e64 v0, v190, -v0, vcc
	v_mul_f32_e32 v9, 0x4f800000, v0
	v_cmp_gt_f32_e32 vcc, s18, v0
	s_nop 1
	v_cndmask_b32_e32 v0, v0, v9, vcc
	v_sqrt_f32_e32 v9, v0
	s_nop 0
	v_add_u32_e32 v11, -1, v9
	v_fma_f32 v13, -v11, v9, v0
	v_cmp_ge_f32_e64 s[0:1], 0, v13
	v_add_u32_e32 v13, 1, v9
	s_nop 0
	v_cndmask_b32_e64 v11, v9, v11, s[0:1]
	v_fma_f32 v9, -v13, v9, v0
	v_cmp_lt_f32_e64 s[0:1], 0, v9
	s_nop 1
	v_cndmask_b32_e64 v9, v11, v13, s[0:1]
	v_mul_f32_e32 v11, 0x37800000, v9
	v_cndmask_b32_e32 v9, v9, v11, vcc
	v_cmp_class_f32_e32 vcc, v0, v181
	s_nop 1
	v_cndmask_b32_e32 v0, v9, v0, vcc
	v_cmp_ngt_f32_e32 vcc, s19, v8
	s_nop 1
	v_cndmask_b32_e32 v0, 1.0, v0, vcc
	v_mul_f32_e32 v0, v12, v0
	ds_read_b128 v[12:15], v82 offset:32
	v_mul_f32_e32 v76, v0, v1
	v_fmac_f32_e32 v76, v10, v74
	ds_read_b128 v[8:11], v82 offset:48
	s_waitcnt lgkmcnt(1)
	v_ashrrev_i32_e32 v1, 31, v13
	v_mov_b32_e32 v0, v13
	v_ashrrev_i32_e32 v13, 31, v12
	v_lshlrev_b64 v[12:13], 9, v[12:13]
	v_lshl_add_u64 v[12:13], v[12:13], 0, v[24:25]
	v_lshlrev_b64 v[12:13], 2, v[12:13]
	v_lshl_add_u64 v[72:73], s[14:15], 0, v[12:13]
	v_lshl_add_u64 v[12:13], s[16:17], 0, v[12:13]
	global_store_dword v[72:73], v75, off
	global_store_dword v[12:13], v74, off
	v_mul_f32_e32 v12, 0xbfb8aa3b, v68
	v_lshlrev_b64 v[0:1], 9, v[0:1]
	v_exp_f32_e32 v68, v12
	v_lshl_add_u64 v[0:1], v[0:1], 0, v[26:27]
	v_lshlrev_b64 v[0:1], 2, v[0:1]
	v_lshl_add_u64 v[12:13], s[14:15], 0, v[0:1]
	global_store_dword v[12:13], v77, off
	v_add_f32_e32 v12, 1.0, v68
	v_div_scale_f32 v13, s[0:1], v12, v12, 1.0
	v_rcp_f32_e32 v68, v13
	v_lshl_add_u64 v[0:1], s[16:17], 0, v[0:1]
	global_store_dword v[0:1], v76, off
	v_mul_f32_e32 v0, 0xbfb8aa3b, v70
	v_exp_f32_e32 v1, v0
	v_fma_f32 v0, -v13, v68, 1.0
	v_fmac_f32_e32 v68, v0, v68
	v_div_scale_f32 v0, vcc, 1.0, v12, 1.0
	v_mul_f32_e32 v70, v0, v68
	v_fma_f32 v72, -v13, v70, v0
	v_fmac_f32_e32 v70, v72, v68
	v_fma_f32 v0, -v13, v70, v0
	v_div_fmas_f32 v0, v0, v68, v70
	v_add_f32_e32 v68, 1.0, v69
	v_div_scale_f32 v13, s[0:1], v68, v68, 1.0
	v_rcp_f32_e32 v69, v13
	v_div_fixup_f32 v70, v0, v12, 1.0
	v_mul_f32_e32 v0, 0xbfb8aa3b, v71
	v_exp_f32_e32 v0, v0
	v_fma_f32 v12, -v13, v69, 1.0
	v_fmac_f32_e32 v69, v12, v69
	v_div_scale_f32 v12, vcc, 1.0, v68, 1.0
	v_mul_f32_e32 v71, v12, v69
	v_fma_f32 v72, -v13, v71, v12
	v_pk_add_f32 v[0:1], v[0:1], 1.0 op_sel_hi:[1,0]
	v_fmac_f32_e32 v71, v72, v69
	v_div_scale_f32 v72, s[0:1], v1, v1, 1.0
	v_rcp_f32_e32 v73, v72
	v_fma_f32 v12, -v13, v71, v12
	v_div_fmas_f32 v69, v12, v69, v71
	v_div_fixup_f32 v68, v69, v68, 1.0
	v_fma_f32 v12, -v72, v73, 1.0
	v_fmac_f32_e32 v73, v12, v73
	v_div_scale_f32 v12, vcc, 1.0, v1, 1.0
	v_mul_f32_e32 v13, v12, v73
	v_fma_f32 v71, -v72, v13, v12
	v_fmac_f32_e32 v13, v71, v73
	v_div_scale_f32 v71, s[0:1], v0, v0, 1.0
	v_fma_f32 v12, -v72, v13, v12
	v_rcp_f32_e32 v72, v71
	v_div_fmas_f32 v12, v12, v73, v13
	v_div_fixup_f32 v1, v12, v1, 1.0
	v_fma_f32 v12, -v71, v72, 1.0
	v_fmac_f32_e32 v72, v12, v72
	v_div_scale_f32 v12, vcc, 1.0, v0, 1.0
	v_mul_f32_e32 v13, v12, v72
	v_fma_f32 v73, -v71, v13, v12
	v_fmac_f32_e32 v13, v73, v72
	v_fma_f32 v12, -v71, v13, v12
	v_div_fmas_f32 v12, v12, v72, v13
	v_div_fixup_f32 v0, v12, v0, 1.0
	v_pk_mul_f32 v[0:1], v[0:1], s[44:45] op_sel_hi:[1,0]
	s_nop 0
	v_pk_mul_f32 v[0:1], v[18:19], v[0:1]
	s_nop 0
	v_pk_add_f32 v[12:13], v[0:1], v[0:1]
	v_mul_f32_e32 v1, 0x3fb8aa3b, v1
	v_mul_f32_e32 v71, 0x3fb8aa3b, v13
	v_rndne_f32_e32 v71, v71
	v_fmamk_f32 v72, v71, 0xbf317218, v13
	v_fmac_f32_e32 v72, 0x3102e308, v71
	v_fmamk_f32 v73, v72, 0x395133b1, v180
	v_fmaak_f32 v73, v72, v73, 0x3c0887f9
	v_fmaak_f32 v73, v72, v73, 0x3d2aaa81
	v_cvt_i32_f32_e32 v74, v71
	v_fmaak_f32 v73, v72, v73, 0x3e2aaaab
	v_fma_f32 v73, v72, v73, 0.5
	v_mul_f32_e32 v73, v72, v73
	v_fmac_f32_e32 v72, v72, v73
	v_ldexp_f32 v73, 1.0, v74
	v_cmp_eq_f32_e32 vcc, s34, v71
	v_exp_f32_e32 v1, v1
	v_mul_f32_e32 v0, 0x3fb8aa3b, v0
	v_cndmask_b32_e32 v71, v73, v197, vcc
	v_add_f32_e32 v73, -1.0, v71
	v_fmac_f32_e32 v73, v71, v72
	v_add_f32_e32 v71, v73, v73
	v_cndmask_b32_e32 v71, v73, v71, vcc
	v_cmp_nlt_f32_e32 vcc, s35, v13
	v_exp_f32_e32 v0, v0
	s_nop 0
	v_cndmask_b32_e64 v71, v190, -v71, vcc
	v_mul_f32_e32 v72, 0x4f800000, v71
	v_cmp_gt_f32_e32 vcc, s18, v71
	s_nop 1
	v_cndmask_b32_e32 v71, v71, v72, vcc
	v_sqrt_f32_e32 v72, v71
	s_nop 0
	v_add_u32_e32 v69, -1, v72
	v_fma_f32 v73, -v69, v72, v71
	v_cmp_ge_f32_e64 s[0:1], 0, v73
	v_add_u32_e32 v73, 1, v72
	s_nop 0
	v_cndmask_b32_e64 v69, v72, v69, s[0:1]
	v_fma_f32 v72, -v73, v72, v71
	v_cmp_lt_f32_e64 s[0:1], 0, v72
	s_nop 1
	v_cndmask_b32_e64 v69, v69, v73, s[0:1]
	v_mul_f32_e32 v72, 0x37800000, v69
	v_cndmask_b32_e32 v69, v69, v72, vcc
	v_cmp_class_f32_e32 vcc, v71, v181
	s_nop 1
	v_cndmask_b32_e32 v69, v69, v71, vcc
	v_cmp_ngt_f32_e32 vcc, s19, v13
	s_nop 1
	v_cndmask_b32_e32 v13, 1.0, v69, vcc
	v_mul_f32_e32 v13, v70, v13
	v_mul_f32_e32 v69, v13, v2
	v_mul_f32_e32 v2, 0x3fb8aa3b, v12
	v_rndne_f32_e32 v2, v2
	v_fmamk_f32 v13, v2, 0xbf317218, v12
	v_fmac_f32_e32 v13, 0x3102e308, v2
	v_fmamk_f32 v70, v13, 0x395133b1, v180
	v_fmaak_f32 v70, v13, v70, 0x3c0887f9
	v_fmaak_f32 v70, v13, v70, 0x3d2aaa81
	v_cvt_i32_f32_e32 v71, v2
	v_fmaak_f32 v70, v13, v70, 0x3e2aaaab
	v_fma_f32 v70, v13, v70, 0.5
	v_mul_f32_e32 v70, v13, v70
	v_fmac_f32_e32 v13, v13, v70
	v_ldexp_f32 v70, 1.0, v71
	v_cmp_eq_f32_e32 vcc, s34, v2
	v_fmac_f32_e32 v69, v1, v76
	s_nop 0
	v_cndmask_b32_e32 v2, v70, v197, vcc
	v_add_f32_e32 v70, -1.0, v2
	v_fmac_f32_e32 v70, v2, v13
	v_add_f32_e32 v2, v70, v70
	v_cndmask_b32_e32 v2, v70, v2, vcc
	v_cmp_nlt_f32_e32 vcc, s35, v12
	v_mul_f32_e32 v70, v1, v77
	s_nop 0
	v_cndmask_b32_e64 v2, v190, -v2, vcc
	v_mul_f32_e32 v13, 0x4f800000, v2
	v_cmp_gt_f32_e32 vcc, s18, v2
	s_nop 1
	v_cndmask_b32_e32 v2, v2, v13, vcc
	v_sqrt_f32_e32 v13, v2
	s_nop 0
	v_add_u32_e32 v1, -1, v13
	v_fma_f32 v71, -v1, v13, v2
	v_cmp_ge_f32_e64 s[0:1], 0, v71
	v_add_u32_e32 v71, 1, v13
	s_nop 0
	v_cndmask_b32_e64 v1, v13, v1, s[0:1]
	v_fma_f32 v13, -v71, v13, v2
	v_cmp_lt_f32_e64 s[0:1], 0, v13
	s_nop 1
	v_cndmask_b32_e64 v1, v1, v71, s[0:1]
	v_mul_f32_e32 v13, 0x37800000, v1
	v_cndmask_b32_e32 v1, v1, v13, vcc
	v_cmp_class_f32_e32 vcc, v2, v181
	v_mul_f32_e32 v71, v0, v70
	s_nop 0
	v_cndmask_b32_e32 v1, v1, v2, vcc
	v_cmp_ngt_f32_e32 vcc, s19, v12
	s_nop 1
	v_cndmask_b32_e32 v1, 1.0, v1, vcc
	v_mul_f32_e32 v1, v68, v1
	v_mul_f32_e32 v68, v1, v3
	v_fmac_f32_e32 v68, v0, v69
	v_ashrrev_i32_e32 v1, 31, v15
	v_mov_b32_e32 v0, v15
	v_ashrrev_i32_e32 v15, 31, v14
	v_lshlrev_b64 v[2:3], 9, v[14:15]
	v_lshl_add_u64 v[2:3], v[2:3], 0, v[24:25]
	v_lshlrev_b64 v[2:3], 2, v[2:3]
	v_lshl_add_u64 v[12:13], s[14:15], 0, v[2:3]
	v_lshl_add_u64 v[2:3], s[16:17], 0, v[2:3]
	global_store_dword v[12:13], v70, off
	global_store_dword v[2:3], v69, off
	v_mul_f32_e32 v2, 0xbfb8aa3b, v64
	v_lshlrev_b64 v[0:1], 9, v[0:1]
	v_exp_f32_e32 v12, v2
	v_lshl_add_u64 v[0:1], v[0:1], 0, v[26:27]
	v_lshlrev_b64 v[0:1], 2, v[0:1]
	v_lshl_add_u64 v[2:3], s[14:15], 0, v[0:1]
	global_store_dword v[2:3], v71, off
	v_add_f32_e32 v2, 1.0, v12
	v_div_scale_f32 v3, s[0:1], v2, v2, 1.0
	v_rcp_f32_e32 v12, v3
	v_lshl_add_u64 v[0:1], s[16:17], 0, v[0:1]
	global_store_dword v[0:1], v68, off
	v_mul_f32_e32 v0, 0xbfb8aa3b, v66
	v_exp_f32_e32 v1, v0
	v_fma_f32 v0, -v3, v12, 1.0
	v_fmac_f32_e32 v12, v0, v12
	v_div_scale_f32 v0, vcc, 1.0, v2, 1.0
	v_mul_f32_e32 v13, v0, v12
	v_fma_f32 v14, -v3, v13, v0
	v_fmac_f32_e32 v13, v14, v12
	v_mul_f32_e32 v14, 0xbfb8aa3b, v65
	v_exp_f32_e32 v14, v14
	v_fma_f32 v0, -v3, v13, v0
	v_div_fmas_f32 v0, v0, v12, v13
	v_add_f32_e32 v12, 1.0, v14
	v_div_scale_f32 v3, s[0:1], v12, v12, 1.0
	v_rcp_f32_e32 v13, v3
	v_div_fixup_f32 v14, v0, v2, 1.0
	v_mul_f32_e32 v0, 0xbfb8aa3b, v67
	v_exp_f32_e32 v0, v0
	v_fma_f32 v2, -v3, v13, 1.0
	v_fmac_f32_e32 v13, v2, v13
	v_div_scale_f32 v2, vcc, 1.0, v12, 1.0
	v_mul_f32_e32 v15, v2, v13
	v_fma_f32 v64, -v3, v15, v2
	v_pk_add_f32 v[0:1], v[0:1], 1.0 op_sel_hi:[1,0]
	v_fmac_f32_e32 v15, v64, v13
	v_div_scale_f32 v64, s[0:1], v1, v1, 1.0
	v_rcp_f32_e32 v65, v64
	v_fma_f32 v2, -v3, v15, v2
	v_div_fmas_f32 v13, v2, v13, v15
	v_div_fixup_f32 v12, v13, v12, 1.0
	v_fma_f32 v2, -v64, v65, 1.0
	v_fmac_f32_e32 v65, v2, v65
	v_div_scale_f32 v2, vcc, 1.0, v1, 1.0
	v_mul_f32_e32 v3, v2, v65
	v_fma_f32 v15, -v64, v3, v2
	v_fmac_f32_e32 v3, v15, v65
	v_div_scale_f32 v15, s[0:1], v0, v0, 1.0
	v_fma_f32 v2, -v64, v3, v2
	v_rcp_f32_e32 v64, v15
	v_div_fmas_f32 v2, v2, v65, v3
	v_div_fixup_f32 v1, v2, v1, 1.0
	v_fma_f32 v2, -v15, v64, 1.0
	v_fmac_f32_e32 v64, v2, v64
	v_div_scale_f32 v2, vcc, 1.0, v0, 1.0
	v_mul_f32_e32 v3, v2, v64
	v_fma_f32 v65, -v15, v3, v2
	v_fmac_f32_e32 v3, v65, v64
	v_fma_f32 v2, -v15, v3, v2
	v_div_fmas_f32 v2, v2, v64, v3
	v_div_fixup_f32 v0, v2, v0, 1.0
	v_pk_mul_f32 v[0:1], v[0:1], s[44:45] op_sel_hi:[1,0]
	s_nop 0
	v_pk_mul_f32 v[0:1], v[18:19], v[0:1]
	s_nop 0
	v_pk_add_f32 v[2:3], v[0:1], v[0:1]
	v_mul_f32_e32 v1, 0x3fb8aa3b, v1
	v_mul_f32_e32 v15, 0x3fb8aa3b, v3
	v_rndne_f32_e32 v15, v15
	v_fmamk_f32 v64, v15, 0xbf317218, v3
	v_fmac_f32_e32 v64, 0x3102e308, v15
	v_fmamk_f32 v65, v64, 0x395133b1, v180
	v_fmaak_f32 v65, v64, v65, 0x3c0887f9
	v_fmaak_f32 v65, v64, v65, 0x3d2aaa81
	v_cvt_i32_f32_e32 v66, v15
	v_fmaak_f32 v65, v64, v65, 0x3e2aaaab
	v_fma_f32 v65, v64, v65, 0.5
	v_mul_f32_e32 v65, v64, v65
	v_fmac_f32_e32 v64, v64, v65
	v_ldexp_f32 v65, 1.0, v66
	v_cmp_eq_f32_e32 vcc, s34, v15
	v_exp_f32_e32 v1, v1
	v_mul_f32_e32 v0, 0x3fb8aa3b, v0
	v_cndmask_b32_e32 v15, v65, v197, vcc
	v_add_f32_e32 v65, -1.0, v15
	v_fmac_f32_e32 v65, v15, v64
	v_add_f32_e32 v15, v65, v65
	v_cndmask_b32_e32 v15, v65, v15, vcc
	v_cmp_nlt_f32_e32 vcc, s35, v3
	v_exp_f32_e32 v0, v0
	s_nop 0
	v_cndmask_b32_e64 v15, v190, -v15, vcc
	v_mul_f32_e32 v64, 0x4f800000, v15
	v_cmp_gt_f32_e32 vcc, s18, v15
	s_nop 1
	v_cndmask_b32_e32 v15, v15, v64, vcc
	v_sqrt_f32_e32 v64, v15
	s_nop 0
	v_add_u32_e32 v13, -1, v64
	v_fma_f32 v65, -v13, v64, v15
	v_cmp_ge_f32_e64 s[0:1], 0, v65
	v_add_u32_e32 v65, 1, v64
	s_nop 0
	v_cndmask_b32_e64 v13, v64, v13, s[0:1]
	v_fma_f32 v64, -v65, v64, v15
	v_cmp_lt_f32_e64 s[0:1], 0, v64
	s_nop 1
	v_cndmask_b32_e64 v13, v13, v65, s[0:1]
	v_mul_f32_e32 v64, 0x37800000, v13
	v_cndmask_b32_e32 v13, v13, v64, vcc
	v_cmp_class_f32_e32 vcc, v15, v181
	s_nop 1
	v_cndmask_b32_e32 v13, v13, v15, vcc
	v_cmp_ngt_f32_e32 vcc, s19, v3
	s_nop 1
	v_cndmask_b32_e32 v3, 1.0, v13, vcc
	v_mul_f32_e32 v3, v14, v3
	v_mul_f32_e32 v13, v3, v4
	v_mul_f32_e32 v3, 0x3fb8aa3b, v2
	v_rndne_f32_e32 v3, v3
	v_fmamk_f32 v4, v3, 0xbf317218, v2
	v_fmac_f32_e32 v4, 0x3102e308, v3
	v_fmamk_f32 v14, v4, 0x395133b1, v180
	v_fmaak_f32 v14, v4, v14, 0x3c0887f9
	v_fmaak_f32 v14, v4, v14, 0x3d2aaa81
	v_cvt_i32_f32_e32 v15, v3
	v_fmaak_f32 v14, v4, v14, 0x3e2aaaab
	v_fma_f32 v14, v4, v14, 0.5
	v_mul_f32_e32 v14, v4, v14
	v_fmac_f32_e32 v4, v4, v14
	v_ldexp_f32 v14, 1.0, v15
	v_cmp_eq_f32_e32 vcc, s34, v3
	v_fmac_f32_e32 v13, v1, v68
	s_nop 0
	v_cndmask_b32_e32 v3, v14, v197, vcc
	v_add_f32_e32 v14, -1.0, v3
	v_fmac_f32_e32 v14, v3, v4
	v_add_f32_e32 v3, v14, v14
	v_cndmask_b32_e32 v3, v14, v3, vcc
	v_cmp_nlt_f32_e32 vcc, s35, v2
	v_mul_f32_e32 v14, v1, v71
	s_nop 0
	v_cndmask_b32_e64 v3, v190, -v3, vcc
	v_mul_f32_e32 v4, 0x4f800000, v3
	v_cmp_gt_f32_e32 vcc, s18, v3
	s_nop 1
	v_cndmask_b32_e32 v3, v3, v4, vcc
	v_sqrt_f32_e32 v4, v3
	s_nop 0
	v_add_u32_e32 v1, -1, v4
	v_fma_f32 v15, -v1, v4, v3
	v_cmp_ge_f32_e64 s[0:1], 0, v15
	v_add_u32_e32 v15, 1, v4
	s_nop 0
	v_cndmask_b32_e64 v1, v4, v1, s[0:1]
	v_fma_f32 v4, -v15, v4, v3
	v_cmp_lt_f32_e64 s[0:1], 0, v4
	s_nop 1
	v_cndmask_b32_e64 v1, v1, v15, s[0:1]
	v_mul_f32_e32 v4, 0x37800000, v1
	v_cndmask_b32_e32 v1, v1, v4, vcc
	v_cmp_class_f32_e32 vcc, v3, v181
	v_mul_f32_e32 v15, v0, v14
	s_nop 0
	v_cndmask_b32_e32 v1, v1, v3, vcc
	v_cmp_ngt_f32_e32 vcc, s19, v2
	s_nop 1
	v_cndmask_b32_e32 v1, 1.0, v1, vcc
	v_mul_f32_e32 v1, v12, v1
	v_mul_f32_e32 v12, v1, v5
	v_fmac_f32_e32 v12, v0, v13
	s_waitcnt lgkmcnt(0)
	v_ashrrev_i32_e32 v1, 31, v9
	v_mov_b32_e32 v0, v9
	v_ashrrev_i32_e32 v9, 31, v8
	v_lshlrev_b64 v[2:3], 9, v[8:9]
	v_lshl_add_u64 v[2:3], v[2:3], 0, v[24:25]
	v_lshlrev_b64 v[2:3], 2, v[2:3]
	v_lshl_add_u64 v[4:5], s[14:15], 0, v[2:3]
	v_lshl_add_u64 v[2:3], s[16:17], 0, v[2:3]
	global_store_dword v[4:5], v14, off
	global_store_dword v[2:3], v13, off
	v_mul_f32_e32 v2, 0xbfb8aa3b, v60
	v_lshlrev_b64 v[0:1], 9, v[0:1]
	v_exp_f32_e32 v4, v2
	v_lshl_add_u64 v[0:1], v[0:1], 0, v[26:27]
	v_lshlrev_b64 v[0:1], 2, v[0:1]
	v_lshl_add_u64 v[2:3], s[14:15], 0, v[0:1]
	global_store_dword v[2:3], v15, off
	v_add_f32_e32 v2, 1.0, v4
	v_div_scale_f32 v3, s[0:1], v2, v2, 1.0
	v_rcp_f32_e32 v4, v3
	v_lshl_add_u64 v[0:1], s[16:17], 0, v[0:1]
	global_store_dword v[0:1], v12, off
	v_mul_f32_e32 v0, 0xbfb8aa3b, v62
	v_exp_f32_e32 v1, v0
	v_fma_f32 v0, -v3, v4, 1.0
	v_fmac_f32_e32 v4, v0, v4
	v_div_scale_f32 v0, vcc, 1.0, v2, 1.0
	v_mul_f32_e32 v5, v0, v4
	v_fma_f32 v8, -v3, v5, v0
	v_fmac_f32_e32 v5, v8, v4
	v_mul_f32_e32 v8, 0xbfb8aa3b, v61
	v_exp_f32_e32 v8, v8
	v_fma_f32 v0, -v3, v5, v0
	v_div_fmas_f32 v0, v0, v4, v5
	v_add_f32_e32 v4, 1.0, v8
	v_div_scale_f32 v3, s[0:1], v4, v4, 1.0
	v_rcp_f32_e32 v5, v3
	v_div_fixup_f32 v8, v0, v2, 1.0
	v_mul_f32_e32 v0, 0xbfb8aa3b, v63
	v_exp_f32_e32 v0, v0
	v_fma_f32 v2, -v3, v5, 1.0
	v_fmac_f32_e32 v5, v2, v5
	v_div_scale_f32 v2, vcc, 1.0, v4, 1.0
	v_mul_f32_e32 v9, v2, v5
	v_fma_f32 v13, -v3, v9, v2
	v_pk_add_f32 v[0:1], v[0:1], 1.0 op_sel_hi:[1,0]
	v_fmac_f32_e32 v9, v13, v5
	v_div_scale_f32 v13, s[0:1], v1, v1, 1.0
	v_rcp_f32_e32 v14, v13
	v_fma_f32 v2, -v3, v9, v2
	v_div_fmas_f32 v5, v2, v5, v9
	v_div_fixup_f32 v4, v5, v4, 1.0
	v_fma_f32 v2, -v13, v14, 1.0
	v_fmac_f32_e32 v14, v2, v14
	v_div_scale_f32 v2, vcc, 1.0, v1, 1.0
	v_mul_f32_e32 v3, v2, v14
	v_fma_f32 v9, -v13, v3, v2
	v_fmac_f32_e32 v3, v9, v14
	v_div_scale_f32 v9, s[0:1], v0, v0, 1.0
	v_fma_f32 v2, -v13, v3, v2
	v_rcp_f32_e32 v13, v9
	v_div_fmas_f32 v2, v2, v14, v3
	v_div_fixup_f32 v1, v2, v1, 1.0
	v_fma_f32 v2, -v9, v13, 1.0
	v_fmac_f32_e32 v13, v2, v13
	v_div_scale_f32 v2, vcc, 1.0, v0, 1.0
	v_mul_f32_e32 v3, v2, v13
	v_fma_f32 v14, -v9, v3, v2
	v_fmac_f32_e32 v3, v14, v13
	v_fma_f32 v2, -v9, v3, v2
	v_div_fmas_f32 v2, v2, v13, v3
	v_div_fixup_f32 v0, v2, v0, 1.0
	v_pk_mul_f32 v[0:1], v[0:1], s[44:45] op_sel_hi:[1,0]
	s_nop 0
	v_pk_mul_f32 v[0:1], v[18:19], v[0:1]
	s_nop 0
	v_pk_add_f32 v[2:3], v[0:1], v[0:1]
	v_mul_f32_e32 v1, 0x3fb8aa3b, v1
	v_mul_f32_e32 v9, 0x3fb8aa3b, v3
	v_rndne_f32_e32 v9, v9
	v_fmamk_f32 v13, v9, 0xbf317218, v3
	v_fmac_f32_e32 v13, 0x3102e308, v9
	v_fmamk_f32 v14, v13, 0x395133b1, v180
	v_fmaak_f32 v14, v13, v14, 0x3c0887f9
	v_fmaak_f32 v14, v13, v14, 0x3d2aaa81
	v_cvt_i32_f32_e32 v60, v9
	v_fmaak_f32 v14, v13, v14, 0x3e2aaaab
	v_fma_f32 v14, v13, v14, 0.5
	v_mul_f32_e32 v14, v13, v14
	v_fmac_f32_e32 v13, v13, v14
	v_ldexp_f32 v14, 1.0, v60
	v_cmp_eq_f32_e32 vcc, s34, v9
	v_exp_f32_e32 v1, v1
	v_mul_f32_e32 v0, 0x3fb8aa3b, v0
	v_cndmask_b32_e32 v9, v14, v197, vcc
	v_add_f32_e32 v14, -1.0, v9
	v_fmac_f32_e32 v14, v9, v13
	v_add_f32_e32 v9, v14, v14
	v_cndmask_b32_e32 v9, v14, v9, vcc
	v_cmp_nlt_f32_e32 vcc, s35, v3
	v_exp_f32_e32 v0, v0
	s_nop 0
	v_cndmask_b32_e64 v9, v190, -v9, vcc
	v_mul_f32_e32 v13, 0x4f800000, v9
	v_cmp_gt_f32_e32 vcc, s18, v9
	s_nop 1
	v_cndmask_b32_e32 v9, v9, v13, vcc
	v_sqrt_f32_e32 v13, v9
	s_nop 0
	v_add_u32_e32 v5, -1, v13
	v_fma_f32 v14, -v5, v13, v9
	v_cmp_ge_f32_e64 s[0:1], 0, v14
	v_add_u32_e32 v14, 1, v13
	s_nop 0
	v_cndmask_b32_e64 v5, v13, v5, s[0:1]
	v_fma_f32 v13, -v14, v13, v9
	v_cmp_lt_f32_e64 s[0:1], 0, v13
	s_nop 1
	v_cndmask_b32_e64 v5, v5, v14, s[0:1]
	v_mul_f32_e32 v13, 0x37800000, v5
	v_cndmask_b32_e32 v5, v5, v13, vcc
	v_cmp_class_f32_e32 vcc, v9, v181
	s_nop 1
	v_cndmask_b32_e32 v5, v5, v9, vcc
	v_cmp_ngt_f32_e32 vcc, s19, v3
	s_nop 1
	v_cndmask_b32_e32 v3, 1.0, v5, vcc
	v_mul_f32_e32 v3, v8, v3
	v_mul_f32_e32 v6, v3, v6
	v_mul_f32_e32 v3, 0x3fb8aa3b, v2
	v_rndne_f32_e32 v3, v3
	v_fmamk_f32 v5, v3, 0xbf317218, v2
	v_fmac_f32_e32 v5, 0x3102e308, v3
	v_fmamk_f32 v8, v5, 0x395133b1, v180
	v_fmaak_f32 v8, v5, v8, 0x3c0887f9
	v_fmaak_f32 v8, v5, v8, 0x3d2aaa81
	v_cvt_i32_f32_e32 v9, v3
	v_fmaak_f32 v8, v5, v8, 0x3e2aaaab
	v_fma_f32 v8, v5, v8, 0.5
	v_mul_f32_e32 v8, v5, v8
	v_fmac_f32_e32 v5, v5, v8
	v_ldexp_f32 v8, 1.0, v9
	v_cmp_eq_f32_e32 vcc, s34, v3
	v_fmac_f32_e32 v6, v1, v12
	s_nop 0
	v_cndmask_b32_e32 v3, v8, v197, vcc
	v_add_f32_e32 v8, -1.0, v3
	v_fmac_f32_e32 v8, v3, v5
	v_add_f32_e32 v3, v8, v8
	v_cndmask_b32_e32 v3, v8, v3, vcc
	v_cmp_nlt_f32_e32 vcc, s35, v2
	v_mul_f32_e32 v8, v1, v15
	v_mul_f32_e32 v13, v0, v8
	v_cndmask_b32_e64 v3, v190, -v3, vcc
	v_mul_f32_e32 v5, 0x4f800000, v3
	v_cmp_gt_f32_e32 vcc, s18, v3
	s_nop 1
	v_cndmask_b32_e32 v3, v3, v5, vcc
	v_sqrt_f32_e32 v5, v3
	s_nop 0
	v_add_u32_e32 v1, -1, v5
	v_fma_f32 v9, -v1, v5, v3
	v_cmp_ge_f32_e64 s[0:1], 0, v9
	v_add_u32_e32 v9, 1, v5
	s_nop 0
	v_cndmask_b32_e64 v1, v5, v1, s[0:1]
	v_fma_f32 v5, -v9, v5, v3
	v_cmp_lt_f32_e64 s[0:1], 0, v5
	s_nop 1
	v_cndmask_b32_e64 v1, v1, v9, s[0:1]
	v_mul_f32_e32 v5, 0x37800000, v1
	v_cndmask_b32_e32 v1, v1, v5, vcc
	v_cmp_class_f32_e32 vcc, v3, v181
	s_nop 1
	v_cndmask_b32_e32 v1, v1, v3, vcc
	v_cmp_ngt_f32_e32 vcc, s19, v2
	s_nop 1
	v_cndmask_b32_e32 v1, 1.0, v1, vcc
	v_mul_f32_e32 v1, v4, v1
	v_mul_f32_e32 v12, v1, v7
	v_fmac_f32_e32 v12, v0, v6
	v_ashrrev_i32_e32 v1, 31, v11
	v_mov_b32_e32 v0, v11
	v_ashrrev_i32_e32 v11, 31, v10
	v_lshlrev_b64 v[2:3], 9, v[10:11]
	v_lshl_add_u64 v[2:3], v[2:3], 0, v[24:25]
	v_lshlrev_b64 v[2:3], 2, v[2:3]
	v_lshl_add_u64 v[4:5], s[14:15], 0, v[2:3]
	v_lshl_add_u64 v[2:3], s[16:17], 0, v[2:3]
	global_store_dword v[4:5], v8, off
	global_store_dword v[2:3], v6, off
	v_mul_f32_e32 v2, 0xbfb8aa3b, v56
	v_lshlrev_b64 v[0:1], 9, v[0:1]
	v_exp_f32_e32 v4, v2
	v_lshl_add_u64 v[0:1], v[0:1], 0, v[26:27]
	v_lshlrev_b64 v[0:1], 2, v[0:1]
	v_lshl_add_u64 v[2:3], s[14:15], 0, v[0:1]
	global_store_dword v[2:3], v13, off
	v_add_f32_e32 v2, 1.0, v4
	v_div_scale_f32 v3, s[0:1], v2, v2, 1.0
	v_rcp_f32_e32 v4, v3
	v_lshl_add_u64 v[0:1], s[16:17], 0, v[0:1]
	global_store_dword v[0:1], v12, off
	v_mul_f32_e32 v0, 0xbfb8aa3b, v58
	v_exp_f32_e32 v5, v0
	v_fma_f32 v0, -v3, v4, 1.0
	v_fmac_f32_e32 v4, v0, v4
	v_div_scale_f32 v0, vcc, 1.0, v2, 1.0
	v_mul_f32_e32 v1, v0, v4
	v_fma_f32 v6, -v3, v1, v0
	v_fmac_f32_e32 v1, v6, v4
	v_fma_f32 v0, -v3, v1, v0
	v_mul_f32_e32 v3, 0xbfb8aa3b, v57
	v_exp_f32_e32 v3, v3
	v_div_fmas_f32 v0, v0, v4, v1
	v_mul_f32_e32 v4, 0xbfb8aa3b, v59
	v_exp_f32_e32 v4, v4
	v_add_f32_e32 v7, 1.0, v3
	v_div_scale_f32 v8, s[0:1], v7, v7, 1.0
	v_rcp_f32_e32 v9, v8
	v_pk_add_f32 v[4:5], v[4:5], 1.0 op_sel_hi:[1,0]
	v_div_fixup_f32 v6, v0, v2, 1.0
	ds_read_b128 v[0:3], v87 offset:64
	v_fma_f32 v10, -v8, v9, 1.0
	v_fmac_f32_e32 v9, v10, v9
	v_div_scale_f32 v10, vcc, 1.0, v7, 1.0
	v_mul_f32_e32 v11, v10, v9
	v_fma_f32 v14, -v8, v11, v10
	v_fmac_f32_e32 v11, v14, v9
	v_div_scale_f32 v14, s[0:1], v5, v5, 1.0
	v_rcp_f32_e32 v15, v14
	v_fma_f32 v8, -v8, v11, v10
	v_div_fmas_f32 v56, v8, v9, v11
	v_fma_f32 v8, -v14, v15, 1.0
	v_fmac_f32_e32 v15, v8, v15
	v_div_scale_f32 v8, vcc, 1.0, v5, 1.0
	v_mul_f32_e32 v9, v8, v15
	v_fma_f32 v10, -v14, v9, v8
	v_fmac_f32_e32 v9, v10, v15
	v_div_scale_f32 v10, s[0:1], v4, v4, 1.0
	v_rcp_f32_e32 v11, v10
	v_fma_f32 v8, -v14, v9, v8
	v_div_fmas_f32 v8, v8, v15, v9
	v_div_fixup_f32 v5, v8, v5, 1.0
	v_fma_f32 v8, -v10, v11, 1.0
	v_fmac_f32_e32 v11, v8, v11
	v_div_scale_f32 v8, vcc, 1.0, v4, 1.0
	v_mul_f32_e32 v9, v8, v11
	v_fma_f32 v14, -v10, v9, v8
	v_fmac_f32_e32 v9, v14, v11
	v_fma_f32 v8, -v10, v9, v8
	v_div_fmas_f32 v8, v8, v11, v9
	v_div_fixup_f32 v4, v8, v4, 1.0
	v_pk_mul_f32 v[4:5], v[4:5], s[44:45] op_sel_hi:[1,0]
	s_nop 0
	v_pk_mul_f32 v[10:11], v[18:19], v[4:5]
	s_nop 0
	v_pk_add_f32 v[8:9], v[10:11], v[10:11]
	v_mul_f32_e32 v10, 0x3fb8aa3b, v10
	v_mul_f32_e32 v4, 0x3fb8aa3b, v9
	v_rndne_f32_e32 v4, v4
	v_fmamk_f32 v5, v4, 0xbf317218, v9
	v_fmac_f32_e32 v5, 0x3102e308, v4
	v_fmamk_f32 v14, v5, 0x395133b1, v180
	v_fmaak_f32 v14, v5, v14, 0x3c0887f9
	v_fmaak_f32 v14, v5, v14, 0x3d2aaa81
	v_cvt_i32_f32_e32 v15, v4
	v_fmaak_f32 v14, v5, v14, 0x3e2aaaab
	v_fma_f32 v14, v5, v14, 0.5
	v_mul_f32_e32 v14, v5, v14
	v_fmac_f32_e32 v5, v5, v14
	v_ldexp_f32 v14, 1.0, v15
	v_cmp_eq_f32_e32 vcc, s34, v4
	v_exp_f32_e32 v10, v10
	s_nop 0
	v_cndmask_b32_e32 v4, v14, v197, vcc
	v_add_f32_e32 v14, -1.0, v4
	v_fmac_f32_e32 v14, v4, v5
	v_add_f32_e32 v4, v14, v14
	v_cndmask_b32_e32 v4, v14, v4, vcc
	v_cmp_nlt_f32_e32 vcc, s35, v9
	v_div_fixup_f32 v14, v56, v7, 1.0
	v_mul_f32_e32 v7, 0x3fb8aa3b, v11
	v_cndmask_b32_e64 v4, v190, -v4, vcc
	v_mul_f32_e32 v5, 0x4f800000, v4
	v_cmp_gt_f32_e32 vcc, s18, v4
	v_exp_f32_e32 v11, v7
	s_nop 0
	v_cndmask_b32_e32 v4, v4, v5, vcc
	v_sqrt_f32_e32 v5, v4
	v_mul_f32_e32 v59, v11, v13
	v_mul_f32_e32 v61, v10, v59
	v_add_u32_e32 v7, -1, v5
	v_fma_f32 v15, -v7, v5, v4
	v_cmp_ge_f32_e64 s[0:1], 0, v15
	v_add_u32_e32 v15, 1, v5
	s_nop 0
	v_cndmask_b32_e64 v7, v5, v7, s[0:1]
	v_fma_f32 v5, -v15, v5, v4
	v_cmp_lt_f32_e64 s[0:1], 0, v5
	s_nop 1
	v_cndmask_b32_e64 v5, v7, v15, s[0:1]
	v_mul_f32_e32 v7, 0x37800000, v5
	v_cndmask_b32_e32 v5, v5, v7, vcc
	v_cmp_class_f32_e32 vcc, v4, v181
	s_nop 1
	v_cndmask_b32_e32 v4, v5, v4, vcc
	v_cmp_ngt_f32_e32 vcc, s19, v9
	s_nop 1
	v_cndmask_b32_e32 v4, 1.0, v4, vcc
	v_mul_f32_e32 v9, v6, v4
	ds_read_b128 v[4:7], v87 offset:80
	s_waitcnt lgkmcnt(1)
	v_mul_f32_e32 v58, v9, v0
	v_mul_f32_e32 v0, 0x3fb8aa3b, v8
	v_rndne_f32_e32 v0, v0
	v_fmamk_f32 v9, v0, 0xbf317218, v8
	v_fmac_f32_e32 v9, 0x3102e308, v0
	v_fmac_f32_e32 v58, v11, v12
	v_fmamk_f32 v12, v9, 0x395133b1, v180
	v_fmaak_f32 v12, v9, v12, 0x3c0887f9
	v_fmaak_f32 v12, v9, v12, 0x3d2aaa81
	v_cvt_i32_f32_e32 v15, v0
	v_fmaak_f32 v12, v9, v12, 0x3e2aaaab
	v_fma_f32 v12, v9, v12, 0.5
	v_mul_f32_e32 v12, v9, v12
	v_fmac_f32_e32 v9, v9, v12
	v_ldexp_f32 v12, 1.0, v15
	v_cmp_eq_f32_e32 vcc, s34, v0
	s_nop 1
	v_cndmask_b32_e32 v0, v12, v197, vcc
	v_add_f32_e32 v12, -1.0, v0
	v_fmac_f32_e32 v12, v0, v9
	v_add_f32_e32 v0, v12, v12
	v_cndmask_b32_e32 v0, v12, v0, vcc
	v_cmp_nlt_f32_e32 vcc, s35, v8
	s_nop 1
	v_cndmask_b32_e64 v0, v190, -v0, vcc
	v_mul_f32_e32 v9, 0x4f800000, v0
	v_cmp_gt_f32_e32 vcc, s18, v0
	s_nop 1
	v_cndmask_b32_e32 v0, v0, v9, vcc
	v_sqrt_f32_e32 v9, v0
	s_nop 0
	v_add_u32_e32 v11, -1, v9
	v_fma_f32 v12, -v11, v9, v0
	v_cmp_ge_f32_e64 s[0:1], 0, v12
	v_add_u32_e32 v12, 1, v9
	s_nop 0
	v_cndmask_b32_e64 v11, v9, v11, s[0:1]
	v_fma_f32 v9, -v12, v9, v0
	v_cmp_lt_f32_e64 s[0:1], 0, v9
	s_nop 1
	v_cndmask_b32_e64 v9, v11, v12, s[0:1]
	v_mul_f32_e32 v11, 0x37800000, v9
	v_cndmask_b32_e32 v9, v9, v11, vcc
	v_cmp_class_f32_e32 vcc, v0, v181
	s_nop 1
	v_cndmask_b32_e32 v0, v9, v0, vcc
	v_cmp_ngt_f32_e32 vcc, s19, v8
	s_nop 1
	v_cndmask_b32_e32 v0, 1.0, v0, vcc
	v_mul_f32_e32 v0, v14, v0
	ds_read_b128 v[12:15], v82 offset:64
	v_mul_f32_e32 v60, v0, v1
	v_fmac_f32_e32 v60, v10, v58
	ds_read_b128 v[8:11], v82 offset:80
	s_waitcnt lgkmcnt(1)
	v_ashrrev_i32_e32 v1, 31, v13
	v_mov_b32_e32 v0, v13
	v_ashrrev_i32_e32 v13, 31, v12
	v_lshlrev_b64 v[12:13], 9, v[12:13]
	v_lshl_add_u64 v[12:13], v[12:13], 0, v[24:25]
	v_lshlrev_b64 v[12:13], 2, v[12:13]
	v_lshl_add_u64 v[56:57], s[14:15], 0, v[12:13]
	v_lshl_add_u64 v[12:13], s[16:17], 0, v[12:13]
	global_store_dword v[56:57], v59, off
	global_store_dword v[12:13], v58, off
	v_mul_f32_e32 v12, 0xbfb8aa3b, v52
	v_lshlrev_b64 v[0:1], 9, v[0:1]
	v_exp_f32_e32 v52, v12
	v_lshl_add_u64 v[0:1], v[0:1], 0, v[26:27]
	v_lshlrev_b64 v[0:1], 2, v[0:1]
	v_lshl_add_u64 v[12:13], s[14:15], 0, v[0:1]
	global_store_dword v[12:13], v61, off
	v_add_f32_e32 v12, 1.0, v52
	v_div_scale_f32 v13, s[0:1], v12, v12, 1.0
	v_rcp_f32_e32 v52, v13
	v_lshl_add_u64 v[0:1], s[16:17], 0, v[0:1]
	global_store_dword v[0:1], v60, off
	v_mul_f32_e32 v0, 0xbfb8aa3b, v54
	v_exp_f32_e32 v1, v0
	v_fma_f32 v0, -v13, v52, 1.0
	v_fmac_f32_e32 v52, v0, v52
	v_div_scale_f32 v0, vcc, 1.0, v12, 1.0
	v_mul_f32_e32 v54, v0, v52
	v_fma_f32 v56, -v13, v54, v0
	v_fmac_f32_e32 v54, v56, v52
	v_fma_f32 v0, -v13, v54, v0
	v_div_fmas_f32 v0, v0, v52, v54
	v_add_f32_e32 v52, 1.0, v53
	v_div_scale_f32 v13, s[0:1], v52, v52, 1.0
	v_rcp_f32_e32 v53, v13
	v_div_fixup_f32 v54, v0, v12, 1.0
	v_mul_f32_e32 v0, 0xbfb8aa3b, v55
	v_exp_f32_e32 v0, v0
	v_fma_f32 v12, -v13, v53, 1.0
	v_fmac_f32_e32 v53, v12, v53
	v_div_scale_f32 v12, vcc, 1.0, v52, 1.0
	v_mul_f32_e32 v55, v12, v53
	v_fma_f32 v56, -v13, v55, v12
	v_pk_add_f32 v[0:1], v[0:1], 1.0 op_sel_hi:[1,0]
	v_fmac_f32_e32 v55, v56, v53
	v_div_scale_f32 v56, s[0:1], v1, v1, 1.0
	v_rcp_f32_e32 v57, v56
	v_fma_f32 v12, -v13, v55, v12
	v_div_fmas_f32 v53, v12, v53, v55
	v_div_fixup_f32 v52, v53, v52, 1.0
	v_fma_f32 v12, -v56, v57, 1.0
	v_fmac_f32_e32 v57, v12, v57
	v_div_scale_f32 v12, vcc, 1.0, v1, 1.0
	v_mul_f32_e32 v13, v12, v57
	v_fma_f32 v55, -v56, v13, v12
	v_fmac_f32_e32 v13, v55, v57
	v_div_scale_f32 v55, s[0:1], v0, v0, 1.0
	v_fma_f32 v12, -v56, v13, v12
	v_rcp_f32_e32 v56, v55
	v_div_fmas_f32 v12, v12, v57, v13
	v_div_fixup_f32 v1, v12, v1, 1.0
	v_fma_f32 v12, -v55, v56, 1.0
	v_fmac_f32_e32 v56, v12, v56
	v_div_scale_f32 v12, vcc, 1.0, v0, 1.0
	v_mul_f32_e32 v13, v12, v56
	v_fma_f32 v57, -v55, v13, v12
	v_fmac_f32_e32 v13, v57, v56
	v_fma_f32 v12, -v55, v13, v12
	v_div_fmas_f32 v12, v12, v56, v13
	v_div_fixup_f32 v0, v12, v0, 1.0
	v_pk_mul_f32 v[0:1], v[0:1], s[44:45] op_sel_hi:[1,0]
	s_nop 0
	v_pk_mul_f32 v[0:1], v[18:19], v[0:1]
	s_nop 0
	v_pk_add_f32 v[12:13], v[0:1], v[0:1]
	v_mul_f32_e32 v1, 0x3fb8aa3b, v1
	v_mul_f32_e32 v55, 0x3fb8aa3b, v13
	v_rndne_f32_e32 v55, v55
	v_fmamk_f32 v56, v55, 0xbf317218, v13
	v_fmac_f32_e32 v56, 0x3102e308, v55
	v_fmamk_f32 v57, v56, 0x395133b1, v180
	v_fmaak_f32 v57, v56, v57, 0x3c0887f9
	v_fmaak_f32 v57, v56, v57, 0x3d2aaa81
	v_cvt_i32_f32_e32 v58, v55
	v_fmaak_f32 v57, v56, v57, 0x3e2aaaab
	v_fma_f32 v57, v56, v57, 0.5
	v_mul_f32_e32 v57, v56, v57
	v_fmac_f32_e32 v56, v56, v57
	v_ldexp_f32 v57, 1.0, v58
	v_cmp_eq_f32_e32 vcc, s34, v55
	v_exp_f32_e32 v1, v1
	v_mul_f32_e32 v0, 0x3fb8aa3b, v0
	v_cndmask_b32_e32 v55, v57, v197, vcc
	v_add_f32_e32 v57, -1.0, v55
	v_fmac_f32_e32 v57, v55, v56
	v_add_f32_e32 v55, v57, v57
	v_cndmask_b32_e32 v55, v57, v55, vcc
	v_cmp_nlt_f32_e32 vcc, s35, v13
	v_exp_f32_e32 v0, v0
	s_nop 0
	v_cndmask_b32_e64 v55, v190, -v55, vcc
	v_mul_f32_e32 v56, 0x4f800000, v55
	v_cmp_gt_f32_e32 vcc, s18, v55
	s_nop 1
	v_cndmask_b32_e32 v55, v55, v56, vcc
	v_sqrt_f32_e32 v56, v55
	s_nop 0
	v_add_u32_e32 v53, -1, v56
	v_fma_f32 v57, -v53, v56, v55
	v_cmp_ge_f32_e64 s[0:1], 0, v57
	v_add_u32_e32 v57, 1, v56
	s_nop 0
	v_cndmask_b32_e64 v53, v56, v53, s[0:1]
	v_fma_f32 v56, -v57, v56, v55
	v_cmp_lt_f32_e64 s[0:1], 0, v56
	s_nop 1
	v_cndmask_b32_e64 v53, v53, v57, s[0:1]
	v_mul_f32_e32 v56, 0x37800000, v53
	v_cndmask_b32_e32 v53, v53, v56, vcc
	v_cmp_class_f32_e32 vcc, v55, v181
	s_nop 1
	v_cndmask_b32_e32 v53, v53, v55, vcc
	v_cmp_ngt_f32_e32 vcc, s19, v13
	s_nop 1
	v_cndmask_b32_e32 v13, 1.0, v53, vcc
	v_mul_f32_e32 v13, v54, v13
	v_mul_f32_e32 v53, v13, v2
	v_mul_f32_e32 v2, 0x3fb8aa3b, v12
	v_rndne_f32_e32 v2, v2
	v_fmamk_f32 v13, v2, 0xbf317218, v12
	v_fmac_f32_e32 v13, 0x3102e308, v2
	v_fmamk_f32 v54, v13, 0x395133b1, v180
	v_fmaak_f32 v54, v13, v54, 0x3c0887f9
	v_fmaak_f32 v54, v13, v54, 0x3d2aaa81
	v_cvt_i32_f32_e32 v55, v2
	v_fmaak_f32 v54, v13, v54, 0x3e2aaaab
	v_fma_f32 v54, v13, v54, 0.5
	v_mul_f32_e32 v54, v13, v54
	v_fmac_f32_e32 v13, v13, v54
	v_ldexp_f32 v54, 1.0, v55
	v_cmp_eq_f32_e32 vcc, s34, v2
	v_fmac_f32_e32 v53, v1, v60
	s_nop 0
	v_cndmask_b32_e32 v2, v54, v197, vcc
	v_add_f32_e32 v54, -1.0, v2
	v_fmac_f32_e32 v54, v2, v13
	v_add_f32_e32 v2, v54, v54
	v_cndmask_b32_e32 v2, v54, v2, vcc
	v_cmp_nlt_f32_e32 vcc, s35, v12
	v_mul_f32_e32 v54, v1, v61
	s_nop 0
	v_cndmask_b32_e64 v2, v190, -v2, vcc
	v_mul_f32_e32 v13, 0x4f800000, v2
	v_cmp_gt_f32_e32 vcc, s18, v2
	s_nop 1
	v_cndmask_b32_e32 v2, v2, v13, vcc
	v_sqrt_f32_e32 v13, v2
	s_nop 0
	v_add_u32_e32 v1, -1, v13
	v_fma_f32 v55, -v1, v13, v2
	v_cmp_ge_f32_e64 s[0:1], 0, v55
	v_add_u32_e32 v55, 1, v13
	s_nop 0
	v_cndmask_b32_e64 v1, v13, v1, s[0:1]
	v_fma_f32 v13, -v55, v13, v2
	v_cmp_lt_f32_e64 s[0:1], 0, v13
	s_nop 1
	v_cndmask_b32_e64 v1, v1, v55, s[0:1]
	v_mul_f32_e32 v13, 0x37800000, v1
	v_cndmask_b32_e32 v1, v1, v13, vcc
	v_cmp_class_f32_e32 vcc, v2, v181
	v_mul_f32_e32 v55, v0, v54
	s_nop 0
	v_cndmask_b32_e32 v1, v1, v2, vcc
	v_cmp_ngt_f32_e32 vcc, s19, v12
	s_nop 1
	v_cndmask_b32_e32 v1, 1.0, v1, vcc
	v_mul_f32_e32 v1, v52, v1
	v_mul_f32_e32 v52, v1, v3
	v_fmac_f32_e32 v52, v0, v53
	v_ashrrev_i32_e32 v1, 31, v15
	v_mov_b32_e32 v0, v15
	v_ashrrev_i32_e32 v15, 31, v14
	v_lshlrev_b64 v[2:3], 9, v[14:15]
	v_lshl_add_u64 v[2:3], v[2:3], 0, v[24:25]
	v_lshlrev_b64 v[2:3], 2, v[2:3]
	v_lshl_add_u64 v[12:13], s[14:15], 0, v[2:3]
	v_lshl_add_u64 v[2:3], s[16:17], 0, v[2:3]
	global_store_dword v[12:13], v54, off
	global_store_dword v[2:3], v53, off
	v_mul_f32_e32 v2, 0xbfb8aa3b, v48
	v_lshlrev_b64 v[0:1], 9, v[0:1]
	v_exp_f32_e32 v12, v2
	v_lshl_add_u64 v[0:1], v[0:1], 0, v[26:27]
	v_lshlrev_b64 v[0:1], 2, v[0:1]
	v_lshl_add_u64 v[2:3], s[14:15], 0, v[0:1]
	global_store_dword v[2:3], v55, off
	v_add_f32_e32 v2, 1.0, v12
	v_div_scale_f32 v3, s[0:1], v2, v2, 1.0
	v_rcp_f32_e32 v12, v3
	v_lshl_add_u64 v[0:1], s[16:17], 0, v[0:1]
	global_store_dword v[0:1], v52, off
	v_mul_f32_e32 v0, 0xbfb8aa3b, v50
	v_exp_f32_e32 v1, v0
	v_fma_f32 v0, -v3, v12, 1.0
	v_fmac_f32_e32 v12, v0, v12
	v_div_scale_f32 v0, vcc, 1.0, v2, 1.0
	v_mul_f32_e32 v13, v0, v12
	v_fma_f32 v14, -v3, v13, v0
	v_fmac_f32_e32 v13, v14, v12
	v_mul_f32_e32 v14, 0xbfb8aa3b, v49
	v_exp_f32_e32 v14, v14
	v_fma_f32 v0, -v3, v13, v0
	v_div_fmas_f32 v0, v0, v12, v13
	v_add_f32_e32 v12, 1.0, v14
	v_div_scale_f32 v3, s[0:1], v12, v12, 1.0
	v_rcp_f32_e32 v13, v3
	v_div_fixup_f32 v14, v0, v2, 1.0
	v_mul_f32_e32 v0, 0xbfb8aa3b, v51
	v_exp_f32_e32 v0, v0
	v_fma_f32 v2, -v3, v13, 1.0
	v_fmac_f32_e32 v13, v2, v13
	v_div_scale_f32 v2, vcc, 1.0, v12, 1.0
	v_mul_f32_e32 v15, v2, v13
	v_fma_f32 v48, -v3, v15, v2
	v_pk_add_f32 v[0:1], v[0:1], 1.0 op_sel_hi:[1,0]
	v_fmac_f32_e32 v15, v48, v13
	v_div_scale_f32 v48, s[0:1], v1, v1, 1.0
	v_rcp_f32_e32 v49, v48
	v_fma_f32 v2, -v3, v15, v2
	v_div_fmas_f32 v13, v2, v13, v15
	v_div_fixup_f32 v12, v13, v12, 1.0
	v_fma_f32 v2, -v48, v49, 1.0
	v_fmac_f32_e32 v49, v2, v49
	v_div_scale_f32 v2, vcc, 1.0, v1, 1.0
	v_mul_f32_e32 v3, v2, v49
	v_fma_f32 v15, -v48, v3, v2
	v_fmac_f32_e32 v3, v15, v49
	v_div_scale_f32 v15, s[0:1], v0, v0, 1.0
	v_fma_f32 v2, -v48, v3, v2
	v_rcp_f32_e32 v48, v15
	v_div_fmas_f32 v2, v2, v49, v3
	v_div_fixup_f32 v1, v2, v1, 1.0
	v_fma_f32 v2, -v15, v48, 1.0
	v_fmac_f32_e32 v48, v2, v48
	v_div_scale_f32 v2, vcc, 1.0, v0, 1.0
	v_mul_f32_e32 v3, v2, v48
	v_fma_f32 v49, -v15, v3, v2
	v_fmac_f32_e32 v3, v49, v48
	v_fma_f32 v2, -v15, v3, v2
	v_div_fmas_f32 v2, v2, v48, v3
	v_div_fixup_f32 v0, v2, v0, 1.0
	v_pk_mul_f32 v[0:1], v[0:1], s[44:45] op_sel_hi:[1,0]
	s_nop 0
	v_pk_mul_f32 v[0:1], v[18:19], v[0:1]
	s_nop 0
	v_pk_add_f32 v[2:3], v[0:1], v[0:1]
	v_mul_f32_e32 v1, 0x3fb8aa3b, v1
	v_mul_f32_e32 v15, 0x3fb8aa3b, v3
	v_rndne_f32_e32 v15, v15
	v_fmamk_f32 v48, v15, 0xbf317218, v3
	v_fmac_f32_e32 v48, 0x3102e308, v15
	v_fmamk_f32 v49, v48, 0x395133b1, v180
	v_fmaak_f32 v49, v48, v49, 0x3c0887f9
	v_fmaak_f32 v49, v48, v49, 0x3d2aaa81
	v_cvt_i32_f32_e32 v50, v15
	v_fmaak_f32 v49, v48, v49, 0x3e2aaaab
	v_fma_f32 v49, v48, v49, 0.5
	v_mul_f32_e32 v49, v48, v49
	v_fmac_f32_e32 v48, v48, v49
	v_ldexp_f32 v49, 1.0, v50
	v_cmp_eq_f32_e32 vcc, s34, v15
	v_exp_f32_e32 v1, v1
	v_mul_f32_e32 v0, 0x3fb8aa3b, v0
	v_cndmask_b32_e32 v15, v49, v197, vcc
	v_add_f32_e32 v49, -1.0, v15
	v_fmac_f32_e32 v49, v15, v48
	v_add_f32_e32 v15, v49, v49
	v_cndmask_b32_e32 v15, v49, v15, vcc
	v_cmp_nlt_f32_e32 vcc, s35, v3
	v_exp_f32_e32 v0, v0
	s_nop 0
	v_cndmask_b32_e64 v15, v190, -v15, vcc
	v_mul_f32_e32 v48, 0x4f800000, v15
	v_cmp_gt_f32_e32 vcc, s18, v15
	s_nop 1
	v_cndmask_b32_e32 v15, v15, v48, vcc
	v_sqrt_f32_e32 v48, v15
	s_nop 0
	v_add_u32_e32 v13, -1, v48
	v_fma_f32 v49, -v13, v48, v15
	v_cmp_ge_f32_e64 s[0:1], 0, v49
	v_add_u32_e32 v49, 1, v48
	s_nop 0
	v_cndmask_b32_e64 v13, v48, v13, s[0:1]
	v_fma_f32 v48, -v49, v48, v15
	v_cmp_lt_f32_e64 s[0:1], 0, v48
	s_nop 1
	v_cndmask_b32_e64 v13, v13, v49, s[0:1]
	v_mul_f32_e32 v48, 0x37800000, v13
	v_cndmask_b32_e32 v13, v13, v48, vcc
	v_cmp_class_f32_e32 vcc, v15, v181
	s_nop 1
	v_cndmask_b32_e32 v13, v13, v15, vcc
	v_cmp_ngt_f32_e32 vcc, s19, v3
	s_nop 1
	v_cndmask_b32_e32 v3, 1.0, v13, vcc
	v_mul_f32_e32 v3, v14, v3
	v_mul_f32_e32 v13, v3, v4
	v_mul_f32_e32 v3, 0x3fb8aa3b, v2
	v_rndne_f32_e32 v3, v3
	v_fmamk_f32 v4, v3, 0xbf317218, v2
	v_fmac_f32_e32 v4, 0x3102e308, v3
	v_fmamk_f32 v14, v4, 0x395133b1, v180
	v_fmaak_f32 v14, v4, v14, 0x3c0887f9
	v_fmaak_f32 v14, v4, v14, 0x3d2aaa81
	v_cvt_i32_f32_e32 v15, v3
	v_fmaak_f32 v14, v4, v14, 0x3e2aaaab
	v_fma_f32 v14, v4, v14, 0.5
	v_mul_f32_e32 v14, v4, v14
	v_fmac_f32_e32 v4, v4, v14
	v_ldexp_f32 v14, 1.0, v15
	v_cmp_eq_f32_e32 vcc, s34, v3
	v_fmac_f32_e32 v13, v1, v52
	s_nop 0
	v_cndmask_b32_e32 v3, v14, v197, vcc
	v_add_f32_e32 v14, -1.0, v3
	v_fmac_f32_e32 v14, v3, v4
	v_add_f32_e32 v3, v14, v14
	v_cndmask_b32_e32 v3, v14, v3, vcc
	v_cmp_nlt_f32_e32 vcc, s35, v2
	v_mul_f32_e32 v14, v1, v55
	s_nop 0
	v_cndmask_b32_e64 v3, v190, -v3, vcc
	v_mul_f32_e32 v4, 0x4f800000, v3
	v_cmp_gt_f32_e32 vcc, s18, v3
	s_nop 1
	v_cndmask_b32_e32 v3, v3, v4, vcc
	v_sqrt_f32_e32 v4, v3
	s_nop 0
	v_add_u32_e32 v1, -1, v4
	v_fma_f32 v15, -v1, v4, v3
	v_cmp_ge_f32_e64 s[0:1], 0, v15
	v_add_u32_e32 v15, 1, v4
	s_nop 0
	v_cndmask_b32_e64 v1, v4, v1, s[0:1]
	v_fma_f32 v4, -v15, v4, v3
	v_cmp_lt_f32_e64 s[0:1], 0, v4
	s_nop 1
	v_cndmask_b32_e64 v1, v1, v15, s[0:1]
	v_mul_f32_e32 v4, 0x37800000, v1
	v_cndmask_b32_e32 v1, v1, v4, vcc
	v_cmp_class_f32_e32 vcc, v3, v181
	v_mul_f32_e32 v15, v0, v14
	s_nop 0
	v_cndmask_b32_e32 v1, v1, v3, vcc
	v_cmp_ngt_f32_e32 vcc, s19, v2
	s_nop 1
	v_cndmask_b32_e32 v1, 1.0, v1, vcc
	v_mul_f32_e32 v1, v12, v1
	v_mul_f32_e32 v12, v1, v5
	v_fmac_f32_e32 v12, v0, v13
	s_waitcnt lgkmcnt(0)
	v_ashrrev_i32_e32 v1, 31, v9
	v_mov_b32_e32 v0, v9
	v_ashrrev_i32_e32 v9, 31, v8
	v_lshlrev_b64 v[2:3], 9, v[8:9]
	v_lshl_add_u64 v[2:3], v[2:3], 0, v[24:25]
	v_lshlrev_b64 v[2:3], 2, v[2:3]
	v_lshl_add_u64 v[4:5], s[14:15], 0, v[2:3]
	v_lshl_add_u64 v[2:3], s[16:17], 0, v[2:3]
	global_store_dword v[4:5], v14, off
	global_store_dword v[2:3], v13, off
	v_mul_f32_e32 v2, 0xbfb8aa3b, v44
	v_lshlrev_b64 v[0:1], 9, v[0:1]
	v_exp_f32_e32 v4, v2
	v_lshl_add_u64 v[0:1], v[0:1], 0, v[26:27]
	v_lshlrev_b64 v[0:1], 2, v[0:1]
	v_lshl_add_u64 v[2:3], s[14:15], 0, v[0:1]
	global_store_dword v[2:3], v15, off
	v_add_f32_e32 v2, 1.0, v4
	v_div_scale_f32 v3, s[0:1], v2, v2, 1.0
	v_rcp_f32_e32 v4, v3
	v_lshl_add_u64 v[0:1], s[16:17], 0, v[0:1]
	global_store_dword v[0:1], v12, off
	v_mul_f32_e32 v0, 0xbfb8aa3b, v46
	v_exp_f32_e32 v1, v0
	v_fma_f32 v0, -v3, v4, 1.0
	v_fmac_f32_e32 v4, v0, v4
	v_div_scale_f32 v0, vcc, 1.0, v2, 1.0
	v_mul_f32_e32 v5, v0, v4
	v_fma_f32 v8, -v3, v5, v0
	v_fmac_f32_e32 v5, v8, v4
	v_mul_f32_e32 v8, 0xbfb8aa3b, v45
	v_exp_f32_e32 v8, v8
	v_fma_f32 v0, -v3, v5, v0
	v_div_fmas_f32 v0, v0, v4, v5
	v_add_f32_e32 v4, 1.0, v8
	v_div_scale_f32 v3, s[0:1], v4, v4, 1.0
	v_rcp_f32_e32 v5, v3
	v_div_fixup_f32 v8, v0, v2, 1.0
	v_mul_f32_e32 v0, 0xbfb8aa3b, v47
	v_exp_f32_e32 v0, v0
	v_fma_f32 v2, -v3, v5, 1.0
	v_fmac_f32_e32 v5, v2, v5
	v_div_scale_f32 v2, vcc, 1.0, v4, 1.0
	v_mul_f32_e32 v9, v2, v5
	v_fma_f32 v13, -v3, v9, v2
	v_pk_add_f32 v[0:1], v[0:1], 1.0 op_sel_hi:[1,0]
	v_fmac_f32_e32 v9, v13, v5
	v_div_scale_f32 v13, s[0:1], v1, v1, 1.0
	v_rcp_f32_e32 v14, v13
	v_fma_f32 v2, -v3, v9, v2
	v_div_fmas_f32 v5, v2, v5, v9
	v_div_fixup_f32 v4, v5, v4, 1.0
	v_fma_f32 v2, -v13, v14, 1.0
	v_fmac_f32_e32 v14, v2, v14
	v_div_scale_f32 v2, vcc, 1.0, v1, 1.0
	v_mul_f32_e32 v3, v2, v14
	v_fma_f32 v9, -v13, v3, v2
	v_fmac_f32_e32 v3, v9, v14
	v_div_scale_f32 v9, s[0:1], v0, v0, 1.0
	v_fma_f32 v2, -v13, v3, v2
	v_rcp_f32_e32 v13, v9
	v_div_fmas_f32 v2, v2, v14, v3
	v_div_fixup_f32 v1, v2, v1, 1.0
	v_fma_f32 v2, -v9, v13, 1.0
	v_fmac_f32_e32 v13, v2, v13
	v_div_scale_f32 v2, vcc, 1.0, v0, 1.0
	v_mul_f32_e32 v3, v2, v13
	v_fma_f32 v14, -v9, v3, v2
	v_fmac_f32_e32 v3, v14, v13
	v_fma_f32 v2, -v9, v3, v2
	v_div_fmas_f32 v2, v2, v13, v3
	v_div_fixup_f32 v0, v2, v0, 1.0
	v_pk_mul_f32 v[0:1], v[0:1], s[44:45] op_sel_hi:[1,0]
	s_nop 0
	v_pk_mul_f32 v[0:1], v[18:19], v[0:1]
	s_nop 0
	v_pk_add_f32 v[2:3], v[0:1], v[0:1]
	v_mul_f32_e32 v1, 0x3fb8aa3b, v1
	v_mul_f32_e32 v9, 0x3fb8aa3b, v3
	v_rndne_f32_e32 v9, v9
	v_fmamk_f32 v13, v9, 0xbf317218, v3
	v_fmac_f32_e32 v13, 0x3102e308, v9
	v_fmamk_f32 v14, v13, 0x395133b1, v180
	v_fmaak_f32 v14, v13, v14, 0x3c0887f9
	v_fmaak_f32 v14, v13, v14, 0x3d2aaa81
	v_cvt_i32_f32_e32 v44, v9
	v_fmaak_f32 v14, v13, v14, 0x3e2aaaab
	v_fma_f32 v14, v13, v14, 0.5
	v_mul_f32_e32 v14, v13, v14
	v_fmac_f32_e32 v13, v13, v14
	v_ldexp_f32 v14, 1.0, v44
	v_cmp_eq_f32_e32 vcc, s34, v9
	v_exp_f32_e32 v1, v1
	v_mul_f32_e32 v0, 0x3fb8aa3b, v0
	v_cndmask_b32_e32 v9, v14, v197, vcc
	v_add_f32_e32 v14, -1.0, v9
	v_fmac_f32_e32 v14, v9, v13
	v_add_f32_e32 v9, v14, v14
	v_cndmask_b32_e32 v9, v14, v9, vcc
	v_cmp_nlt_f32_e32 vcc, s35, v3
	v_exp_f32_e32 v0, v0
	s_nop 0
	v_cndmask_b32_e64 v9, v190, -v9, vcc
	v_mul_f32_e32 v13, 0x4f800000, v9
	v_cmp_gt_f32_e32 vcc, s18, v9
	s_nop 1
	v_cndmask_b32_e32 v9, v9, v13, vcc
	v_sqrt_f32_e32 v13, v9
	s_nop 0
	v_add_u32_e32 v5, -1, v13
	v_fma_f32 v14, -v5, v13, v9
	v_cmp_ge_f32_e64 s[0:1], 0, v14
	v_add_u32_e32 v14, 1, v13
	s_nop 0
	v_cndmask_b32_e64 v5, v13, v5, s[0:1]
	v_fma_f32 v13, -v14, v13, v9
	v_cmp_lt_f32_e64 s[0:1], 0, v13
	s_nop 1
	v_cndmask_b32_e64 v5, v5, v14, s[0:1]
	v_mul_f32_e32 v13, 0x37800000, v5
	v_cndmask_b32_e32 v5, v5, v13, vcc
	v_cmp_class_f32_e32 vcc, v9, v181
	s_nop 1
	v_cndmask_b32_e32 v5, v5, v9, vcc
	v_cmp_ngt_f32_e32 vcc, s19, v3
	s_nop 1
	v_cndmask_b32_e32 v3, 1.0, v5, vcc
	v_mul_f32_e32 v3, v8, v3
	v_mul_f32_e32 v6, v3, v6
	v_mul_f32_e32 v3, 0x3fb8aa3b, v2
	v_rndne_f32_e32 v3, v3
	v_fmamk_f32 v5, v3, 0xbf317218, v2
	v_fmac_f32_e32 v5, 0x3102e308, v3
	v_fmamk_f32 v8, v5, 0x395133b1, v180
	v_fmaak_f32 v8, v5, v8, 0x3c0887f9
	v_fmaak_f32 v8, v5, v8, 0x3d2aaa81
	v_cvt_i32_f32_e32 v9, v3
	v_fmaak_f32 v8, v5, v8, 0x3e2aaaab
	v_fma_f32 v8, v5, v8, 0.5
	v_mul_f32_e32 v8, v5, v8
	v_fmac_f32_e32 v5, v5, v8
	v_ldexp_f32 v8, 1.0, v9
	v_cmp_eq_f32_e32 vcc, s34, v3
	v_fmac_f32_e32 v6, v1, v12
	s_nop 0
	v_cndmask_b32_e32 v3, v8, v197, vcc
	v_add_f32_e32 v8, -1.0, v3
	v_fmac_f32_e32 v8, v3, v5
	v_add_f32_e32 v3, v8, v8
	v_cndmask_b32_e32 v3, v8, v3, vcc
	v_cmp_nlt_f32_e32 vcc, s35, v2
	v_mul_f32_e32 v8, v1, v15
	v_mul_f32_e32 v13, v0, v8
	v_cndmask_b32_e64 v3, v190, -v3, vcc
	v_mul_f32_e32 v5, 0x4f800000, v3
	v_cmp_gt_f32_e32 vcc, s18, v3
	s_nop 1
	v_cndmask_b32_e32 v3, v3, v5, vcc
	v_sqrt_f32_e32 v5, v3
	s_nop 0
	v_add_u32_e32 v1, -1, v5
	v_fma_f32 v9, -v1, v5, v3
	v_cmp_ge_f32_e64 s[0:1], 0, v9
	v_add_u32_e32 v9, 1, v5
	s_nop 0
	v_cndmask_b32_e64 v1, v5, v1, s[0:1]
	v_fma_f32 v5, -v9, v5, v3
	v_cmp_lt_f32_e64 s[0:1], 0, v5
	s_nop 1
	v_cndmask_b32_e64 v1, v1, v9, s[0:1]
	v_mul_f32_e32 v5, 0x37800000, v1
	v_cndmask_b32_e32 v1, v1, v5, vcc
	v_cmp_class_f32_e32 vcc, v3, v181
	s_nop 1
	v_cndmask_b32_e32 v1, v1, v3, vcc
	v_cmp_ngt_f32_e32 vcc, s19, v2
	s_nop 1
	v_cndmask_b32_e32 v1, 1.0, v1, vcc
	v_mul_f32_e32 v1, v4, v1
	v_mul_f32_e32 v12, v1, v7
	v_fmac_f32_e32 v12, v0, v6
	v_ashrrev_i32_e32 v1, 31, v11
	v_mov_b32_e32 v0, v11
	v_ashrrev_i32_e32 v11, 31, v10
	v_lshlrev_b64 v[2:3], 9, v[10:11]
	v_lshl_add_u64 v[2:3], v[2:3], 0, v[24:25]
	v_lshlrev_b64 v[2:3], 2, v[2:3]
	v_lshl_add_u64 v[4:5], s[14:15], 0, v[2:3]
	v_lshl_add_u64 v[2:3], s[16:17], 0, v[2:3]
	global_store_dword v[4:5], v8, off
	global_store_dword v[2:3], v6, off
	v_mul_f32_e32 v2, 0xbfb8aa3b, v40
	v_lshlrev_b64 v[0:1], 9, v[0:1]
	v_exp_f32_e32 v4, v2
	v_lshl_add_u64 v[0:1], v[0:1], 0, v[26:27]
	v_lshlrev_b64 v[0:1], 2, v[0:1]
	v_lshl_add_u64 v[2:3], s[14:15], 0, v[0:1]
	global_store_dword v[2:3], v13, off
	v_add_f32_e32 v2, 1.0, v4
	v_div_scale_f32 v3, s[0:1], v2, v2, 1.0
	v_rcp_f32_e32 v4, v3
	v_lshl_add_u64 v[0:1], s[16:17], 0, v[0:1]
	global_store_dword v[0:1], v12, off
	v_mul_f32_e32 v0, 0xbfb8aa3b, v42
	v_exp_f32_e32 v1, v0
	v_fma_f32 v0, -v3, v4, 1.0
	v_fmac_f32_e32 v4, v0, v4
	v_div_scale_f32 v0, vcc, 1.0, v2, 1.0
	v_mul_f32_e32 v5, v0, v4
	v_fma_f32 v6, -v3, v5, v0
	v_fmac_f32_e32 v5, v6, v4
	v_fma_f32 v0, -v3, v5, v0
	v_mul_f32_e32 v3, 0xbfb8aa3b, v41
	v_exp_f32_e32 v3, v3
	v_div_fmas_f32 v0, v0, v4, v5
	v_div_fixup_f32 v2, v0, v2, 1.0
	v_mul_f32_e32 v0, 0xbfb8aa3b, v43
	v_add_f32_e32 v3, 1.0, v3
	v_div_scale_f32 v8, s[0:1], v3, v3, 1.0
	v_rcp_f32_e32 v9, v8
	v_exp_f32_e32 v0, v0
	ds_read_b128 v[4:7], v87 offset:96
	v_fma_f32 v10, -v8, v9, 1.0
	v_fmac_f32_e32 v9, v10, v9
	v_div_scale_f32 v10, vcc, 1.0, v3, 1.0
	v_mul_f32_e32 v11, v10, v9
	v_fma_f32 v14, -v8, v11, v10
	v_pk_add_f32 v[0:1], v[0:1], 1.0 op_sel_hi:[1,0]
	v_fmac_f32_e32 v11, v14, v9
	v_div_scale_f32 v14, s[0:1], v1, v1, 1.0
	v_rcp_f32_e32 v15, v14
	v_fma_f32 v8, -v8, v11, v10
	v_div_fmas_f32 v40, v8, v9, v11
	v_fma_f32 v8, -v14, v15, 1.0
	v_fmac_f32_e32 v15, v8, v15
	v_div_scale_f32 v8, vcc, 1.0, v1, 1.0
	v_mul_f32_e32 v9, v8, v15
	v_fma_f32 v10, -v14, v9, v8
	v_fmac_f32_e32 v9, v10, v15
	v_div_scale_f32 v10, s[0:1], v0, v0, 1.0
	v_rcp_f32_e32 v11, v10
	v_fma_f32 v8, -v14, v9, v8
	v_div_fmas_f32 v8, v8, v15, v9
	v_div_fixup_f32 v1, v8, v1, 1.0
	v_fma_f32 v8, -v10, v11, 1.0
	v_fmac_f32_e32 v11, v8, v11
	v_div_scale_f32 v8, vcc, 1.0, v0, 1.0
	v_mul_f32_e32 v9, v8, v11
	v_fma_f32 v14, -v10, v9, v8
	v_fmac_f32_e32 v9, v14, v11
	v_fma_f32 v8, -v10, v9, v8
	v_div_fmas_f32 v8, v8, v11, v9
	v_div_fixup_f32 v0, v8, v0, 1.0
	v_pk_mul_f32 v[0:1], v[0:1], s[44:45] op_sel_hi:[1,0]
	s_nop 0
	v_pk_mul_f32 v[10:11], v[18:19], v[0:1]
	s_nop 0
	v_pk_add_f32 v[8:9], v[10:11], v[10:11]
	v_mul_f32_e32 v10, 0x3fb8aa3b, v10
	v_mul_f32_e32 v0, 0x3fb8aa3b, v9
	v_rndne_f32_e32 v0, v0
	v_fmamk_f32 v1, v0, 0xbf317218, v9
	v_fmac_f32_e32 v1, 0x3102e308, v0
	v_fmamk_f32 v14, v1, 0x395133b1, v180
	v_fmaak_f32 v14, v1, v14, 0x3c0887f9
	v_fmaak_f32 v14, v1, v14, 0x3d2aaa81
	v_cvt_i32_f32_e32 v15, v0
	v_fmaak_f32 v14, v1, v14, 0x3e2aaaab
	v_fma_f32 v14, v1, v14, 0.5
	v_mul_f32_e32 v14, v1, v14
	v_fmac_f32_e32 v1, v1, v14
	v_ldexp_f32 v14, 1.0, v15
	v_cmp_eq_f32_e32 vcc, s34, v0
	v_exp_f32_e32 v10, v10
	s_nop 0
	v_cndmask_b32_e32 v0, v14, v197, vcc
	v_add_f32_e32 v14, -1.0, v0
	v_fmac_f32_e32 v14, v0, v1
	v_add_f32_e32 v0, v14, v14
	v_cndmask_b32_e32 v0, v14, v0, vcc
	v_cmp_nlt_f32_e32 vcc, s35, v9
	v_div_fixup_f32 v14, v40, v3, 1.0
	v_mul_f32_e32 v3, 0x3fb8aa3b, v11
	v_cndmask_b32_e64 v0, v190, -v0, vcc
	v_mul_f32_e32 v1, 0x4f800000, v0
	v_cmp_gt_f32_e32 vcc, s18, v0
	v_exp_f32_e32 v11, v3
	s_nop 0
	v_cndmask_b32_e32 v0, v0, v1, vcc
	v_sqrt_f32_e32 v1, v0
	v_mul_f32_e32 v43, v11, v13
	v_mul_f32_e32 v45, v10, v43
	v_add_u32_e32 v3, -1, v1
	v_fma_f32 v15, -v3, v1, v0
	v_cmp_ge_f32_e64 s[0:1], 0, v15
	v_add_u32_e32 v15, 1, v1
	s_nop 0
	v_cndmask_b32_e64 v3, v1, v3, s[0:1]
	v_fma_f32 v1, -v15, v1, v0
	v_cmp_lt_f32_e64 s[0:1], 0, v1
	s_nop 1
	v_cndmask_b32_e64 v1, v3, v15, s[0:1]
	v_mul_f32_e32 v3, 0x37800000, v1
	v_cndmask_b32_e32 v1, v1, v3, vcc
	v_cmp_class_f32_e32 vcc, v0, v181
	s_nop 1
	v_cndmask_b32_e32 v0, v1, v0, vcc
	v_cmp_ngt_f32_e32 vcc, s19, v9
	s_nop 1
	v_cndmask_b32_e32 v0, 1.0, v0, vcc
	v_mul_f32_e32 v9, v2, v0
	ds_read_b128 v[0:3], v87 offset:112
	s_waitcnt lgkmcnt(1)
	v_mul_f32_e32 v42, v9, v4
	v_mul_f32_e32 v4, 0x3fb8aa3b, v8
	v_rndne_f32_e32 v4, v4
	v_fmamk_f32 v9, v4, 0xbf317218, v8
	v_fmac_f32_e32 v9, 0x3102e308, v4
	v_fmac_f32_e32 v42, v11, v12
	v_fmamk_f32 v12, v9, 0x395133b1, v180
	v_fmaak_f32 v12, v9, v12, 0x3c0887f9
	v_fmaak_f32 v12, v9, v12, 0x3d2aaa81
	v_cvt_i32_f32_e32 v15, v4
	v_fmaak_f32 v12, v9, v12, 0x3e2aaaab
	v_fma_f32 v12, v9, v12, 0.5
	v_mul_f32_e32 v12, v9, v12
	v_fmac_f32_e32 v9, v9, v12
	v_ldexp_f32 v12, 1.0, v15
	v_cmp_eq_f32_e32 vcc, s34, v4
	s_nop 1
	v_cndmask_b32_e32 v4, v12, v197, vcc
	v_add_f32_e32 v12, -1.0, v4
	v_fmac_f32_e32 v12, v4, v9
	v_add_f32_e32 v4, v12, v12
	v_cndmask_b32_e32 v4, v12, v4, vcc
	v_cmp_nlt_f32_e32 vcc, s35, v8
	s_nop 1
	v_cndmask_b32_e64 v4, v190, -v4, vcc
	v_mul_f32_e32 v9, 0x4f800000, v4
	v_cmp_gt_f32_e32 vcc, s18, v4
	s_nop 1
	v_cndmask_b32_e32 v4, v4, v9, vcc
	v_sqrt_f32_e32 v9, v4
	s_nop 0
	v_add_u32_e32 v11, -1, v9
	v_fma_f32 v12, -v11, v9, v4
	v_cmp_ge_f32_e64 s[0:1], 0, v12
	v_add_u32_e32 v12, 1, v9
	s_nop 0
	v_cndmask_b32_e64 v11, v9, v11, s[0:1]
	v_fma_f32 v9, -v12, v9, v4
	v_cmp_lt_f32_e64 s[0:1], 0, v9
	s_nop 1
	v_cndmask_b32_e64 v9, v11, v12, s[0:1]
	v_mul_f32_e32 v11, 0x37800000, v9
	v_cndmask_b32_e32 v9, v9, v11, vcc
	v_cmp_class_f32_e32 vcc, v4, v181
	s_nop 1
	v_cndmask_b32_e32 v4, v9, v4, vcc
	v_cmp_ngt_f32_e32 vcc, s19, v8
	s_nop 1
	v_cndmask_b32_e32 v4, 1.0, v4, vcc
	v_mul_f32_e32 v4, v14, v4
	ds_read_b128 v[12:15], v82 offset:96
	v_mul_f32_e32 v44, v4, v5
	v_fmac_f32_e32 v44, v10, v42
	ds_read_b128 v[8:11], v82 offset:112
	s_waitcnt lgkmcnt(1)
	v_ashrrev_i32_e32 v5, 31, v13
	v_mov_b32_e32 v4, v13
	v_ashrrev_i32_e32 v13, 31, v12
	v_lshlrev_b64 v[12:13], 9, v[12:13]
	v_lshl_add_u64 v[12:13], v[12:13], 0, v[24:25]
	v_lshlrev_b64 v[12:13], 2, v[12:13]
	v_lshl_add_u64 v[40:41], s[14:15], 0, v[12:13]
	v_lshl_add_u64 v[12:13], s[16:17], 0, v[12:13]
	global_store_dword v[40:41], v43, off
	global_store_dword v[12:13], v42, off
	v_mul_f32_e32 v12, 0xbfb8aa3b, v36
	v_lshlrev_b64 v[4:5], 9, v[4:5]
	v_exp_f32_e32 v36, v12
	v_lshl_add_u64 v[4:5], v[4:5], 0, v[26:27]
	v_lshlrev_b64 v[4:5], 2, v[4:5]
	v_lshl_add_u64 v[12:13], s[14:15], 0, v[4:5]
	global_store_dword v[12:13], v45, off
	v_add_f32_e32 v12, 1.0, v36
	v_div_scale_f32 v13, s[0:1], v12, v12, 1.0
	v_rcp_f32_e32 v36, v13
	v_lshl_add_u64 v[4:5], s[16:17], 0, v[4:5]
	global_store_dword v[4:5], v44, off
	v_mul_f32_e32 v4, 0xbfb8aa3b, v38
	v_exp_f32_e32 v5, v4
	v_fma_f32 v4, -v13, v36, 1.0
	v_fmac_f32_e32 v36, v4, v36
	v_div_scale_f32 v4, vcc, 1.0, v12, 1.0
	v_mul_f32_e32 v38, v4, v36
	v_fma_f32 v40, -v13, v38, v4
	v_fmac_f32_e32 v38, v40, v36
	v_fma_f32 v4, -v13, v38, v4
	v_div_fmas_f32 v4, v4, v36, v38
	v_add_f32_e32 v36, 1.0, v37
	v_div_scale_f32 v13, s[0:1], v36, v36, 1.0
	v_rcp_f32_e32 v37, v13
	v_div_fixup_f32 v38, v4, v12, 1.0
	v_mul_f32_e32 v4, 0xbfb8aa3b, v39
	v_exp_f32_e32 v4, v4
	v_fma_f32 v12, -v13, v37, 1.0
	v_fmac_f32_e32 v37, v12, v37
	v_div_scale_f32 v12, vcc, 1.0, v36, 1.0
	v_mul_f32_e32 v39, v12, v37
	v_fma_f32 v40, -v13, v39, v12
	v_pk_add_f32 v[4:5], v[4:5], 1.0 op_sel_hi:[1,0]
	v_fmac_f32_e32 v39, v40, v37
	v_div_scale_f32 v40, s[0:1], v5, v5, 1.0
	v_rcp_f32_e32 v41, v40
	v_fma_f32 v12, -v13, v39, v12
	v_div_fmas_f32 v37, v12, v37, v39
	v_div_fixup_f32 v36, v37, v36, 1.0
	v_fma_f32 v12, -v40, v41, 1.0
	v_fmac_f32_e32 v41, v12, v41
	v_div_scale_f32 v12, vcc, 1.0, v5, 1.0
	v_mul_f32_e32 v13, v12, v41
	v_fma_f32 v39, -v40, v13, v12
	v_fmac_f32_e32 v13, v39, v41
	v_div_scale_f32 v39, s[0:1], v4, v4, 1.0
	v_fma_f32 v12, -v40, v13, v12
	v_rcp_f32_e32 v40, v39
	v_div_fmas_f32 v12, v12, v41, v13
	v_div_fixup_f32 v5, v12, v5, 1.0
	v_fma_f32 v12, -v39, v40, 1.0
	v_fmac_f32_e32 v40, v12, v40
	v_div_scale_f32 v12, vcc, 1.0, v4, 1.0
	v_mul_f32_e32 v13, v12, v40
	v_fma_f32 v41, -v39, v13, v12
	v_fmac_f32_e32 v13, v41, v40
	v_fma_f32 v12, -v39, v13, v12
	v_div_fmas_f32 v12, v12, v40, v13
	v_div_fixup_f32 v4, v12, v4, 1.0
	v_pk_mul_f32 v[4:5], v[4:5], s[44:45] op_sel_hi:[1,0]
	s_nop 0
	v_pk_mul_f32 v[4:5], v[18:19], v[4:5]
	s_nop 0
	v_pk_add_f32 v[12:13], v[4:5], v[4:5]
	v_mul_f32_e32 v5, 0x3fb8aa3b, v5
	v_mul_f32_e32 v39, 0x3fb8aa3b, v13
	v_rndne_f32_e32 v39, v39
	v_fmamk_f32 v40, v39, 0xbf317218, v13
	v_fmac_f32_e32 v40, 0x3102e308, v39
	v_fmamk_f32 v41, v40, 0x395133b1, v180
	v_fmaak_f32 v41, v40, v41, 0x3c0887f9
	v_fmaak_f32 v41, v40, v41, 0x3d2aaa81
	v_cvt_i32_f32_e32 v42, v39
	v_fmaak_f32 v41, v40, v41, 0x3e2aaaab
	v_fma_f32 v41, v40, v41, 0.5
	v_mul_f32_e32 v41, v40, v41
	v_fmac_f32_e32 v40, v40, v41
	v_ldexp_f32 v41, 1.0, v42
	v_cmp_eq_f32_e32 vcc, s34, v39
	v_exp_f32_e32 v5, v5
	v_mul_f32_e32 v4, 0x3fb8aa3b, v4
	v_cndmask_b32_e32 v39, v41, v197, vcc
	v_add_f32_e32 v41, -1.0, v39
	v_fmac_f32_e32 v41, v39, v40
	v_add_f32_e32 v39, v41, v41
	v_cndmask_b32_e32 v39, v41, v39, vcc
	v_cmp_nlt_f32_e32 vcc, s35, v13
	v_exp_f32_e32 v4, v4
	s_nop 0
	v_cndmask_b32_e64 v39, v190, -v39, vcc
	v_mul_f32_e32 v40, 0x4f800000, v39
	v_cmp_gt_f32_e32 vcc, s18, v39
	s_nop 1
	v_cndmask_b32_e32 v39, v39, v40, vcc
	v_sqrt_f32_e32 v40, v39
	s_nop 0
	v_add_u32_e32 v37, -1, v40
	v_fma_f32 v41, -v37, v40, v39
	v_cmp_ge_f32_e64 s[0:1], 0, v41
	v_add_u32_e32 v41, 1, v40
	s_nop 0
	v_cndmask_b32_e64 v37, v40, v37, s[0:1]
	v_fma_f32 v40, -v41, v40, v39
	v_cmp_lt_f32_e64 s[0:1], 0, v40
	s_nop 1
	v_cndmask_b32_e64 v37, v37, v41, s[0:1]
	v_mul_f32_e32 v40, 0x37800000, v37
	v_cndmask_b32_e32 v37, v37, v40, vcc
	v_cmp_class_f32_e32 vcc, v39, v181
	s_nop 1
	v_cndmask_b32_e32 v37, v37, v39, vcc
	v_cmp_ngt_f32_e32 vcc, s19, v13
	s_nop 1
	v_cndmask_b32_e32 v13, 1.0, v37, vcc
	v_mul_f32_e32 v13, v38, v13
	v_mul_f32_e32 v37, v13, v6
	v_mul_f32_e32 v6, 0x3fb8aa3b, v12
	v_rndne_f32_e32 v6, v6
	v_fmamk_f32 v13, v6, 0xbf317218, v12
	v_fmac_f32_e32 v13, 0x3102e308, v6
	v_fmamk_f32 v38, v13, 0x395133b1, v180
	v_fmaak_f32 v38, v13, v38, 0x3c0887f9
	v_fmaak_f32 v38, v13, v38, 0x3d2aaa81
	v_cvt_i32_f32_e32 v39, v6
	v_fmaak_f32 v38, v13, v38, 0x3e2aaaab
	v_fma_f32 v38, v13, v38, 0.5
	v_mul_f32_e32 v38, v13, v38
	v_fmac_f32_e32 v13, v13, v38
	v_ldexp_f32 v38, 1.0, v39
	v_cmp_eq_f32_e32 vcc, s34, v6
	v_fmac_f32_e32 v37, v5, v44
	s_nop 0
	v_cndmask_b32_e32 v6, v38, v197, vcc
	v_add_f32_e32 v38, -1.0, v6
	v_fmac_f32_e32 v38, v6, v13
	v_add_f32_e32 v6, v38, v38
	v_cndmask_b32_e32 v6, v38, v6, vcc
	v_cmp_nlt_f32_e32 vcc, s35, v12
	v_mul_f32_e32 v38, v5, v45
	s_nop 0
	v_cndmask_b32_e64 v6, v190, -v6, vcc
	v_mul_f32_e32 v13, 0x4f800000, v6
	v_cmp_gt_f32_e32 vcc, s18, v6
	s_nop 1
	v_cndmask_b32_e32 v6, v6, v13, vcc
	v_sqrt_f32_e32 v13, v6
	s_nop 0
	v_add_u32_e32 v5, -1, v13
	v_fma_f32 v39, -v5, v13, v6
	v_cmp_ge_f32_e64 s[0:1], 0, v39
	v_add_u32_e32 v39, 1, v13
	s_nop 0
	v_cndmask_b32_e64 v5, v13, v5, s[0:1]
	v_fma_f32 v13, -v39, v13, v6
	v_cmp_lt_f32_e64 s[0:1], 0, v13
	s_nop 1
	v_cndmask_b32_e64 v5, v5, v39, s[0:1]
	v_mul_f32_e32 v13, 0x37800000, v5
	v_cndmask_b32_e32 v5, v5, v13, vcc
	v_cmp_class_f32_e32 vcc, v6, v181
	v_mul_f32_e32 v39, v4, v38
	s_nop 0
	v_cndmask_b32_e32 v5, v5, v6, vcc
	v_cmp_ngt_f32_e32 vcc, s19, v12
	s_nop 1
	v_cndmask_b32_e32 v5, 1.0, v5, vcc
	v_mul_f32_e32 v5, v36, v5
	v_mul_f32_e32 v36, v5, v7
	v_fmac_f32_e32 v36, v4, v37
	v_ashrrev_i32_e32 v5, 31, v15
	v_mov_b32_e32 v4, v15
	v_ashrrev_i32_e32 v15, 31, v14
	v_lshlrev_b64 v[6:7], 9, v[14:15]
	v_lshl_add_u64 v[6:7], v[6:7], 0, v[24:25]
	v_lshlrev_b64 v[6:7], 2, v[6:7]
	v_lshl_add_u64 v[12:13], s[14:15], 0, v[6:7]
	v_lshl_add_u64 v[6:7], s[16:17], 0, v[6:7]
	global_store_dword v[12:13], v38, off
	global_store_dword v[6:7], v37, off
	v_mul_f32_e32 v6, 0xbfb8aa3b, v32
	v_lshlrev_b64 v[4:5], 9, v[4:5]
	v_exp_f32_e32 v12, v6
	v_lshl_add_u64 v[4:5], v[4:5], 0, v[26:27]
	v_lshlrev_b64 v[4:5], 2, v[4:5]
	v_lshl_add_u64 v[6:7], s[14:15], 0, v[4:5]
	global_store_dword v[6:7], v39, off
	v_add_f32_e32 v6, 1.0, v12
	v_div_scale_f32 v7, s[0:1], v6, v6, 1.0
	v_rcp_f32_e32 v12, v7
	v_lshl_add_u64 v[4:5], s[16:17], 0, v[4:5]
	global_store_dword v[4:5], v36, off
	v_mul_f32_e32 v4, 0xbfb8aa3b, v34
	v_exp_f32_e32 v5, v4
	v_fma_f32 v4, -v7, v12, 1.0
	v_fmac_f32_e32 v12, v4, v12
	v_div_scale_f32 v4, vcc, 1.0, v6, 1.0
	v_mul_f32_e32 v13, v4, v12
	v_fma_f32 v14, -v7, v13, v4
	v_fmac_f32_e32 v13, v14, v12
	v_mul_f32_e32 v14, 0xbfb8aa3b, v33
	v_exp_f32_e32 v14, v14
	v_fma_f32 v4, -v7, v13, v4
	v_div_fmas_f32 v4, v4, v12, v13
	v_add_f32_e32 v12, 1.0, v14
	v_div_scale_f32 v7, s[0:1], v12, v12, 1.0
	v_rcp_f32_e32 v13, v7
	v_div_fixup_f32 v14, v4, v6, 1.0
	v_mul_f32_e32 v4, 0xbfb8aa3b, v35
	v_exp_f32_e32 v4, v4
	v_fma_f32 v6, -v7, v13, 1.0
	v_fmac_f32_e32 v13, v6, v13
	v_div_scale_f32 v6, vcc, 1.0, v12, 1.0
	v_mul_f32_e32 v15, v6, v13
	v_fma_f32 v32, -v7, v15, v6
	v_pk_add_f32 v[4:5], v[4:5], 1.0 op_sel_hi:[1,0]
	v_fmac_f32_e32 v15, v32, v13
	v_div_scale_f32 v32, s[0:1], v5, v5, 1.0
	v_rcp_f32_e32 v33, v32
	v_fma_f32 v6, -v7, v15, v6
	v_div_fmas_f32 v13, v6, v13, v15
	v_div_fixup_f32 v12, v13, v12, 1.0
	v_fma_f32 v6, -v32, v33, 1.0
	v_fmac_f32_e32 v33, v6, v33
	v_div_scale_f32 v6, vcc, 1.0, v5, 1.0
	v_mul_f32_e32 v7, v6, v33
	v_fma_f32 v15, -v32, v7, v6
	v_fmac_f32_e32 v7, v15, v33
	v_div_scale_f32 v15, s[0:1], v4, v4, 1.0
	v_fma_f32 v6, -v32, v7, v6
	v_rcp_f32_e32 v32, v15
	v_div_fmas_f32 v6, v6, v33, v7
	v_div_fixup_f32 v5, v6, v5, 1.0
	v_fma_f32 v6, -v15, v32, 1.0
	v_fmac_f32_e32 v32, v6, v32
	v_div_scale_f32 v6, vcc, 1.0, v4, 1.0
	v_mul_f32_e32 v7, v6, v32
	v_fma_f32 v33, -v15, v7, v6
	v_fmac_f32_e32 v7, v33, v32
	v_fma_f32 v6, -v15, v7, v6
	v_div_fmas_f32 v6, v6, v32, v7
	v_div_fixup_f32 v4, v6, v4, 1.0
	v_pk_mul_f32 v[4:5], v[4:5], s[44:45] op_sel_hi:[1,0]
	s_nop 0
	v_pk_mul_f32 v[4:5], v[18:19], v[4:5]
	s_nop 0
	v_pk_add_f32 v[6:7], v[4:5], v[4:5]
	v_mul_f32_e32 v4, 0x3fb8aa3b, v4
	v_mul_f32_e32 v15, 0x3fb8aa3b, v7
	v_rndne_f32_e32 v15, v15
	v_fmamk_f32 v32, v15, 0xbf317218, v7
	v_fmac_f32_e32 v32, 0x3102e308, v15
	v_fmamk_f32 v33, v32, 0x395133b1, v180
	v_fmaak_f32 v33, v32, v33, 0x3c0887f9
	v_fmaak_f32 v33, v32, v33, 0x3d2aaa81
	v_cvt_i32_f32_e32 v34, v15
	v_fmaak_f32 v33, v32, v33, 0x3e2aaaab
	v_fma_f32 v33, v32, v33, 0.5
	v_mul_f32_e32 v33, v32, v33
	v_fmac_f32_e32 v32, v32, v33
	v_ldexp_f32 v33, 1.0, v34
	v_cmp_eq_f32_e32 vcc, s34, v15
	v_mul_f32_e32 v5, 0x3fb8aa3b, v5
	v_exp_f32_e32 v5, v5
	v_cndmask_b32_e32 v15, v33, v197, vcc
	v_add_f32_e32 v33, -1.0, v15
	v_fmac_f32_e32 v33, v15, v32
	v_add_f32_e32 v15, v33, v33
	v_cndmask_b32_e32 v15, v33, v15, vcc
	v_cmp_nlt_f32_e32 vcc, s35, v7
	s_nop 1
	v_cndmask_b32_e64 v15, v190, -v15, vcc
	v_mul_f32_e32 v32, 0x4f800000, v15
	v_cmp_gt_f32_e32 vcc, s18, v15
	s_nop 1
	v_cndmask_b32_e32 v15, v15, v32, vcc
	v_sqrt_f32_e32 v32, v15
	s_nop 0
	v_add_u32_e32 v13, -1, v32
	v_fma_f32 v33, -v13, v32, v15
	v_cmp_ge_f32_e64 s[0:1], 0, v33
	v_add_u32_e32 v33, 1, v32
	s_nop 0
	v_cndmask_b32_e64 v13, v32, v13, s[0:1]
	v_fma_f32 v32, -v33, v32, v15
	v_cmp_lt_f32_e64 s[0:1], 0, v32
	s_nop 1
	v_cndmask_b32_e64 v13, v13, v33, s[0:1]
	v_mul_f32_e32 v32, 0x37800000, v13
	v_cndmask_b32_e32 v13, v13, v32, vcc
	v_cmp_class_f32_e32 vcc, v15, v181
	s_nop 1
	v_cndmask_b32_e32 v13, v13, v15, vcc
	v_cmp_ngt_f32_e32 vcc, s19, v7
	s_nop 1
	v_cndmask_b32_e32 v7, 1.0, v13, vcc
	v_mul_f32_e32 v7, v14, v7
	v_mul_f32_e32 v14, v7, v0
	v_mul_f32_e32 v0, 0x3fb8aa3b, v6
	v_rndne_f32_e32 v0, v0
	v_fmamk_f32 v7, v0, 0xbf317218, v6
	v_fmac_f32_e32 v7, 0x3102e308, v0
	v_fmamk_f32 v13, v7, 0x395133b1, v180
	v_fmaak_f32 v13, v7, v13, 0x3c0887f9
	v_fmaak_f32 v13, v7, v13, 0x3d2aaa81
	v_cvt_i32_f32_e32 v15, v0
	v_fmaak_f32 v13, v7, v13, 0x3e2aaaab
	v_fma_f32 v13, v7, v13, 0.5
	v_mul_f32_e32 v13, v7, v13
	v_fmac_f32_e32 v7, v7, v13
	v_ldexp_f32 v13, 1.0, v15
	v_cmp_eq_f32_e32 vcc, s34, v0
	v_fmac_f32_e32 v14, v5, v36
	v_mul_f32_e32 v5, v5, v39
	v_cndmask_b32_e32 v0, v13, v197, vcc
	v_add_f32_e32 v13, -1.0, v0
	v_fmac_f32_e32 v13, v0, v7
	v_add_f32_e32 v0, v13, v13
	v_cndmask_b32_e32 v0, v13, v0, vcc
	v_cmp_nlt_f32_e32 vcc, s35, v6
	s_nop 1
	v_cndmask_b32_e64 v0, v190, -v0, vcc
	v_mul_f32_e32 v7, 0x4f800000, v0
	v_cmp_gt_f32_e32 vcc, s18, v0
	s_nop 1
	v_cndmask_b32_e32 v0, v0, v7, vcc
	v_sqrt_f32_e32 v13, v0
	v_exp_f32_e32 v7, v4
	v_add_u32_e32 v4, -1, v13
	v_fma_f32 v15, -v4, v13, v0
	v_cmp_ge_f32_e64 s[0:1], 0, v15
	v_add_u32_e32 v15, 1, v13
	s_nop 0
	v_cndmask_b32_e64 v4, v13, v4, s[0:1]
	v_fma_f32 v13, -v15, v13, v0
	v_cmp_lt_f32_e64 s[0:1], 0, v13
	s_nop 1
	v_cndmask_b32_e64 v4, v4, v15, s[0:1]
	v_mul_f32_e32 v13, 0x37800000, v4
	v_cndmask_b32_e32 v4, v4, v13, vcc
	v_cmp_class_f32_e32 vcc, v0, v181
	s_nop 1
	v_cndmask_b32_e32 v0, v4, v0, vcc
	v_cmp_ngt_f32_e32 vcc, s19, v6
	v_mul_f32_e32 v4, 0xbfb8aa3b, v28
	v_exp_f32_e32 v4, v4
	v_cndmask_b32_e32 v0, 1.0, v0, vcc
	v_mul_f32_e32 v0, v12, v0
	v_mul_f32_e32 v6, v0, v1
	s_waitcnt lgkmcnt(0)
	v_ashrrev_i32_e32 v1, 31, v9
	v_mov_b32_e32 v0, v9
	v_ashrrev_i32_e32 v9, 31, v8
	v_lshlrev_b64 v[8:9], 9, v[8:9]
	v_lshl_add_u64 v[8:9], v[8:9], 0, v[24:25]
	v_lshlrev_b64 v[8:9], 2, v[8:9]
	v_lshl_add_u64 v[12:13], s[14:15], 0, v[8:9]
	v_add_f32_e32 v4, 1.0, v4
	v_lshlrev_b64 v[0:1], 9, v[0:1]
	v_lshl_add_u64 v[8:9], s[16:17], 0, v[8:9]
	global_store_dword v[12:13], v5, off
	global_store_dword v[8:9], v14, off
	v_div_scale_f32 v12, s[0:1], v4, v4, 1.0
	v_lshl_add_u64 v[0:1], v[0:1], 0, v[26:27]
	v_rcp_f32_e32 v13, v12
	v_lshlrev_b64 v[0:1], 2, v[0:1]
	v_fmac_f32_e32 v6, v7, v14
	v_lshl_add_u64 v[8:9], s[14:15], 0, v[0:1]
	v_lshl_add_u64 v[0:1], s[16:17], 0, v[0:1]
	global_store_dword v[0:1], v6, off
	v_mul_f32_e32 v0, 0xbfb8aa3b, v30
	v_exp_f32_e32 v1, v0
	v_fma_f32 v0, -v12, v13, 1.0
	v_fmac_f32_e32 v13, v0, v13
	v_div_scale_f32 v0, vcc, 1.0, v4, 1.0
	v_mul_f32_e32 v14, v0, v13
	v_fma_f32 v15, -v12, v14, v0
	v_fmac_f32_e32 v14, v15, v13
	v_mul_f32_e32 v15, 0xbfb8aa3b, v29
	v_exp_f32_e32 v15, v15
	v_fma_f32 v0, -v12, v14, v0
	v_div_fmas_f32 v0, v0, v13, v14
	v_add_f32_e32 v14, 1.0, v15
	v_div_scale_f32 v12, s[0:1], v14, v14, 1.0
	v_rcp_f32_e32 v13, v12
	v_div_fixup_f32 v15, v0, v4, 1.0
	v_mul_f32_e32 v0, 0xbfb8aa3b, v31
	v_exp_f32_e32 v0, v0
	v_fma_f32 v4, -v12, v13, 1.0
	v_fmac_f32_e32 v13, v4, v13
	v_div_scale_f32 v4, vcc, 1.0, v14, 1.0
	v_mul_f32_e32 v28, v4, v13
	v_fma_f32 v29, -v12, v28, v4
	v_pk_add_f32 v[0:1], v[0:1], 1.0 op_sel_hi:[1,0]
	v_fmac_f32_e32 v28, v29, v13
	v_div_scale_f32 v29, s[0:1], v1, v1, 1.0
	v_rcp_f32_e32 v30, v29
	v_fma_f32 v4, -v12, v28, v4
	v_div_fmas_f32 v4, v4, v13, v28
	v_div_fixup_f32 v4, v4, v14, 1.0
	v_fma_f32 v12, -v29, v30, 1.0
	v_fmac_f32_e32 v30, v12, v30
	v_div_scale_f32 v12, vcc, 1.0, v1, 1.0
	v_mul_f32_e32 v13, v12, v30
	v_fma_f32 v28, -v29, v13, v12
	v_fmac_f32_e32 v13, v28, v30
	v_div_scale_f32 v28, s[0:1], v0, v0, 1.0
	v_fma_f32 v12, -v29, v13, v12
	v_rcp_f32_e32 v29, v28
	v_div_fmas_f32 v12, v12, v30, v13
	v_div_fixup_f32 v1, v12, v1, 1.0
	v_fma_f32 v12, -v28, v29, 1.0
	v_fmac_f32_e32 v29, v12, v29
	v_div_scale_f32 v12, vcc, 1.0, v0, 1.0
	v_mul_f32_e32 v13, v12, v29
	v_fma_f32 v30, -v28, v13, v12
	v_fmac_f32_e32 v13, v30, v29
	v_fma_f32 v12, -v28, v13, v12
	v_div_fmas_f32 v12, v12, v29, v13
	v_div_fixup_f32 v0, v12, v0, 1.0
	v_pk_mul_f32 v[0:1], v[0:1], s[44:45] op_sel_hi:[1,0]
	s_nop 0
	v_pk_mul_f32 v[0:1], v[18:19], v[0:1]
	s_nop 0
	v_pk_add_f32 v[12:13], v[0:1], v[0:1]
	v_mul_f32_e32 v1, 0x3fb8aa3b, v1
	v_mul_f32_e32 v28, 0x3fb8aa3b, v13
	v_rndne_f32_e32 v28, v28
	v_fmamk_f32 v29, v28, 0xbf317218, v13
	v_fmac_f32_e32 v29, 0x3102e308, v28
	v_fmamk_f32 v30, v29, 0x395133b1, v180
	v_fmaak_f32 v30, v29, v30, 0x3c0887f9
	v_fmaak_f32 v30, v29, v30, 0x3d2aaa81
	v_cvt_i32_f32_e32 v31, v28
	v_fmaak_f32 v30, v29, v30, 0x3e2aaaab
	v_fma_f32 v30, v29, v30, 0.5
	v_mul_f32_e32 v30, v29, v30
	v_fmac_f32_e32 v29, v29, v30
	v_ldexp_f32 v30, 1.0, v31
	v_cmp_eq_f32_e32 vcc, s34, v28
	v_exp_f32_e32 v1, v1
	v_mul_f32_e32 v0, 0x3fb8aa3b, v0
	v_cndmask_b32_e32 v28, v30, v197, vcc
	v_add_f32_e32 v30, -1.0, v28
	v_fmac_f32_e32 v30, v28, v29
	v_add_f32_e32 v28, v30, v30
	v_cndmask_b32_e32 v28, v30, v28, vcc
	v_cmp_nlt_f32_e32 vcc, s35, v13
	s_nop 1
	v_cndmask_b32_e64 v28, v190, -v28, vcc
	v_mul_f32_e32 v29, 0x4f800000, v28
	v_cmp_gt_f32_e32 vcc, s18, v28
	s_nop 1
	v_cndmask_b32_e32 v28, v28, v29, vcc
	v_sqrt_f32_e32 v29, v28
	s_nop 0
	v_add_u32_e32 v14, -1, v29
	v_fma_f32 v30, -v14, v29, v28
	v_cmp_ge_f32_e64 s[0:1], 0, v30
	v_add_u32_e32 v30, 1, v29
	s_nop 0
	v_cndmask_b32_e64 v14, v29, v14, s[0:1]
	v_fma_f32 v29, -v30, v29, v28
	v_cmp_lt_f32_e64 s[0:1], 0, v29
	s_nop 1
	v_cndmask_b32_e64 v14, v14, v30, s[0:1]
	v_mul_f32_e32 v29, 0x37800000, v14
	v_cndmask_b32_e32 v14, v14, v29, vcc
	v_cmp_class_f32_e32 vcc, v28, v181
	s_nop 1
	v_cndmask_b32_e32 v14, v14, v28, vcc
	v_cmp_ngt_f32_e32 vcc, s19, v13
	s_nop 1
	v_cndmask_b32_e32 v13, 1.0, v14, vcc
	v_mul_f32_e32 v13, v15, v13
	v_mul_f32_e32 v13, v13, v2
	v_mul_f32_e32 v2, 0x3fb8aa3b, v12
	v_rndne_f32_e32 v2, v2
	v_fmamk_f32 v14, v2, 0xbf317218, v12
	v_fmac_f32_e32 v14, 0x3102e308, v2
	v_fmamk_f32 v15, v14, 0x395133b1, v180
	v_fmaak_f32 v15, v14, v15, 0x3c0887f9
	v_fmaak_f32 v15, v14, v15, 0x3d2aaa81
	v_cvt_i32_f32_e32 v28, v2
	v_fmaak_f32 v15, v14, v15, 0x3e2aaaab
	v_fma_f32 v15, v14, v15, 0.5
	v_mul_f32_e32 v15, v14, v15
	v_fmac_f32_e32 v14, v14, v15
	v_ldexp_f32 v15, 1.0, v28
	v_cmp_eq_f32_e32 vcc, s34, v2
	v_fmac_f32_e32 v13, v1, v6
	s_nop 0
	v_cndmask_b32_e32 v2, v15, v197, vcc
	v_add_f32_e32 v15, -1.0, v2
	v_fmac_f32_e32 v15, v2, v14
	v_add_f32_e32 v2, v15, v15
	v_cndmask_b32_e32 v2, v15, v2, vcc
	v_cmp_nlt_f32_e32 vcc, s35, v12
	v_exp_f32_e32 v15, v0
	s_nop 0
	v_cndmask_b32_e64 v2, v190, -v2, vcc
	v_mul_f32_e32 v14, 0x4f800000, v2
	v_cmp_gt_f32_e32 vcc, s18, v2
	s_nop 1
	v_cndmask_b32_e32 v2, v2, v14, vcc
	v_sqrt_f32_e32 v14, v2
	s_nop 0
	v_add_u32_e32 v0, -1, v14
	v_fma_f32 v6, -v0, v14, v2
	v_cmp_ge_f32_e64 s[0:1], 0, v6
	v_add_u32_e32 v6, 1, v14
	s_nop 0
	v_cndmask_b32_e64 v0, v14, v0, s[0:1]
	v_fma_f32 v14, -v6, v14, v2
	v_cmp_lt_f32_e64 s[0:1], 0, v14
	s_nop 1
	v_cndmask_b32_e64 v0, v0, v6, s[0:1]
	v_mul_f32_e32 v6, 0x37800000, v0
	v_cndmask_b32_e32 v0, v0, v6, vcc
	v_cmp_class_f32_e32 vcc, v2, v181
	s_mov_b64 s[0:1], 0
	s_nop 0
	v_cndmask_b32_e32 v0, v0, v2, vcc
	v_cmp_ngt_f32_e32 vcc, s19, v12
	v_mul_f32_e32 v2, v15, v13
	s_nop 0
	v_cndmask_b32_e32 v6, 1.0, v0, vcc
	v_pk_mul_f32 v[6:7], v[4:5], v[6:7]
	v_mov_b32_e32 v0, v3
	v_pk_fma_f32 v[4:5], v[6:7], v[0:1], v[2:3]
	v_ashrrev_i32_e32 v3, 31, v11
	v_mov_b32_e32 v2, v11
	v_ashrrev_i32_e32 v11, 31, v10
	global_store_dword v[8:9], v7, off
	v_lshlrev_b64 v[8:9], 9, v[10:11]
	v_lshlrev_b64 v[2:3], 9, v[2:3]
	v_lshl_add_u64 v[8:9], v[8:9], 0, v[24:25]
	v_lshl_add_u64 v[2:3], v[2:3], 0, v[26:27]
	v_lshlrev_b64 v[8:9], 2, v[8:9]
	v_lshl_add_u64 v[10:11], s[14:15], 0, v[8:9]
	v_mul_f32_e32 v5, v7, v1
	v_lshlrev_b64 v[0:1], 2, v[2:3]
	v_lshl_add_u64 v[8:9], s[16:17], 0, v[8:9]
	global_store_dword v[10:11], v5, off
	global_store_dword v[8:9], v13, off
	v_lshl_add_u64 v[2:3], s[14:15], 0, v[0:1]
	v_mul_f32_e32 v5, v15, v5
	v_lshl_add_u64 v[0:1], s[16:17], 0, v[0:1]
	s_and_b64 vcc, exec, s[8:9]
	global_store_dword v[2:3], v5, off
	global_store_dword v[0:1], v4, off
	s_cbranch_vccz .LBB0_521
	s_and_b64 s[0:1], s[2:3], exec
	s_cselect_b32 s0, 4, 64
	s_not_b32 s1, s13
	s_add_i32 s8, s0, s1
	s_and_b64 s[0:1], s[38:39], exec
	s_cselect_b32 s8, s13, s8
	s_lshl_b32 s0, s12, 6
	s_lshl_b32 s9, s12, 2
	s_add_i32 s10, s0, 0x7ffc40
	s_and_b64 s[0:1], s[2:3], exec
	s_cselect_b32 s0, s9, s10
	s_add_i32 s8, s8, s0
	s_lshl_b32 s0, s8, 9
	s_or_b32 s0, s0, s20
	v_add_u32_e32 v0, s0, v16
	v_ashrrev_i32_e32 v1, 31, v0
	v_readlane_b32 s0, v247, 8
	v_lshlrev_b64 v[0:1], 2, v[0:1]
	v_readlane_b32 s1, v247, 9
	v_readlane_b32 s34, v247, 57
	v_readlane_b32 s35, v247, 58
	v_lshl_add_u64 v[2:3], s[0:1], 0, v[0:1]
	v_readlane_b32 s0, v247, 10
	v_readlane_b32 s1, v247, 11
	global_store_dword v[2:3], v5, off
	s_nop 0
	v_lshl_add_u64 v[0:1], s[0:1], 0, v[0:1]
	global_store_dword v[0:1], v4, off
	s_branch .LBB0_460

.LBB0_833:
	s_lshl_b32 s0, s14, 6
	s_add_i32 s8, s13, s0
	s_cmp_gt_u32 s11, 7
	s_cselect_b64 s[4:5], -1, 0
	s_cmpk_gt_i32 s8, 0x1ff
	s_cselect_b64 s[0:1], -1, 0
	s_or_b64 s[6:7], s[4:5], s[0:1]
	s_andn2_b64 vcc, exec, s[6:7]
	s_cbranch_vccnz .LBB0_845
	v_and_b32_e32 v25, 63, v28
	v_cmp_gt_i32_e32 vcc, s53, v28
	s_waitcnt lgkmcnt(0)
	s_barrier
	s_and_saveexec_b64 s[6:7], vcc
	s_cbranch_execz .LBB0_841
	s_bfe_u32 s9, s8, 0x90016
	s_add_i32 s8, s8, s9
	s_sext_i32_i16 s8, s8
	s_ashr_i32 s16, s8, 9
	s_lshr_b32 s17, s11, 3
	s_lshl_b32 s8, s10, 2
	v_readlane_b32 s9, v247, 24
	s_add_u32 s8, s9, s8
	v_readlane_b32 s9, v247, 25
	s_addc_u32 s9, s9, 0
	v_lshlrev_b32_e32 v148, 2, v25
	v_lshl_add_u64 v[16:17], s[8:9], 0, v[148:149]
	s_lshl_b32 s8, s18, 4
	s_add_i32 s19, s15, s8
	s_add_i32 s8, s17, s19
	s_addk_i32 s8, 0xfc00
	s_ashr_i32 s9, s8, 31
	s_lshl_b64 s[8:9], s[8:9], 14
	v_readlane_b32 s17, v247, 28
	v_ashrrev_i32_e32 v29, 31, v28
	s_add_u32 s8, s17, s8
	v_readlane_b32 s20, v247, 29
	v_lshlrev_b64 v[20:21], 2, v[28:29]
	s_addc_u32 s9, s20, s9
	v_lshl_add_u64 v[18:19], s[8:9], 0, v[20:21]
	s_add_i32 s8, s19, s16
	s_addk_i32 s8, 0xfc08
	s_ashr_i32 s9, s8, 31
	s_lshl_b64 s[8:9], s[8:9], 14
	s_add_u32 s8, s17, s8
	s_addc_u32 s9, s20, s9
	v_lshl_add_u64 v[20:21], s[8:9], 0, v[20:21]
	s_mov_b64 s[8:9], 0
	v_mov_b32_e32 v26, v28
	v_lshrrev_b32_e32 v154, 6, v28
	v_lshlrev_b32_e32 v155, 2, v154
	ds_read_b32 v66, v155 offset:36864
	ds_read_b32 v67, v155 offset:36880
	ds_read_b32 v68, v155 offset:36896
	ds_read_b32 v69, v155 offset:36912
	ds_read_b32 v70, v155 offset:36928
	ds_read_b32 v71, v155 offset:36944
	ds_read_b32 v72, v155 offset:36960
	ds_read_b32 v73, v155 offset:36976
	ds_read_b32 v74, v155 offset:36992
	ds_read_b32 v75, v155 offset:37008
	ds_read_b32 v76, v155 offset:37024
	ds_read_b32 v77, v155 offset:37040
	ds_read_b32 v78, v155 offset:37056
	ds_read_b32 v79, v155 offset:37072
	ds_read_b32 v80, v155 offset:37088
	ds_read_b32 v81, v155 offset:37104
	v_mul_u32_u24_e32 v154, 0x48, v154
	v_add_lshl_u32 v154, v154, v25, 1
	s_mov_b32 s16, 0xff800000
	s_mov_b32 s17, -1
	v_lshl_add_u64 v[156:157], v[16:17], 0, s[16:17]
	s_mov_b64 s[16:17], 0x1000
	s_waitcnt lgkmcnt(0)
	v_lshlrev_b32_e32 v158, 11, v66
	v_mov_b32_e32 v159, 0
	v_lshl_add_u64 v[158:159], v[158:159], 0, v[156:157]
	v_lshlrev_b32_e32 v160, 11, v67
	v_mov_b32_e32 v161, 0
	v_lshl_add_u64 v[160:161], v[160:161], 0, v[156:157]
	v_lshlrev_b32_e32 v162, 11, v68
	v_mov_b32_e32 v163, 0
	v_lshl_add_u64 v[162:163], v[162:163], 0, v[156:157]
	v_lshlrev_b32_e32 v164, 11, v69
	v_mov_b32_e32 v165, 0
	v_lshl_add_u64 v[164:165], v[164:165], 0, v[156:157]
	v_lshlrev_b32_e32 v166, 11, v70
	v_mov_b32_e32 v167, 0
	v_lshl_add_u64 v[166:167], v[166:167], 0, v[156:157]
	v_lshlrev_b32_e32 v168, 11, v71
	v_mov_b32_e32 v169, 0
	v_lshl_add_u64 v[168:169], v[168:169], 0, v[156:157]
	v_lshlrev_b32_e32 v170, 11, v72
	v_mov_b32_e32 v171, 0
	v_lshl_add_u64 v[170:171], v[170:171], 0, v[156:157]
	v_lshlrev_b32_e32 v204, 11, v73
	v_mov_b32_e32 v205, 0
	v_lshl_add_u64 v[204:205], v[204:205], 0, v[156:157]
	v_lshlrev_b32_e32 v206, 11, v74
	v_mov_b32_e32 v207, 0
	v_lshl_add_u64 v[206:207], v[206:207], 0, v[156:157]
	v_lshlrev_b32_e32 v208, 11, v75
	v_mov_b32_e32 v209, 0
	v_lshl_add_u64 v[208:209], v[208:209], 0, v[156:157]
	v_lshlrev_b32_e32 v210, 11, v76
	v_mov_b32_e32 v211, 0
	v_lshl_add_u64 v[210:211], v[210:211], 0, v[156:157]
	v_lshlrev_b32_e32 v212, 11, v77
	v_mov_b32_e32 v213, 0
	v_lshl_add_u64 v[212:213], v[212:213], 0, v[156:157]
	v_lshlrev_b32_e32 v214, 11, v78
	v_mov_b32_e32 v215, 0
	v_lshl_add_u64 v[214:215], v[214:215], 0, v[156:157]
	v_lshlrev_b32_e32 v216, 11, v79
	v_mov_b32_e32 v217, 0
	v_lshl_add_u64 v[216:217], v[216:217], 0, v[156:157]
	v_lshlrev_b32_e32 v218, 11, v80
	v_mov_b32_e32 v219, 0
	v_lshl_add_u64 v[218:219], v[218:219], 0, v[156:157]
	v_lshlrev_b32_e32 v220, 11, v81
	v_mov_b32_e32 v221, 0
	v_lshl_add_u64 v[220:221], v[220:221], 0, v[156:157]
	s_and_b64 vcc, exec, s[4:5]
	s_cbranch_vccz .Lrwc_noA
	global_load_dword v82, v[158:159], off
	global_load_dword v83, v[160:161], off
	global_load_dword v84, v[162:163], off
	global_load_dword v85, v[164:165], off
	global_load_dword v86, v[166:167], off
	global_load_dword v87, v[168:169], off
	global_load_dword v88, v[170:171], off
	global_load_dword v89, v[204:205], off
	global_load_dword v90, v[206:207], off
	global_load_dword v91, v[208:209], off
	global_load_dword v92, v[210:211], off
	global_load_dword v93, v[212:213], off
	global_load_dword v94, v[214:215], off
	global_load_dword v95, v[216:217], off
	global_load_dword v96, v[218:219], off
	global_load_dword v97, v[220:221], off
	global_load_dword v98, v[18:19], off
	global_load_dword v99, v[18:19], off offset:1024
	global_load_dword v100, v[18:19], off offset:2048
	global_load_dword v101, v[18:19], off offset:3072
	v_lshl_add_u64 v[18:19], v[18:19], 0, s[16:17]
	global_load_dword v102, v[18:19], off
	global_load_dword v103, v[18:19], off offset:1024
	global_load_dword v104, v[18:19], off offset:2048
	global_load_dword v105, v[18:19], off offset:3072
	v_lshl_add_u64 v[18:19], v[18:19], 0, s[16:17]
	global_load_dword v106, v[18:19], off
	global_load_dword v107, v[18:19], off offset:1024
	global_load_dword v108, v[18:19], off offset:2048
	global_load_dword v109, v[18:19], off offset:3072
	v_lshl_add_u64 v[18:19], v[18:19], 0, s[16:17]
	global_load_dword v110, v[18:19], off
	global_load_dword v111, v[18:19], off offset:1024
	global_load_dword v112, v[18:19], off offset:2048
	global_load_dword v113, v[18:19], off offset:3072
.Lrwc_noA:
	s_and_b64 vcc, exec, s[0:1]
	s_cbranch_vccz .Lrwc_noC
	global_load_dword v114, v[158:159], off offset:1024
	global_load_dword v115, v[160:161], off offset:1024
	global_load_dword v116, v[162:163], off offset:1024
	global_load_dword v117, v[164:165], off offset:1024
	global_load_dword v118, v[166:167], off offset:1024
	global_load_dword v119, v[168:169], off offset:1024
	global_load_dword v120, v[170:171], off offset:1024
	global_load_dword v121, v[204:205], off offset:1024
	global_load_dword v122, v[206:207], off offset:1024
	global_load_dword v123, v[208:209], off offset:1024
	global_load_dword v124, v[210:211], off offset:1024
	global_load_dword v125, v[212:213], off offset:1024
	global_load_dword v126, v[214:215], off offset:1024
	global_load_dword v127, v[216:217], off offset:1024
	global_load_dword v128, v[218:219], off offset:1024
	global_load_dword v129, v[220:221], off offset:1024
	global_load_dword v130, v[20:21], off
	global_load_dword v131, v[20:21], off offset:1024
	global_load_dword v132, v[20:21], off offset:2048
	global_load_dword v133, v[20:21], off offset:3072
	v_lshl_add_u64 v[20:21], v[20:21], 0, s[16:17]
	global_load_dword v134, v[20:21], off
	global_load_dword v135, v[20:21], off offset:1024
	global_load_dword v136, v[20:21], off offset:2048
	global_load_dword v137, v[20:21], off offset:3072
	v_lshl_add_u64 v[20:21], v[20:21], 0, s[16:17]
	global_load_dword v138, v[20:21], off
	global_load_dword v139, v[20:21], off offset:1024
	global_load_dword v140, v[20:21], off offset:2048
	global_load_dword v141, v[20:21], off offset:3072
	v_lshl_add_u64 v[20:21], v[20:21], 0, s[16:17]
	global_load_dword v142, v[20:21], off
	global_load_dword v143, v[20:21], off offset:1024
	global_load_dword v152, v[20:21], off offset:2048
	global_load_dword v153, v[20:21], off offset:3072
.Lrwc_noC:
	s_waitcnt vmcnt(0)
	s_and_b64 vcc, exec, s[4:5]
	s_cbranch_vccz .Lrwc_noA2
	v_bfe_u32 v222, v82, 16, 1
	v_add3_u32 v82, v82, v222, s52
	ds_write_b16_d16_hi v154, v82
	v_bfe_u32 v222, v83, 16, 1
	v_add3_u32 v83, v83, v222, s52
	ds_write_b16_d16_hi v154, v83 offset:576
	v_bfe_u32 v222, v84, 16, 1
	v_add3_u32 v84, v84, v222, s52
	ds_write_b16_d16_hi v154, v84 offset:1152
	v_bfe_u32 v222, v85, 16, 1
	v_add3_u32 v85, v85, v222, s52
	ds_write_b16_d16_hi v154, v85 offset:1728
	v_bfe_u32 v222, v86, 16, 1
	v_add3_u32 v86, v86, v222, s52
	ds_write_b16_d16_hi v154, v86 offset:2304
	v_bfe_u32 v222, v87, 16, 1
	v_add3_u32 v87, v87, v222, s52
	ds_write_b16_d16_hi v154, v87 offset:2880
	v_bfe_u32 v222, v88, 16, 1
	v_add3_u32 v88, v88, v222, s52
	ds_write_b16_d16_hi v154, v88 offset:3456
	v_bfe_u32 v222, v89, 16, 1
	v_add3_u32 v89, v89, v222, s52
	ds_write_b16_d16_hi v154, v89 offset:4032
	v_bfe_u32 v222, v90, 16, 1
	v_add3_u32 v90, v90, v222, s52
	ds_write_b16_d16_hi v154, v90 offset:4608
	v_bfe_u32 v222, v91, 16, 1
	v_add3_u32 v91, v91, v222, s52
	ds_write_b16_d16_hi v154, v91 offset:5184
	v_bfe_u32 v222, v92, 16, 1
	v_add3_u32 v92, v92, v222, s52
	ds_write_b16_d16_hi v154, v92 offset:5760
	v_bfe_u32 v222, v93, 16, 1
	v_add3_u32 v93, v93, v222, s52
	ds_write_b16_d16_hi v154, v93 offset:6336
	v_bfe_u32 v222, v94, 16, 1
	v_add3_u32 v94, v94, v222, s52
	ds_write_b16_d16_hi v154, v94 offset:6912
	v_bfe_u32 v222, v95, 16, 1
	v_add3_u32 v95, v95, v222, s52
	ds_write_b16_d16_hi v154, v95 offset:7488
	v_bfe_u32 v222, v96, 16, 1
	v_add3_u32 v96, v96, v222, s52
	ds_write_b16_d16_hi v154, v96 offset:8064
	v_bfe_u32 v222, v97, 16, 1
	v_add3_u32 v97, v97, v222, s52
	ds_write_b16_d16_hi v154, v97 offset:8640
	v_bfe_u32 v222, v98, 16, 1
	v_add3_u32 v98, v98, v222, s52
	ds_write_b16_d16_hi v154, v98 offset:9216
	v_bfe_u32 v222, v99, 16, 1
	v_add3_u32 v99, v99, v222, s52
	ds_write_b16_d16_hi v154, v99 offset:9792
	v_bfe_u32 v222, v100, 16, 1
	v_add3_u32 v100, v100, v222, s52
	ds_write_b16_d16_hi v154, v100 offset:10368
	v_bfe_u32 v222, v101, 16, 1
	v_add3_u32 v101, v101, v222, s52
	ds_write_b16_d16_hi v154, v101 offset:10944
	v_bfe_u32 v222, v102, 16, 1
	v_add3_u32 v102, v102, v222, s52
	ds_write_b16_d16_hi v154, v102 offset:11520
	v_bfe_u32 v222, v103, 16, 1
	v_add3_u32 v103, v103, v222, s52
	ds_write_b16_d16_hi v154, v103 offset:12096
	v_bfe_u32 v222, v104, 16, 1
	v_add3_u32 v104, v104, v222, s52
	ds_write_b16_d16_hi v154, v104 offset:12672
	v_bfe_u32 v222, v105, 16, 1
	v_add3_u32 v105, v105, v222, s52
	ds_write_b16_d16_hi v154, v105 offset:13248
	v_bfe_u32 v222, v106, 16, 1
	v_add3_u32 v106, v106, v222, s52
	ds_write_b16_d16_hi v154, v106 offset:13824
	v_bfe_u32 v222, v107, 16, 1
	v_add3_u32 v107, v107, v222, s52
	ds_write_b16_d16_hi v154, v107 offset:14400
	v_bfe_u32 v222, v108, 16, 1
	v_add3_u32 v108, v108, v222, s52
	ds_write_b16_d16_hi v154, v108 offset:14976
	v_bfe_u32 v222, v109, 16, 1
	v_add3_u32 v109, v109, v222, s52
	ds_write_b16_d16_hi v154, v109 offset:15552
	v_bfe_u32 v222, v110, 16, 1
	v_add3_u32 v110, v110, v222, s52
	ds_write_b16_d16_hi v154, v110 offset:16128
	v_bfe_u32 v222, v111, 16, 1
	v_add3_u32 v111, v111, v222, s52
	ds_write_b16_d16_hi v154, v111 offset:16704
	v_bfe_u32 v222, v112, 16, 1
	v_add3_u32 v112, v112, v222, s52
	ds_write_b16_d16_hi v154, v112 offset:17280
	v_bfe_u32 v222, v113, 16, 1
	v_add3_u32 v113, v113, v222, s52
	ds_write_b16_d16_hi v154, v113 offset:17856
.Lrwc_noA2:
	s_and_b64 vcc, exec, s[0:1]
	s_cbranch_vccz .Lrwc_noC2
	v_bfe_u32 v222, v114, 16, 1
	v_add3_u32 v114, v114, v222, s52
	ds_write_b16_d16_hi v154, v114 offset:18432
	v_bfe_u32 v222, v115, 16, 1
	v_add3_u32 v115, v115, v222, s52
	ds_write_b16_d16_hi v154, v115 offset:19008
	v_bfe_u32 v222, v116, 16, 1
	v_add3_u32 v116, v116, v222, s52
	ds_write_b16_d16_hi v154, v116 offset:19584
	v_bfe_u32 v222, v117, 16, 1
	v_add3_u32 v117, v117, v222, s52
	ds_write_b16_d16_hi v154, v117 offset:20160
	v_bfe_u32 v222, v118, 16, 1
	v_add3_u32 v118, v118, v222, s52
	ds_write_b16_d16_hi v154, v118 offset:20736
	v_bfe_u32 v222, v119, 16, 1
	v_add3_u32 v119, v119, v222, s52
	ds_write_b16_d16_hi v154, v119 offset:21312
	v_bfe_u32 v222, v120, 16, 1
	v_add3_u32 v120, v120, v222, s52
	ds_write_b16_d16_hi v154, v120 offset:21888
	v_bfe_u32 v222, v121, 16, 1
	v_add3_u32 v121, v121, v222, s52
	ds_write_b16_d16_hi v154, v121 offset:22464
	v_bfe_u32 v222, v122, 16, 1
	v_add3_u32 v122, v122, v222, s52
	ds_write_b16_d16_hi v154, v122 offset:23040
	v_bfe_u32 v222, v123, 16, 1
	v_add3_u32 v123, v123, v222, s52
	ds_write_b16_d16_hi v154, v123 offset:23616
	v_bfe_u32 v222, v124, 16, 1
	v_add3_u32 v124, v124, v222, s52
	ds_write_b16_d16_hi v154, v124 offset:24192
	v_bfe_u32 v222, v125, 16, 1
	v_add3_u32 v125, v125, v222, s52
	ds_write_b16_d16_hi v154, v125 offset:24768
	v_bfe_u32 v222, v126, 16, 1
	v_add3_u32 v126, v126, v222, s52
	ds_write_b16_d16_hi v154, v126 offset:25344
	v_bfe_u32 v222, v127, 16, 1
	v_add3_u32 v127, v127, v222, s52
	ds_write_b16_d16_hi v154, v127 offset:25920
	v_bfe_u32 v222, v128, 16, 1
	v_add3_u32 v128, v128, v222, s52
	ds_write_b16_d16_hi v154, v128 offset:26496
	v_bfe_u32 v222, v129, 16, 1
	v_add3_u32 v129, v129, v222, s52
	ds_write_b16_d16_hi v154, v129 offset:27072
	v_bfe_u32 v222, v130, 16, 1
	v_add3_u32 v130, v130, v222, s52
	ds_write_b16_d16_hi v154, v130 offset:27648
	v_bfe_u32 v222, v131, 16, 1
	v_add3_u32 v131, v131, v222, s52
	ds_write_b16_d16_hi v154, v131 offset:28224
	v_bfe_u32 v222, v132, 16, 1
	v_add3_u32 v132, v132, v222, s52
	ds_write_b16_d16_hi v154, v132 offset:28800
	v_bfe_u32 v222, v133, 16, 1
	v_add3_u32 v133, v133, v222, s52
	ds_write_b16_d16_hi v154, v133 offset:29376
	v_bfe_u32 v222, v134, 16, 1
	v_add3_u32 v134, v134, v222, s52
	ds_write_b16_d16_hi v154, v134 offset:29952
	v_bfe_u32 v222, v135, 16, 1
	v_add3_u32 v135, v135, v222, s52
	ds_write_b16_d16_hi v154, v135 offset:30528
	v_bfe_u32 v222, v136, 16, 1
	v_add3_u32 v136, v136, v222, s52
	ds_write_b16_d16_hi v154, v136 offset:31104
	v_bfe_u32 v222, v137, 16, 1
	v_add3_u32 v137, v137, v222, s52
	ds_write_b16_d16_hi v154, v137 offset:31680
	v_bfe_u32 v222, v138, 16, 1
	v_add3_u32 v138, v138, v222, s52
	ds_write_b16_d16_hi v154, v138 offset:32256
	v_bfe_u32 v222, v139, 16, 1
	v_add3_u32 v139, v139, v222, s52
	ds_write_b16_d16_hi v154, v139 offset:32832
	v_bfe_u32 v222, v140, 16, 1
	v_add3_u32 v140, v140, v222, s52
	ds_write_b16_d16_hi v154, v140 offset:33408
	v_bfe_u32 v222, v141, 16, 1
	v_add3_u32 v141, v141, v222, s52
	ds_write_b16_d16_hi v154, v141 offset:33984
	v_bfe_u32 v222, v142, 16, 1
	v_add3_u32 v142, v142, v222, s52
	ds_write_b16_d16_hi v154, v142 offset:34560
	v_bfe_u32 v222, v143, 16, 1
	v_add3_u32 v143, v143, v222, s52
	ds_write_b16_d16_hi v154, v143 offset:35136
	v_bfe_u32 v222, v152, 16, 1
	v_add3_u32 v152, v152, v222, s52
	ds_write_b16_d16_hi v154, v152 offset:35712
	v_bfe_u32 v222, v153, 16, 1
	v_add3_u32 v153, v153, v222, s52
	ds_write_b16_d16_hi v154, v153 offset:36288
.Lrwc_noC2:
.LBB0_841:
	s_or_b64 exec, exec, s[6:7]
	v_ashrrev_i32_e32 v16, 6, v28
	v_lshl_or_b32 v18, v16, 4, v24
	v_or_b32_e32 v16, 48, v25
	s_and_b64 vcc, exec, s[4:5]
	v_mul_u32_u24_e32 v17, 0x48, v24
	v_mul_u32_u24_e32 v16, 0x48, v16
	s_waitcnt lgkmcnt(0)
	s_barrier
	s_cbranch_vccz .LBB0_843
	v_and_b32_e32 v26, 48, v28
	v_mad_u64_u32 v[34:35], s[4:5], v18, s33, v[26:27]
	ds_read_b128 v[20:23], v34
	v_lshl_add_u32 v19, v17, 1, v26
	ds_read_b128 v[30:33], v19 offset:9216
	v_lshl_add_u32 v25, v16, 1, v26
	s_waitcnt lgkmcnt(0)
	v_mfma_f32_16x16x32_bf16 v[12:15], v[20:23], v[30:33], v[12:15]
	ds_read_b128 v[30:33], v19 offset:11520
	s_waitcnt lgkmcnt(0)
	v_mfma_f32_16x16x32_bf16 v[8:11], v[20:23], v[30:33], v[8:11]
	ds_read_b128 v[30:33], v19 offset:13824
	s_waitcnt lgkmcnt(0)
	v_mfma_f32_16x16x32_bf16 v[4:7], v[20:23], v[30:33], v[4:7]
	ds_read_b128 v[30:33], v25 offset:9216
	s_waitcnt lgkmcnt(0)
	v_mfma_f32_16x16x32_bf16 v[0:3], v[20:23], v[30:33], v[0:3]
	ds_read_b128 v[20:23], v34 offset:64
	ds_read_b128 v[30:33], v19 offset:9280
	s_waitcnt lgkmcnt(0)
	v_mfma_f32_16x16x32_bf16 v[12:15], v[20:23], v[30:33], v[12:15]
	ds_read_b128 v[30:33], v19 offset:11584
	s_waitcnt lgkmcnt(0)
	v_mfma_f32_16x16x32_bf16 v[8:11], v[20:23], v[30:33], v[8:11]
	ds_read_b128 v[30:33], v19 offset:13888
	s_waitcnt lgkmcnt(0)
	v_mfma_f32_16x16x32_bf16 v[4:7], v[20:23], v[30:33], v[4:7]
	ds_read_b128 v[30:33], v25 offset:9280
	s_waitcnt lgkmcnt(0)
	v_mfma_f32_16x16x32_bf16 v[0:3], v[20:23], v[30:33], v[0:3]

.LBB0_845:
	v_and_b32_e32 v142, 0xffffffc0, v28
	v_and_b32_e32 v143, 48, v28
	v_add_u32_e32 v142, v142, v143
	ds_read_b128 v[130:133], v142 offset:36864
	v_and_b32_e32 v143, 15, v28
	v_or_b32_e32 v143, s10, v143
	v_lshlrev_b32_e32 v143, 2, v143
	s_waitcnt lgkmcnt(0)
	v_mul_u32_u24_e32 v134, 0x3a00, v130
	v_add_u32_e32 v134, v134, v143
	v_mov_b32_e32 v135, 0
	v_lshl_add_u64 v[134:135], v[134:135], 0, s[94:95]
	v_mul_u32_u24_e32 v136, 0x3a00, v131
	v_add_u32_e32 v136, v136, v143
	v_mov_b32_e32 v137, 0
	v_lshl_add_u64 v[136:137], v[136:137], 0, s[94:95]
	v_mul_u32_u24_e32 v138, 0x3a00, v132
	v_add_u32_e32 v138, v138, v143
	v_mov_b32_e32 v139, 0
	v_lshl_add_u64 v[138:139], v[138:139], 0, s[94:95]
	v_mul_u32_u24_e32 v140, 0x3a00, v133
	v_add_u32_e32 v140, v140, v143
	v_mov_b32_e32 v141, 0
	v_lshl_add_u64 v[140:141], v[140:141], 0, s[94:95]
	global_load_dword v66, v[134:135], off
	global_load_dword v67, v[134:135], off offset:64
	global_load_dword v68, v[134:135], off offset:128
	global_load_dword v69, v[134:135], off offset:192
	global_load_dword v70, v[134:135], off offset:1024
	global_load_dword v71, v[134:135], off offset:1088
	global_load_dword v72, v[134:135], off offset:1152
	global_load_dword v73, v[134:135], off offset:1216
	global_load_dword v74, v[134:135], off offset:2048
	global_load_dword v75, v[134:135], off offset:2112
	global_load_dword v76, v[134:135], off offset:2176
	global_load_dword v77, v[134:135], off offset:2240
	global_load_dword v78, v[134:135], off offset:3072
	global_load_dword v79, v[134:135], off offset:3136
	global_load_dword v80, v[134:135], off offset:3200
	global_load_dword v81, v[134:135], off offset:3264
	global_load_dword v82, v[136:137], off
	global_load_dword v83, v[136:137], off offset:64
	global_load_dword v84, v[136:137], off offset:128
	global_load_dword v85, v[136:137], off offset:192
	global_load_dword v86, v[136:137], off offset:1024
	global_load_dword v87, v[136:137], off offset:1088
	global_load_dword v88, v[136:137], off offset:1152
	global_load_dword v89, v[136:137], off offset:1216
	global_load_dword v90, v[136:137], off offset:2048
	global_load_dword v91, v[136:137], off offset:2112
	global_load_dword v92, v[136:137], off offset:2176
	global_load_dword v93, v[136:137], off offset:2240
	global_load_dword v94, v[136:137], off offset:3072
	global_load_dword v95, v[136:137], off offset:3136
	global_load_dword v96, v[136:137], off offset:3200
	global_load_dword v97, v[136:137], off offset:3264
	global_load_dword v98, v[138:139], off
	global_load_dword v99, v[138:139], off offset:64
	global_load_dword v100, v[138:139], off offset:128
	global_load_dword v101, v[138:139], off offset:192
	global_load_dword v102, v[138:139], off offset:1024
	global_load_dword v103, v[138:139], off offset:1088
	global_load_dword v104, v[138:139], off offset:1152
	global_load_dword v105, v[138:139], off offset:1216
	global_load_dword v106, v[138:139], off offset:2048
	global_load_dword v107, v[138:139], off offset:2112
	global_load_dword v108, v[138:139], off offset:2176
	global_load_dword v109, v[138:139], off offset:2240
	global_load_dword v110, v[138:139], off offset:3072
	global_load_dword v111, v[138:139], off offset:3136
	global_load_dword v112, v[138:139], off offset:3200
	global_load_dword v113, v[138:139], off offset:3264
	global_load_dword v114, v[140:141], off
	global_load_dword v115, v[140:141], off offset:64
	global_load_dword v116, v[140:141], off offset:128
	global_load_dword v117, v[140:141], off offset:192
	global_load_dword v118, v[140:141], off offset:1024
	global_load_dword v119, v[140:141], off offset:1088
	global_load_dword v120, v[140:141], off offset:1152
	global_load_dword v121, v[140:141], off offset:1216
	global_load_dword v122, v[140:141], off offset:2048
	global_load_dword v123, v[140:141], off offset:2112
	global_load_dword v124, v[140:141], off offset:2176
	global_load_dword v125, v[140:141], off offset:2240
	global_load_dword v126, v[140:141], off offset:3072
	global_load_dword v127, v[140:141], off offset:3136
	global_load_dword v128, v[140:141], off offset:3200
	global_load_dword v129, v[140:141], off offset:3264
	v_and_b32_e32 v16, 0xffffffc0, v28
	v_and_b32_e32 v17, 48, v28
	v_or_b32_e32 v148, s10, v24
	v_readlane_b32 s0, v249, 23
	v_add_u32_e32 v32, v16, v17
	v_readlane_b32 s36, v251, 13
	v_or_b32_e32 v16, s0, v148
	v_ashrrev_i32_e32 v17, 31, v16
	v_lshlrev_b64 v[16:17], 2, v[16:17]
	v_readlane_b32 s37, v251, 14
	v_readlane_b32 s1, v249, 24
	v_readlane_b32 s38, v251, 15
	v_lshl_add_u64 v[18:19], s[36:37], 0, v[16:17]
	global_load_dword v54, v[18:19], off
	v_lshl_add_u64 v[18:19], v[148:149], 0, s[0:1]
	v_readlane_b32 s39, v251, 16
	v_lshlrev_b64 v[18:19], 2, v[18:19]
	v_lshl_add_u64 v[30:31], s[36:37], 0, v[18:19]
	v_lshl_add_u64 v[16:17], s[38:39], 0, v[16:17]
	global_load_dword v53, v[30:31], off offset:64
	global_load_dword v52, v[30:31], off offset:128
	global_load_dword v51, v[30:31], off offset:192
	global_load_dword v50, v[16:17], off
	v_lshl_add_u64 v[16:17], s[38:39], 0, v[18:19]
	global_load_dword v49, v[16:17], off offset:64
	global_load_dword v48, v[16:17], off offset:128
	global_load_dword v29, v[16:17], off offset:192
	ds_read_b128 v[16:19], v32 offset:36864
	v_mov_b64_e32 v[30:31], s[94:95]
	s_movk_i32 s6, 0x3a00
	v_lshlrev_b32_e32 v32, 2, v148
	v_mov_b32_e32 v33, v149
	s_waitcnt lgkmcnt(0)
	v_mad_i64_i32 v[34:35], s[0:1], v16, s6, v[30:31]
	v_lshl_add_u64 v[34:35], v[34:35], 0, v[32:33]
	v_ashrrev_i32_e32 v47, 31, v16
	v_mov_b32_e32 v46, v16
	v_ashrrev_i32_e32 v45, 31, v17
	v_mov_b32_e32 v44, v17
	v_pk_mul_f32 v[42:43], v[12:13], v[12:13]
	v_pk_mul_f32 v[40:41], v[8:9], v[8:9]
	v_pk_mul_f32 v[38:39], v[4:5], v[4:5]
	v_pk_mul_f32 v[36:37], v[0:1], v[0:1]
	s_mov_b32 s8, 0x3c800000
	s_mov_b32 s7, 0x800000
	v_readlane_b32 s4, v247, 30
	v_lshlrev_b64 v[46:47], 11, v[46:47]
	v_readlane_b32 s5, v247, 31
	v_lshlrev_b32_e32 v148, 1, v148
	v_pk_mul_f32 v[26:27], v[14:15], v[14:15]
	v_lshl_add_u64 v[46:47], s[4:5], 0, v[46:47]
	v_lshl_add_u64 v[46:47], v[46:47], 0, v[148:149]
	v_pk_mul_f32 v[24:25], v[10:11], v[10:11]
	v_pk_mul_f32 v[22:23], v[6:7], v[6:7]
	v_pk_mul_f32 v[20:21], v[2:3], v[2:3]
	v_readlane_b32 s40, v251, 17
	v_readlane_b32 s41, v251, 18
	v_readlane_b32 s42, v251, 19
	v_readlane_b32 s43, v251, 20
	v_readlane_b32 s44, v251, 21
	v_readlane_b32 s45, v251, 22
	v_readlane_b32 s46, v251, 23
	v_readlane_b32 s47, v251, 24
	v_readlane_b32 s48, v251, 25
	v_readlane_b32 s49, v251, 26
	v_readlane_b32 s50, v251, 27
	v_readlane_b32 s51, v251, 28
	s_waitcnt vmcnt(0)
	v_mul_f32_e32 v16, v66, v70
	v_fma_f32 v16, v16, v54, 0
	v_mul_f32_e32 v55, v67, v71
	v_fmac_f32_e32 v16, v55, v53
	v_mul_f32_e32 v55, v68, v72
	v_fmac_f32_e32 v16, v55, v52
	v_mul_f32_e32 v55, v69, v73
	v_fmac_f32_e32 v16, v55, v51
	s_nop 1
	v_add_f32_dpp v16, v16, v16 row_ror:8 row_mask:0xf bank_mask:0xf bound_ctrl:1
	s_nop 1
	v_add_f32_dpp v16, v16, v16 row_ror:4 row_mask:0xf bank_mask:0xf bound_ctrl:1
	s_nop 1
	v_add_f32_dpp v16, v16, v16 row_ror:2 row_mask:0xf bank_mask:0xf bound_ctrl:1
	s_nop 1
	v_add_f32_dpp v56, v16, v16 row_ror:1 row_mask:0xf bank_mask:0xf bound_ctrl:1
	v_mul_f32_e32 v16, 0xbfb8aa3b, v78
	v_exp_f32_e32 v16, v16
	s_nop 0
	v_add_f32_e32 v16, 1.0, v16
	v_div_scale_f32 v55, s[0:1], v16, v16, 1.0
	v_rcp_f32_e32 v58, v55
	s_nop 0
	v_fma_f32 v59, -v55, v58, 1.0
	v_fmac_f32_e32 v58, v59, v58
	v_div_scale_f32 v59, vcc, 1.0, v16, 1.0
	v_mul_f32_e32 v60, v59, v58
	v_fma_f32 v61, -v55, v60, v59
	v_fmac_f32_e32 v60, v61, v58
	v_fma_f32 v55, -v55, v60, v59
	v_div_fmas_f32 v55, v55, v58, v60
	v_div_fixup_f32 v58, v55, v16, 1.0
	v_mul_f32_e32 v59, v56, v75
	v_mul_f32_e32 v16, 0xbfb8aa3b, v79
	v_exp_f32_e32 v16, v16
	s_nop 0
	v_add_f32_e32 v16, 1.0, v16
	v_div_scale_f32 v55, s[0:1], v16, v16, 1.0
	v_rcp_f32_e32 v60, v55
	s_nop 0
	v_fma_f32 v61, -v55, v60, 1.0
	v_fmac_f32_e32 v60, v61, v60
	v_div_scale_f32 v61, vcc, 1.0, v16, 1.0
	v_mul_f32_e32 v62, v61, v60
	v_fma_f32 v63, -v55, v62, v61
	v_fmac_f32_e32 v62, v63, v60
	v_fma_f32 v55, -v55, v62, v61
	v_div_fmas_f32 v55, v55, v60, v62
	v_div_fixup_f32 v60, v55, v16, 1.0
	v_mul_f32_e32 v61, v56, v76
	v_mul_f32_e32 v16, 0xbfb8aa3b, v80
	v_exp_f32_e32 v16, v16
	s_nop 0
	v_add_f32_e32 v16, 1.0, v16
	v_div_scale_f32 v55, s[0:1], v16, v16, 1.0
	v_rcp_f32_e32 v62, v55
	s_nop 0
	v_fma_f32 v63, -v55, v62, 1.0
	v_fmac_f32_e32 v62, v63, v62
	v_div_scale_f32 v63, vcc, 1.0, v16, 1.0
	v_mul_f32_e32 v64, v63, v62
	v_fma_f32 v65, -v55, v64, v63
	v_fmac_f32_e32 v64, v65, v62
	v_fma_f32 v55, -v55, v64, v63
	v_div_fmas_f32 v55, v55, v62, v64
	v_div_fixup_f32 v62, v55, v16, 1.0
	v_mul_f32_e32 v63, v56, v77
	v_mul_f32_e32 v16, 0xbfb8aa3b, v81
	v_exp_f32_e32 v16, v16
	s_nop 0
	v_add_f32_e32 v16, 1.0, v16
	v_div_scale_f32 v34, s[0:1], v16, v16, 1.0
	v_rcp_f32_e32 v35, v34
	s_nop 0
	v_fma_f32 v55, -v34, v35, 1.0
	v_fmac_f32_e32 v35, v55, v35
	v_div_scale_f32 v55, vcc, 1.0, v16, 1.0
	v_mul_f32_e32 v64, v55, v35
	v_fma_f32 v65, -v34, v64, v55
	v_fmac_f32_e32 v64, v65, v35
	v_fma_f32 v34, -v34, v64, v55
	v_div_fmas_f32 v34, v34, v35, v64
	v_div_fixup_f32 v64, v34, v16, 1.0
	v_mad_i64_i32 v[16:17], s[0:1], v17, s6, v[30:31]
	v_lshl_add_u64 v[34:35], v[16:17], 0, v[32:33]
	s_mov_b32 s0, 0x358637bd
	v_mul_f32_e32 v16, v82, v86
	v_fma_f32 v16, v54, v16, 0
	v_mul_f32_e32 v17, v83, v87
	v_fmac_f32_e32 v16, v53, v17
	v_mul_f32_e32 v17, v84, v88
	v_fmac_f32_e32 v16, v52, v17
	v_mul_f32_e32 v17, v85, v89
	v_fmac_f32_e32 v16, v51, v17
	v_mov_b32_e32 v17, v42
	v_mov_b32_e32 v42, v41
	v_add_f32_dpp v16, v16, v16 row_ror:8 row_mask:0xf bank_mask:0xf bound_ctrl:1
	v_mov_b32_e32 v41, v38
	v_mov_b32_e32 v38, v37
	v_add_f32_dpp v16, v16, v16 row_ror:4 row_mask:0xf bank_mask:0xf bound_ctrl:1
	s_nop 1
	v_add_f32_dpp v16, v16, v16 row_ror:2 row_mask:0xf bank_mask:0xf bound_ctrl:1
	s_nop 1
	v_add_f32_dpp v55, v16, v16 row_ror:1 row_mask:0xf bank_mask:0xf bound_ctrl:1
	v_mov_b32_e32 v16, v43
	v_mov_b32_e32 v43, v40
	v_pk_add_f32 v[16:17], v[16:17], v[42:43]
	v_mov_b32_e32 v40, v39
	v_pk_add_f32 v[16:17], v[40:41], v[16:17]
	v_mov_b32_e32 v39, v36
	v_pk_add_f32 v[16:17], v[38:39], v[16:17]
	s_nop 1
	v_mov_b32_dpp v37, v17 row_ror:8 row_mask:0xf bank_mask:0xf bound_ctrl:1
	v_mov_b32_dpp v36, v16 row_ror:8 row_mask:0xf bank_mask:0xf bound_ctrl:1
	v_pk_add_f32 v[16:17], v[16:17], v[36:37]
	s_nop 1
	v_mov_b32_dpp v37, v17 row_ror:4 row_mask:0xf bank_mask:0xf bound_ctrl:1
	v_mov_b32_dpp v36, v16 row_ror:4 row_mask:0xf bank_mask:0xf bound_ctrl:1
	v_pk_add_f32 v[16:17], v[16:17], v[36:37]
	s_nop 1
	v_mov_b32_dpp v37, v17 row_ror:2 row_mask:0xf bank_mask:0xf bound_ctrl:1
	v_mov_b32_dpp v36, v16 row_ror:2 row_mask:0xf bank_mask:0xf bound_ctrl:1
	v_pk_add_f32 v[16:17], v[16:17], v[36:37]
	s_nop 1
	v_mov_b32_dpp v37, v17 row_ror:1 row_mask:0xf bank_mask:0xf bound_ctrl:1
	v_mov_b32_dpp v36, v16 row_ror:1 row_mask:0xf bank_mask:0xf bound_ctrl:1
	v_pk_add_f32 v[36:37], v[16:17], v[36:37]
	v_mov_b64_e32 v[16:17], s[0:1]
	v_pk_fma_f32 v[36:37], v[36:37], s[8:9], v[16:17] op_sel_hi:[1, 0, 0]
	s_nop 0
	v_mul_f32_e32 v38, 0x4b800000, v37
	v_cmp_gt_f32_e64 s[0:1], s7, v37
	v_cmp_gt_f32_e32 vcc, s7, v36
	s_nop 0
	v_cndmask_b32_e64 v37, v37, v38, s[0:1]
	v_rsq_f32_e32 v37, v37
	s_nop 0
	v_mul_f32_e32 v38, 0x45800000, v37
	v_cndmask_b32_e64 v37, v37, v38, s[0:1]
	v_mul_f32_e32 v12, v12, v37
	v_mul_f32_e32 v12, v50, v12
	v_fmac_f32_e32 v12, v56, v74
	v_mul_f32_e32 v12, v58, v12
	v_mul_f32_e32 v8, v8, v37
	v_bfe_u32 v38, v12, 16, 1
	v_fmac_f32_e32 v59, v49, v8
	v_add3_u32 v12, v12, v38, s52
	v_mul_f32_e32 v8, v59, v60
	v_mul_f32_e32 v4, v4, v37
	global_store_short_d16_hi v[46:47], v12, off
	v_bfe_u32 v12, v8, 16, 1
	v_fmac_f32_e32 v61, v4, v48
	v_add3_u32 v8, v8, v12, s52
	v_mul_f32_e32 v4, v61, v62
	global_store_short_d16_hi v[46:47], v8, off offset:32
	v_bfe_u32 v8, v4, 16, 1
	v_add3_u32 v4, v4, v8, s52
	v_mul_f32_e32 v0, v0, v37
	v_fmac_f32_e32 v63, v0, v29
	v_mul_f32_e32 v0, v63, v64
	global_store_short_d16_hi v[46:47], v4, off offset:64
	v_bfe_u32 v4, v0, 16, 1
	v_add3_u32 v0, v0, v4, s52
	global_store_short_d16_hi v[46:47], v0, off offset:96
	v_mul_f32_e32 v0, 0x4b800000, v36
	v_cndmask_b32_e32 v0, v36, v0, vcc
	v_rsq_f32_e32 v0, v0
	v_lshlrev_b64 v[36:37], 11, v[44:45]
	v_lshl_add_u64 v[36:37], s[4:5], 0, v[36:37]
	v_mul_f32_e32 v4, 0x45800000, v0
	v_cndmask_b32_e32 v0, v0, v4, vcc
	v_mul_f32_e32 v4, v13, v0
	v_mul_f32_e32 v4, v50, v4
	v_fmac_f32_e32 v4, v90, v55
	v_mul_f32_e32 v8, 0xbfb8aa3b, v94
	v_exp_f32_e32 v8, v8
	s_nop 0
	v_add_f32_e32 v8, 1.0, v8
	v_div_scale_f32 v12, s[0:1], v8, v8, 1.0
	v_rcp_f32_e32 v13, v12
	s_nop 0
	v_fma_f32 v38, -v12, v13, 1.0
	v_fmac_f32_e32 v13, v38, v13
	v_div_scale_f32 v38, vcc, 1.0, v8, 1.0
	v_mul_f32_e32 v39, v38, v13
	v_fma_f32 v40, -v12, v39, v38
	v_fmac_f32_e32 v39, v40, v13
	v_fma_f32 v12, -v12, v39, v38
	v_div_fmas_f32 v12, v12, v13, v39
	v_div_fixup_f32 v8, v12, v8, 1.0
	v_mul_f32_e32 v4, v8, v4
	v_bfe_u32 v8, v4, 16, 1
	v_add3_u32 v4, v4, v8, s52
	v_lshl_add_u64 v[12:13], v[36:37], 0, v[148:149]
	global_store_short_d16_hi v[12:13], v4, off
	v_mul_f32_e32 v4, v9, v0
	v_mul_f32_e32 v4, v49, v4
	v_fmac_f32_e32 v4, v55, v91
	v_mul_f32_e32 v8, 0xbfb8aa3b, v95
	v_exp_f32_e32 v8, v8
	s_nop 0
	v_add_f32_e32 v8, 1.0, v8
	v_div_scale_f32 v9, s[0:1], v8, v8, 1.0
	v_rcp_f32_e32 v36, v9
	s_nop 0
	v_fma_f32 v37, -v9, v36, 1.0
	v_fmac_f32_e32 v36, v37, v36
	v_div_scale_f32 v37, vcc, 1.0, v8, 1.0
	v_mul_f32_e32 v38, v37, v36
	v_fma_f32 v39, -v9, v38, v37
	v_fmac_f32_e32 v38, v39, v36
	v_fma_f32 v9, -v9, v38, v37
	v_div_fmas_f32 v9, v9, v36, v38
	v_div_fixup_f32 v8, v9, v8, 1.0
	v_mul_f32_e32 v4, v4, v8
	v_bfe_u32 v8, v4, 16, 1
	v_add3_u32 v4, v4, v8, s52
	global_store_short_d16_hi v[12:13], v4, off offset:32
	v_mul_f32_e32 v4, v5, v0
	v_mul_f32_e32 v0, v1, v0
	v_mul_f32_e32 v5, v55, v92
	v_fmac_f32_e32 v5, v48, v4
	v_mul_f32_e32 v1, v55, v93
	v_fmac_f32_e32 v1, v29, v0
	v_mul_f32_e32 v4, 0xbfb8aa3b, v96
	v_exp_f32_e32 v4, v4
	v_mul_f32_e32 v0, 0xbfb8aa3b, v97
	v_exp_f32_e32 v0, v0
	v_add_f32_e32 v4, 1.0, v4
	v_div_scale_f32 v8, s[0:1], v4, v4, 1.0
	v_rcp_f32_e32 v9, v8
	v_add_f32_e32 v0, 1.0, v0
	v_fma_f32 v36, -v8, v9, 1.0
	v_fmac_f32_e32 v9, v36, v9
	v_div_scale_f32 v36, vcc, 1.0, v4, 1.0
	v_mul_f32_e32 v37, v36, v9
	v_fma_f32 v38, -v8, v37, v36
	v_fmac_f32_e32 v37, v38, v9
	v_fma_f32 v8, -v8, v37, v36
	v_div_fmas_f32 v8, v8, v9, v37
	v_div_fixup_f32 v4, v8, v4, 1.0
	v_mul_f32_e32 v4, v5, v4
	v_bfe_u32 v5, v4, 16, 1
	v_add3_u32 v4, v4, v5, s52
	global_store_short_d16_hi v[12:13], v4, off offset:64
	v_div_scale_f32 v4, s[0:1], v0, v0, 1.0
	v_rcp_f32_e32 v5, v4
	s_nop 0
	v_fma_f32 v8, -v4, v5, 1.0
	v_fmac_f32_e32 v5, v8, v5
	v_div_scale_f32 v8, vcc, 1.0, v0, 1.0
	v_mul_f32_e32 v9, v8, v5
	v_fma_f32 v34, -v4, v9, v8
	v_fmac_f32_e32 v9, v34, v5
	v_fma_f32 v4, -v4, v9, v8
	v_div_fmas_f32 v4, v4, v5, v9
	v_div_fixup_f32 v0, v4, v0, 1.0
	v_mul_f32_e32 v0, v1, v0
	v_bfe_u32 v1, v0, 16, 1
	v_add3_u32 v0, v0, v1, s52
	global_store_short_d16_hi v[12:13], v0, off offset:96
	v_mad_i64_i32 v[0:1], s[0:1], v18, s6, v[30:31]
	v_lshl_add_u64 v[0:1], v[0:1], 0, v[32:33]
	v_ashrrev_i32_e32 v9, 31, v18
	v_mov_b32_e32 v8, v18
	v_ashrrev_i32_e32 v5, 31, v19
	v_mov_b32_e32 v4, v19
	v_lshlrev_b64 v[8:9], 11, v[8:9]
	v_lshl_add_u64 v[8:9], s[4:5], 0, v[8:9]
	v_lshl_add_u64 v[8:9], v[8:9], 0, v[148:149]
	v_lshlrev_b64 v[4:5], 11, v[4:5]
	v_lshl_add_u64 v[4:5], s[4:5], 0, v[4:5]
	v_lshl_add_u64 v[4:5], v[4:5], 0, v[148:149]
	v_mul_f32_e32 v12, v98, v102
	v_fma_f32 v12, v54, v12, 0
	v_mul_f32_e32 v13, v99, v103
	v_fmac_f32_e32 v12, v53, v13
	v_mul_f32_e32 v13, v100, v104
	v_fmac_f32_e32 v12, v52, v13
	v_mul_f32_e32 v13, v101, v105
	v_fmac_f32_e32 v12, v51, v13
	s_nop 1
	v_add_f32_dpp v12, v12, v12 row_ror:8 row_mask:0xf bank_mask:0xf bound_ctrl:1
	s_nop 1
	v_add_f32_dpp v12, v12, v12 row_ror:4 row_mask:0xf bank_mask:0xf bound_ctrl:1
	s_nop 1
	v_add_f32_dpp v12, v12, v12 row_ror:2 row_mask:0xf bank_mask:0xf bound_ctrl:1
	s_nop 1
	v_add_f32_dpp v13, v12, v12 row_ror:1 row_mask:0xf bank_mask:0xf bound_ctrl:1
	v_mul_f32_e32 v12, 0xbfb8aa3b, v110
	v_exp_f32_e32 v12, v12
	s_nop 0
	v_add_f32_e32 v12, 1.0, v12
	v_div_scale_f32 v34, s[0:1], v12, v12, 1.0
	v_rcp_f32_e32 v35, v34
	s_nop 0
	v_fma_f32 v36, -v34, v35, 1.0
	v_fmac_f32_e32 v35, v36, v35
	v_div_scale_f32 v36, vcc, 1.0, v12, 1.0
	v_mul_f32_e32 v37, v36, v35
	v_fma_f32 v38, -v34, v37, v36
	v_fmac_f32_e32 v37, v38, v35
	v_fma_f32 v34, -v34, v37, v36
	v_div_fmas_f32 v34, v34, v35, v37
	v_div_fixup_f32 v35, v34, v12, 1.0
	v_mul_f32_e32 v12, 0xbfb8aa3b, v111
	v_exp_f32_e32 v12, v12
	s_nop 0
	v_add_f32_e32 v12, 1.0, v12
	v_div_scale_f32 v36, s[0:1], v12, v12, 1.0
	v_rcp_f32_e32 v37, v36
	s_nop 0
	v_fma_f32 v38, -v36, v37, 1.0
	v_fmac_f32_e32 v37, v38, v37
	v_div_scale_f32 v38, vcc, 1.0, v12, 1.0
	v_mul_f32_e32 v39, v38, v37
	v_fma_f32 v40, -v36, v39, v38
	v_fmac_f32_e32 v39, v40, v37
	v_fma_f32 v36, -v36, v39, v38
	v_div_fmas_f32 v36, v36, v37, v39
	v_div_fixup_f32 v36, v36, v12, 1.0
	v_mul_f32_e32 v37, v13, v108
	v_mul_f32_e32 v12, 0xbfb8aa3b, v112
	v_exp_f32_e32 v12, v12
	s_nop 0
	v_add_f32_e32 v12, 1.0, v12
	v_div_scale_f32 v38, s[0:1], v12, v12, 1.0
	v_rcp_f32_e32 v39, v38
	s_nop 0
	v_fma_f32 v40, -v38, v39, 1.0
	v_fmac_f32_e32 v39, v40, v39
	v_div_scale_f32 v40, vcc, 1.0, v12, 1.0
	v_mul_f32_e32 v41, v40, v39
	v_fma_f32 v42, -v38, v41, v40
	v_fmac_f32_e32 v41, v42, v39
	v_fma_f32 v38, -v38, v41, v40
	v_div_fmas_f32 v38, v38, v39, v41
	v_div_fixup_f32 v38, v38, v12, 1.0
	v_mul_f32_e32 v39, v13, v109
	v_mul_f32_e32 v0, 0xbfb8aa3b, v113
	v_exp_f32_e32 v0, v0
	s_nop 0
	v_add_f32_e32 v0, 1.0, v0
	v_div_scale_f32 v1, s[0:1], v0, v0, 1.0
	v_rcp_f32_e32 v12, v1
	s_nop 0
	v_fma_f32 v40, -v1, v12, 1.0
	v_fmac_f32_e32 v12, v40, v12
	v_div_scale_f32 v40, vcc, 1.0, v0, 1.0
	v_mul_f32_e32 v41, v40, v12
	v_fma_f32 v42, -v1, v41, v40
	v_fmac_f32_e32 v41, v42, v12
	v_fma_f32 v1, -v1, v41, v40
	v_div_fmas_f32 v1, v1, v12, v41
	v_div_fixup_f32 v40, v1, v0, 1.0
	v_mad_i64_i32 v[0:1], s[0:1], v19, s6, v[30:31]
	v_lshl_add_u64 v[0:1], v[0:1], 0, v[32:33]
	v_mov_b32_e32 v31, v26
	v_mov_b32_e32 v26, v25
	v_mul_f32_e32 v12, v114, v118
	v_fma_f32 v12, v54, v12, 0
	v_mul_f32_e32 v19, v115, v119
	v_fmac_f32_e32 v12, v53, v19
	v_mul_f32_e32 v19, v116, v120
	v_fmac_f32_e32 v12, v52, v19
	v_mul_f32_e32 v19, v117, v121
	v_mov_b32_e32 v30, v27
	v_mov_b32_e32 v27, v24
	v_pk_add_f32 v[24:25], v[30:31], v[26:27]
	v_mov_b32_e32 v26, v23
	v_mov_b32_e32 v27, v22
	v_pk_add_f32 v[22:23], v[26:27], v[24:25]
	v_mov_b32_e32 v24, v21
	v_mov_b32_e32 v25, v20
	v_pk_add_f32 v[20:21], v[24:25], v[22:23]
	v_fmac_f32_e32 v12, v51, v19
	s_nop 0
	v_mov_b32_dpp v23, v21 row_ror:8 row_mask:0xf bank_mask:0xf bound_ctrl:1
	v_mov_b32_dpp v22, v20 row_ror:8 row_mask:0xf bank_mask:0xf bound_ctrl:1
	v_pk_add_f32 v[20:21], v[20:21], v[22:23]
	v_add_f32_dpp v12, v12, v12 row_ror:8 row_mask:0xf bank_mask:0xf bound_ctrl:1
	s_nop 0
	v_mov_b32_dpp v23, v21 row_ror:4 row_mask:0xf bank_mask:0xf bound_ctrl:1
	v_mov_b32_dpp v22, v20 row_ror:4 row_mask:0xf bank_mask:0xf bound_ctrl:1
	v_pk_add_f32 v[20:21], v[20:21], v[22:23]
	v_add_f32_dpp v12, v12, v12 row_ror:4 row_mask:0xf bank_mask:0xf bound_ctrl:1
	s_nop 0
	v_mov_b32_dpp v23, v21 row_ror:2 row_mask:0xf bank_mask:0xf bound_ctrl:1
	v_mov_b32_dpp v22, v20 row_ror:2 row_mask:0xf bank_mask:0xf bound_ctrl:1
	v_pk_add_f32 v[20:21], v[20:21], v[22:23]
	v_add_f32_dpp v12, v12, v12 row_ror:2 row_mask:0xf bank_mask:0xf bound_ctrl:1
	s_nop 0
	v_mov_b32_dpp v23, v21 row_ror:1 row_mask:0xf bank_mask:0xf bound_ctrl:1
	v_mov_b32_dpp v22, v20 row_ror:1 row_mask:0xf bank_mask:0xf bound_ctrl:1
	v_pk_add_f32 v[20:21], v[20:21], v[22:23]
	v_add_f32_dpp v12, v12, v12 row_ror:1 row_mask:0xf bank_mask:0xf bound_ctrl:1
	v_pk_fma_f32 v[16:17], v[20:21], s[8:9], v[16:17] op_sel_hi:[1, 0, 0]
	s_nop 0
	v_mul_f32_e32 v19, 0x4b800000, v17
	v_cmp_gt_f32_e64 s[0:1], s7, v17
	v_cmp_gt_f32_e32 vcc, s7, v16
	s_nop 0
	v_cndmask_b32_e64 v17, v17, v19, s[0:1]
	v_rsq_f32_e32 v17, v17
	s_nop 0
	v_mul_f32_e32 v19, 0x45800000, v17
	v_cndmask_b32_e64 v17, v17, v19, s[0:1]
	v_mul_f32_e32 v10, v10, v17
	v_mul_f32_e32 v10, v49, v10
	v_mul_f32_e32 v14, v14, v17
	v_fmac_f32_e32 v10, v13, v107
	v_mul_f32_e32 v14, v50, v14
	v_mul_f32_e32 v10, v10, v36
	v_mul_f32_e32 v6, v6, v17
	v_fmac_f32_e32 v14, v106, v13
	v_bfe_u32 v13, v10, 16, 1
	v_fmac_f32_e32 v37, v48, v6
	v_add3_u32 v10, v10, v13, s52
	v_mul_f32_e32 v6, v37, v38
	v_mul_f32_e32 v2, v2, v17
	global_store_short_d16_hi v[8:9], v10, off offset:32
	v_bfe_u32 v10, v6, 16, 1
	v_fmac_f32_e32 v39, v29, v2
	v_mul_f32_e32 v14, v35, v14
	v_add3_u32 v6, v6, v10, s52
	v_mul_f32_e32 v2, v39, v40
	v_bfe_u32 v18, v14, 16, 1
	global_store_short_d16_hi v[8:9], v6, off offset:64
	v_bfe_u32 v6, v2, 16, 1
	v_add3_u32 v14, v14, v18, s52
	v_add3_u32 v2, v2, v6, s52
	global_store_short_d16_hi v[8:9], v14, off
	global_store_short_d16_hi v[8:9], v2, off offset:96
	v_mul_f32_e32 v2, 0x4b800000, v16
	v_cndmask_b32_e32 v2, v16, v2, vcc
	v_rsq_f32_e32 v2, v2
	s_nop 0
	v_mul_f32_e32 v6, 0x45800000, v2
	v_cndmask_b32_e32 v2, v2, v6, vcc
	v_mul_f32_e32 v6, v15, v2
	v_mul_f32_e32 v6, v50, v6
	v_fmac_f32_e32 v6, v122, v12
	v_mul_f32_e32 v8, 0xbfb8aa3b, v126
	v_exp_f32_e32 v8, v8
	s_nop 0
	v_add_f32_e32 v8, 1.0, v8
	v_div_scale_f32 v9, s[0:1], v8, v8, 1.0
	v_rcp_f32_e32 v10, v9
	s_nop 0
	v_fma_f32 v13, -v9, v10, 1.0
	v_fmac_f32_e32 v10, v13, v10
	v_div_scale_f32 v13, vcc, 1.0, v8, 1.0
	v_mul_f32_e32 v14, v13, v10
	v_fma_f32 v15, -v9, v14, v13
	v_fmac_f32_e32 v14, v15, v10
	v_fma_f32 v9, -v9, v14, v13
	v_div_fmas_f32 v9, v9, v10, v14
	v_div_fixup_f32 v8, v9, v8, 1.0
	v_mul_f32_e32 v6, v8, v6
	v_bfe_u32 v8, v6, 16, 1
	v_add3_u32 v6, v6, v8, s52
	s_nop 0
	global_store_short_d16_hi v[4:5], v6, off
	v_mul_f32_e32 v6, v11, v2
	v_mul_f32_e32 v6, v49, v6
	v_fmac_f32_e32 v6, v12, v123
	v_mul_f32_e32 v8, 0xbfb8aa3b, v127
	v_exp_f32_e32 v8, v8
	s_nop 0
	v_add_f32_e32 v8, 1.0, v8
	v_div_scale_f32 v9, s[0:1], v8, v8, 1.0
	v_rcp_f32_e32 v10, v9
	s_nop 0
	v_fma_f32 v11, -v9, v10, 1.0
	v_fmac_f32_e32 v10, v11, v10
	v_div_scale_f32 v11, vcc, 1.0, v8, 1.0
	v_mul_f32_e32 v13, v11, v10
	v_fma_f32 v14, -v9, v13, v11
	v_fmac_f32_e32 v13, v14, v10
	v_fma_f32 v9, -v9, v13, v11
	v_div_fmas_f32 v9, v9, v10, v13
	v_div_fixup_f32 v8, v9, v8, 1.0
	v_mul_f32_e32 v6, v6, v8
	v_bfe_u32 v8, v6, 16, 1
	v_add3_u32 v6, v6, v8, s52
	global_store_short_d16_hi v[4:5], v6, off offset:32
	v_mul_f32_e32 v6, v7, v2
	v_mul_f32_e32 v2, v3, v2
	v_mul_f32_e32 v7, v12, v124
	v_fmac_f32_e32 v7, v48, v6
	v_mul_f32_e32 v3, v12, v125
	v_fmac_f32_e32 v3, v29, v2
	v_mul_f32_e32 v6, 0xbfb8aa3b, v128
	v_exp_f32_e32 v6, v6
	v_mul_f32_e32 v0, 0xbfb8aa3b, v129
	v_exp_f32_e32 v0, v0
	v_add_f32_e32 v6, 1.0, v6
	v_div_scale_f32 v8, s[0:1], v6, v6, 1.0
	v_rcp_f32_e32 v9, v8
	v_add_f32_e32 v0, 1.0, v0
	v_div_scale_f32 v1, s[0:1], v0, v0, 1.0
	v_fma_f32 v10, -v8, v9, 1.0
	v_fmac_f32_e32 v9, v10, v9
	v_div_scale_f32 v10, vcc, 1.0, v6, 1.0
	v_mul_f32_e32 v11, v10, v9
	v_fma_f32 v13, -v8, v11, v10
	v_fmac_f32_e32 v11, v13, v9
	v_fma_f32 v8, -v8, v11, v10
	v_div_fmas_f32 v8, v8, v9, v11
	v_div_fixup_f32 v6, v8, v6, 1.0
	v_rcp_f32_e32 v2, v1
	v_mul_f32_e32 v6, v7, v6
	v_bfe_u32 v7, v6, 16, 1
	v_add3_u32 v6, v6, v7, s52
	global_store_short_d16_hi v[4:5], v6, off offset:64
	v_fma_f32 v6, -v1, v2, 1.0
	v_fmac_f32_e32 v2, v6, v2
	v_div_scale_f32 v6, vcc, 1.0, v0, 1.0
	v_mul_f32_e32 v7, v6, v2
	v_fma_f32 v8, -v1, v7, v6
	v_fmac_f32_e32 v7, v8, v2
	v_fma_f32 v1, -v1, v7, v6
	v_div_fmas_f32 v1, v1, v2, v7
	v_div_fixup_f32 v0, v1, v0, 1.0
	v_mul_f32_e32 v0, v3, v0
	v_bfe_u32 v1, v0, 16, 1
	s_movk_i32 s0, 0x400
	v_add3_u32 v0, v0, v1, s52
	v_cmp_gt_i32_e32 vcc, s0, v28
	global_store_short_d16_hi v[4:5], v0, off offset:96
	s_and_saveexec_b64 s[0:1], vcc
	s_cbranch_execz .LBB0_864
	s_lshr_b32 s5, s13, 6
	s_lshl_b32 s4, s12, 2
	s_add_i32 s5, s5, s14
	s_addk_i32 s15, 0xfc40
	s_and_b64 s[2:3], s[2:3], exec
	s_cselect_b32 s2, s4, s15
	s_add_i32 s5, s5, s2
	s_add_i32 s2, s2, s11
	s_lshl_b32 s2, s2, 9
	s_ashr_i32 s3, s2, 31
	s_lshl_b32 s4, s5, 9
	s_lshl_b64 s[2:3], s[2:3], 2
	v_readlane_b32 s6, v247, 12
	v_readlane_b32 s7, v247, 13
	s_add_u32 s2, s6, s2
	s_addc_u32 s3, s7, s3
	s_ashr_i32 s5, s4, 31
	s_lshl_b64 s[4:5], s[4:5], 2
	s_add_u32 s4, s6, s4
	s_addc_u32 s5, s7, s5
	v_lshlrev_b32_e32 v29, 2, v28
	s_mov_b64 s[6:7], 0
	s_branch .LBB0_848
